# D2 forward substitution rewritten: one ds_read_b32 per 16 N values + DPP row_newbcast fmac (same f32 FMA order), reads pipelined 7 blocks ahead
# speedup vs baseline: 1.0029x; 1.0029x over previous
; DI void wave_lds_fence() { __builtin_amdgcn_fence(__ATOMIC_RELEASE, "wavefront"); __builtin_amdgcn_wave_barrier(); __builtin_amdgcn_fence(__ATOMIC_ACQUIRE, "wavefront"); }
; DI void d2_chunk(const Params& P, int l, int chunk, LAS float* Nm, LAS float* gs, int lane_in) {
;     ...
;         D2_TILE(kk00, qk00, 0, 0); D2_TILE(kk10, qk10, 1, 0); D2_TILE(kk11, qk11, 1, 1);
;     ...
;         *(u32x4*)(INf + ((0 * 4 + 2) * 64 + lane) * 8) = (u32x4){0u, 0u, 0u, 0u};
;         *(u32x4*)(INf + ((0 * 4 + 3) * 64 + lane) * 8) = (u32x4){0u, 0u, 0u, 0u};
;     }
;     wave_lds_fence();
;     __builtin_amdgcn_sched_barrier(0); asm volatile("" ::: "memory");
;     {
;         float t[64];
;     ...
;         D2_TBLOCK(0); D2_TBLOCK(1); D2_TBLOCK(2); D2_TBLOCK(3);
.LBB0_481:
	s_or_b64 exec, exec, s[0:1]
	v_mul_f32_e32 v3, v31, v3
	s_lshl_b64 s[0:1], s[20:21], 20
	s_lshl_b32 s4, s22, 7
	v_mul_f32_e32 v3, v3, v20
	v_add_u32_e32 v176, 0xc00, v94
	v_mul_f32_e32 v14, v38, v14
	v_mul_f32_e32 v13, v39, v13
	v_mul_f32_e32 v12, v36, v12
	v_mul_f32_e32 v11, v37, v11
	v_mul_f32_e32 v23, v34, v10
	v_mul_f32_e32 v7, v35, v7
	v_mul_f32_e32 v2, v32, v5
	v_mul_f32_e32 v5, v33, v6
	s_or_b32 s0, s0, s4
	v_cndmask_b32_e64 v3, 0, v3, s[92:93]
	v_ashrrev_i32_e32 v177, 31, v176
	v_add_u32_e32 v172, 0xe00, v94
	v_mul_f32_e32 v22, v46, v22
	v_mul_f32_e32 v21, v44, v21
	v_mul_f32_e32 v19, v45, v19
	v_mul_f32_e32 v18, v42, v18
	v_mul_f32_e32 v17, v43, v17
	v_mul_f32_e32 v16, v40, v16
	v_mul_f32_e32 v15, v41, v15
	s_lshl_b64 s[4:5], s[0:1], 1
	v_readlane_b32 s0, v255, 11
	ds_write_b32 v4, v3 offset:236
	v_mul_f32_e32 v20, v47, v20
	v_cvt_pk_bf16_f32 v2, v2, v5
	v_cvt_pk_bf16_f32 v3, v23, v7
	v_cvt_pk_bf16_f32 v4, v12, v11
	v_cvt_pk_bf16_f32 v5, v14, v13
	v_lshl_add_u64 v[6:7], v[176:177], 1, s[36:37]
	v_ashrrev_i32_e32 v173, 31, v172
	v_add_u32_e32 v10, 0x80, v166
	s_add_u32 s48, s0, s4
	v_readlane_b32 s0, v255, 12
	global_store_dwordx4 v[6:7], v[2:5], off
	v_lshl_add_u64 v[6:7], v[172:173], 1, s[36:37]
	s_mov_b32 s40, 0
	v_cvt_pk_bf16_f32 v2, v16, v15
	v_cvt_pk_bf16_f32 v3, v18, v17
	v_cvt_pk_bf16_f32 v4, v21, v19
	v_cvt_pk_bf16_f32 v5, v22, v20
	s_addc_u32 s49, s0, s5
	s_lshl_b64 s[38:39], s[8:9], 1
	v_readlane_b32 s0, v255, 15
	global_store_dwordx4 v[6:7], v[2:5], off
	s_mov_b32 s41, s40
	s_add_u32 s44, s0, s38
	v_lshlrev_b32_e32 v2, 3, v10
	v_readlane_b32 s0, v255, 16
	v_ashrrev_i32_e32 v3, 31, v2
	s_mov_b32 s42, s40
	s_mov_b32 s43, s40
	v_mov_b64_e32 v[4:5], s[40:41]
	s_addc_u32 s45, s0, s39
	v_lshl_add_u64 v[2:3], v[2:3], 1, s[36:37]
	v_mov_b64_e32 v[6:7], s[42:43]
	global_store_dwordx4 v[2:3], v[4:7], off
	global_store_dwordx4 v[0:1], v[4:7], off offset:3072
	v_and_b32_e32 v0, 15, v166
	v_lshl_add_u32 v169, v166, 2, s12
	v_lshl_add_u32 v0, v0, 2, s12
	v_cmp_eq_u32_e32 vcc, 0, v166
	ds_read_b32 v12, v0 offset:272
	ds_read_b32 v13, v0 offset:544
	ds_read_b32 v14, v0 offset:816
	ds_read_b32 v15, v0 offset:1088
	ds_read_b32 v16, v0 offset:1360
	ds_read_b32 v17, v0 offset:1632
	ds_read_b32 v18, v0 offset:1904
	ds_read_b32 v19, v0 offset:2176
	v_cndmask_b32_e64 v100, 0, 1.0, vcc
	ds_write_b32 v169, v100
	v_cmp_eq_u32_e32 vcc, 1, v166
	s_nop 1
	v_cndmask_b32_e64 v101, 0, 1.0, vcc
	s_waitcnt lgkmcnt(8)
	v_fmac_f32_dpp v101, -v12, v100 row_newbcast:0 row_mask:0xf bank_mask:0xf
	ds_write_b32 v169, v101 offset:272
	v_cmp_eq_u32_e32 vcc, 2, v166
	s_nop 1
	v_cndmask_b32_e64 v102, 0, 1.0, vcc
	ds_read_b32 v12, v0 offset:2448
	s_waitcnt lgkmcnt(9)
	v_fmac_f32_dpp v102, -v13, v100 row_newbcast:0 row_mask:0xf bank_mask:0xf
	v_fmac_f32_dpp v102, -v13, v101 row_newbcast:1 row_mask:0xf bank_mask:0xf
	ds_write_b32 v169, v102 offset:544
	v_cmp_eq_u32_e32 vcc, 3, v166
	s_nop 1
	v_cndmask_b32_e64 v103, 0, 1.0, vcc
	ds_read_b32 v13, v0 offset:2720
	s_waitcnt lgkmcnt(10)
	v_fmac_f32_dpp v103, -v14, v100 row_newbcast:0 row_mask:0xf bank_mask:0xf
	v_fmac_f32_dpp v103, -v14, v101 row_newbcast:1 row_mask:0xf bank_mask:0xf
	v_fmac_f32_dpp v103, -v14, v102 row_newbcast:2 row_mask:0xf bank_mask:0xf
	ds_write_b32 v169, v103 offset:816
	v_cmp_eq_u32_e32 vcc, 4, v166
	s_nop 1
	v_cndmask_b32_e64 v104, 0, 1.0, vcc
	ds_read_b32 v14, v0 offset:2992
	s_waitcnt lgkmcnt(11)
	v_fmac_f32_dpp v104, -v15, v100 row_newbcast:0 row_mask:0xf bank_mask:0xf
	v_fmac_f32_dpp v104, -v15, v101 row_newbcast:1 row_mask:0xf bank_mask:0xf
	v_fmac_f32_dpp v104, -v15, v102 row_newbcast:2 row_mask:0xf bank_mask:0xf
	v_fmac_f32_dpp v104, -v15, v103 row_newbcast:3 row_mask:0xf bank_mask:0xf
	ds_write_b32 v169, v104 offset:1088
	v_cmp_eq_u32_e32 vcc, 5, v166
	s_nop 1
	v_cndmask_b32_e64 v105, 0, 1.0, vcc
	ds_read_b32 v15, v0 offset:3264
	s_waitcnt lgkmcnt(12)
	v_fmac_f32_dpp v105, -v16, v100 row_newbcast:0 row_mask:0xf bank_mask:0xf
	v_fmac_f32_dpp v105, -v16, v101 row_newbcast:1 row_mask:0xf bank_mask:0xf
	v_fmac_f32_dpp v105, -v16, v102 row_newbcast:2 row_mask:0xf bank_mask:0xf
	v_fmac_f32_dpp v105, -v16, v103 row_newbcast:3 row_mask:0xf bank_mask:0xf
	v_fmac_f32_dpp v105, -v16, v104 row_newbcast:4 row_mask:0xf bank_mask:0xf
	ds_write_b32 v169, v105 offset:1360
	v_cmp_eq_u32_e32 vcc, 6, v166
	s_nop 1
	v_cndmask_b32_e64 v106, 0, 1.0, vcc
	ds_read_b32 v16, v0 offset:3536
	s_waitcnt lgkmcnt(13)
	v_fmac_f32_dpp v106, -v17, v100 row_newbcast:0 row_mask:0xf bank_mask:0xf
	v_fmac_f32_dpp v106, -v17, v101 row_newbcast:1 row_mask:0xf bank_mask:0xf
	v_fmac_f32_dpp v106, -v17, v102 row_newbcast:2 row_mask:0xf bank_mask:0xf
	v_fmac_f32_dpp v106, -v17, v103 row_newbcast:3 row_mask:0xf bank_mask:0xf
	v_fmac_f32_dpp v106, -v17, v104 row_newbcast:4 row_mask:0xf bank_mask:0xf
	v_fmac_f32_dpp v106, -v17, v105 row_newbcast:5 row_mask:0xf bank_mask:0xf
	ds_write_b32 v169, v106 offset:1632
	v_cmp_eq_u32_e32 vcc, 7, v166
	s_nop 1
	v_cndmask_b32_e64 v107, 0, 1.0, vcc
	s_waitcnt lgkmcnt(13)
	v_fmac_f32_dpp v107, -v18, v100 row_newbcast:0 row_mask:0xf bank_mask:0xf
	v_fmac_f32_dpp v107, -v18, v101 row_newbcast:1 row_mask:0xf bank_mask:0xf
	v_fmac_f32_dpp v107, -v18, v102 row_newbcast:2 row_mask:0xf bank_mask:0xf
	v_fmac_f32_dpp v107, -v18, v103 row_newbcast:3 row_mask:0xf bank_mask:0xf
	v_fmac_f32_dpp v107, -v18, v104 row_newbcast:4 row_mask:0xf bank_mask:0xf
	v_fmac_f32_dpp v107, -v18, v105 row_newbcast:5 row_mask:0xf bank_mask:0xf
	v_fmac_f32_dpp v107, -v18, v106 row_newbcast:6 row_mask:0xf bank_mask:0xf
	ds_write_b32 v169, v107 offset:1904
	v_cmp_eq_u32_e32 vcc, 8, v166
	s_nop 1
	v_cndmask_b32_e64 v108, 0, 1.0, vcc
	s_waitcnt lgkmcnt(13)
; DI void d2_chunk(const Params& P, int l, int chunk, LAS float* Nm, LAS float* gs, int lane_in) {
;     ...
;         D2_TBLOCK(0); D2_TBLOCK(1); D2_TBLOCK(2); D2_TBLOCK(3);
	v_fmac_f32_dpp v108, -v19, v100 row_newbcast:0 row_mask:0xf bank_mask:0xf
	v_fmac_f32_dpp v108, -v19, v101 row_newbcast:1 row_mask:0xf bank_mask:0xf
	v_fmac_f32_dpp v108, -v19, v102 row_newbcast:2 row_mask:0xf bank_mask:0xf
	v_fmac_f32_dpp v108, -v19, v103 row_newbcast:3 row_mask:0xf bank_mask:0xf
	v_fmac_f32_dpp v108, -v19, v104 row_newbcast:4 row_mask:0xf bank_mask:0xf
	v_fmac_f32_dpp v108, -v19, v105 row_newbcast:5 row_mask:0xf bank_mask:0xf
	v_fmac_f32_dpp v108, -v19, v106 row_newbcast:6 row_mask:0xf bank_mask:0xf
	v_fmac_f32_dpp v108, -v19, v107 row_newbcast:7 row_mask:0xf bank_mask:0xf
	ds_write_b32 v169, v108 offset:2176
	v_cmp_eq_u32_e32 vcc, 9, v166
	s_nop 1
	v_cndmask_b32_e64 v109, 0, 1.0, vcc
	ds_read_b32 v17, v0 offset:3808
	ds_read_b32 v18, v0 offset:4080
	s_waitcnt lgkmcnt(13)
	v_fmac_f32_dpp v109, -v12, v100 row_newbcast:0 row_mask:0xf bank_mask:0xf
	v_fmac_f32_dpp v109, -v12, v101 row_newbcast:1 row_mask:0xf bank_mask:0xf
	v_fmac_f32_dpp v109, -v12, v102 row_newbcast:2 row_mask:0xf bank_mask:0xf
	v_fmac_f32_dpp v109, -v12, v103 row_newbcast:3 row_mask:0xf bank_mask:0xf
	v_fmac_f32_dpp v109, -v12, v104 row_newbcast:4 row_mask:0xf bank_mask:0xf
	v_fmac_f32_dpp v109, -v12, v105 row_newbcast:5 row_mask:0xf bank_mask:0xf
	v_fmac_f32_dpp v109, -v12, v106 row_newbcast:6 row_mask:0xf bank_mask:0xf
	v_fmac_f32_dpp v109, -v12, v107 row_newbcast:7 row_mask:0xf bank_mask:0xf
	v_fmac_f32_dpp v109, -v12, v108 row_newbcast:8 row_mask:0xf bank_mask:0xf
	ds_write_b32 v169, v109 offset:2448
	v_cmp_eq_u32_e32 vcc, 10, v166
	s_nop 1
	v_cndmask_b32_e64 v110, 0, 1.0, vcc
	ds_read_b32 v19, v0 offset:4352
	s_waitcnt lgkmcnt(13)
	v_fmac_f32_dpp v110, -v13, v100 row_newbcast:0 row_mask:0xf bank_mask:0xf
	v_fmac_f32_dpp v110, -v13, v101 row_newbcast:1 row_mask:0xf bank_mask:0xf
	v_fmac_f32_dpp v110, -v13, v102 row_newbcast:2 row_mask:0xf bank_mask:0xf
	v_fmac_f32_dpp v110, -v13, v103 row_newbcast:3 row_mask:0xf bank_mask:0xf
	v_fmac_f32_dpp v110, -v13, v104 row_newbcast:4 row_mask:0xf bank_mask:0xf
	v_fmac_f32_dpp v110, -v13, v105 row_newbcast:5 row_mask:0xf bank_mask:0xf
	v_fmac_f32_dpp v110, -v13, v106 row_newbcast:6 row_mask:0xf bank_mask:0xf
	v_fmac_f32_dpp v110, -v13, v107 row_newbcast:7 row_mask:0xf bank_mask:0xf
	v_fmac_f32_dpp v110, -v13, v108 row_newbcast:8 row_mask:0xf bank_mask:0xf
	v_fmac_f32_dpp v110, -v13, v109 row_newbcast:9 row_mask:0xf bank_mask:0xf
	ds_write_b32 v169, v110 offset:2720
	v_cmp_eq_u32_e32 vcc, 11, v166
	s_nop 1
	v_cndmask_b32_e64 v111, 0, 1.0, vcc
	ds_read_b32 v12, v0 offset:4624
	s_waitcnt lgkmcnt(13)
	v_fmac_f32_dpp v111, -v14, v100 row_newbcast:0 row_mask:0xf bank_mask:0xf
	v_fmac_f32_dpp v111, -v14, v101 row_newbcast:1 row_mask:0xf bank_mask:0xf
	v_fmac_f32_dpp v111, -v14, v102 row_newbcast:2 row_mask:0xf bank_mask:0xf
	v_fmac_f32_dpp v111, -v14, v103 row_newbcast:3 row_mask:0xf bank_mask:0xf
	v_fmac_f32_dpp v111, -v14, v104 row_newbcast:4 row_mask:0xf bank_mask:0xf
	v_fmac_f32_dpp v111, -v14, v105 row_newbcast:5 row_mask:0xf bank_mask:0xf
	v_fmac_f32_dpp v111, -v14, v106 row_newbcast:6 row_mask:0xf bank_mask:0xf
	v_fmac_f32_dpp v111, -v14, v107 row_newbcast:7 row_mask:0xf bank_mask:0xf
	v_fmac_f32_dpp v111, -v14, v108 row_newbcast:8 row_mask:0xf bank_mask:0xf
	v_fmac_f32_dpp v111, -v14, v109 row_newbcast:9 row_mask:0xf bank_mask:0xf
	v_fmac_f32_dpp v111, -v14, v110 row_newbcast:10 row_mask:0xf bank_mask:0xf
	ds_write_b32 v169, v111 offset:2992
	v_cmp_eq_u32_e32 vcc, 12, v166
	s_nop 1
	v_cndmask_b32_e64 v112, 0, 1.0, vcc
	ds_read_b32 v13, v0 offset:4688
	s_waitcnt lgkmcnt(13)
	v_fmac_f32_dpp v112, -v15, v100 row_newbcast:0 row_mask:0xf bank_mask:0xf
	v_fmac_f32_dpp v112, -v15, v101 row_newbcast:1 row_mask:0xf bank_mask:0xf
	v_fmac_f32_dpp v112, -v15, v102 row_newbcast:2 row_mask:0xf bank_mask:0xf
	v_fmac_f32_dpp v112, -v15, v103 row_newbcast:3 row_mask:0xf bank_mask:0xf
	v_fmac_f32_dpp v112, -v15, v104 row_newbcast:4 row_mask:0xf bank_mask:0xf
	v_fmac_f32_dpp v112, -v15, v105 row_newbcast:5 row_mask:0xf bank_mask:0xf
	v_fmac_f32_dpp v112, -v15, v106 row_newbcast:6 row_mask:0xf bank_mask:0xf
	v_fmac_f32_dpp v112, -v15, v107 row_newbcast:7 row_mask:0xf bank_mask:0xf
	v_fmac_f32_dpp v112, -v15, v108 row_newbcast:8 row_mask:0xf bank_mask:0xf
	v_fmac_f32_dpp v112, -v15, v109 row_newbcast:9 row_mask:0xf bank_mask:0xf
	v_fmac_f32_dpp v112, -v15, v110 row_newbcast:10 row_mask:0xf bank_mask:0xf
	v_fmac_f32_dpp v112, -v15, v111 row_newbcast:11 row_mask:0xf bank_mask:0xf
	ds_write_b32 v169, v112 offset:3264
	v_cmp_eq_u32_e32 vcc, 13, v166
	s_nop 1
	v_cndmask_b32_e64 v113, 0, 1.0, vcc
	ds_read_b32 v14, v0 offset:4896
	s_waitcnt lgkmcnt(13)
	v_fmac_f32_dpp v113, -v16, v100 row_newbcast:0 row_mask:0xf bank_mask:0xf
	v_fmac_f32_dpp v113, -v16, v101 row_newbcast:1 row_mask:0xf bank_mask:0xf
	v_fmac_f32_dpp v113, -v16, v102 row_newbcast:2 row_mask:0xf bank_mask:0xf
	v_fmac_f32_dpp v113, -v16, v103 row_newbcast:3 row_mask:0xf bank_mask:0xf
	v_fmac_f32_dpp v113, -v16, v104 row_newbcast:4 row_mask:0xf bank_mask:0xf
	v_fmac_f32_dpp v113, -v16, v105 row_newbcast:5 row_mask:0xf bank_mask:0xf
	v_fmac_f32_dpp v113, -v16, v106 row_newbcast:6 row_mask:0xf bank_mask:0xf
	v_fmac_f32_dpp v113, -v16, v107 row_newbcast:7 row_mask:0xf bank_mask:0xf
	v_fmac_f32_dpp v113, -v16, v108 row_newbcast:8 row_mask:0xf bank_mask:0xf
	v_fmac_f32_dpp v113, -v16, v109 row_newbcast:9 row_mask:0xf bank_mask:0xf
	v_fmac_f32_dpp v113, -v16, v110 row_newbcast:10 row_mask:0xf bank_mask:0xf
	v_fmac_f32_dpp v113, -v16, v111 row_newbcast:11 row_mask:0xf bank_mask:0xf
	v_fmac_f32_dpp v113, -v16, v112 row_newbcast:12 row_mask:0xf bank_mask:0xf
	ds_write_b32 v169, v113 offset:3536
	v_cmp_eq_u32_e32 vcc, 14, v166
	s_nop 1
	v_cndmask_b32_e64 v114, 0, 1.0, vcc
	ds_read_b32 v15, v0 offset:4960
	ds_read_b32 v16, v0 offset:5168
	s_waitcnt lgkmcnt(12)
; DI void d2_chunk(const Params& P, int l, int chunk, LAS float* Nm, LAS float* gs, int lane_in) {
;     ...
;         D2_TBLOCK(0); D2_TBLOCK(1); D2_TBLOCK(2); D2_TBLOCK(3);
	v_fmac_f32_dpp v114, -v17, v100 row_newbcast:0 row_mask:0xf bank_mask:0xf
	v_fmac_f32_dpp v114, -v17, v101 row_newbcast:1 row_mask:0xf bank_mask:0xf
	v_fmac_f32_dpp v114, -v17, v102 row_newbcast:2 row_mask:0xf bank_mask:0xf
	v_fmac_f32_dpp v114, -v17, v103 row_newbcast:3 row_mask:0xf bank_mask:0xf
	v_fmac_f32_dpp v114, -v17, v104 row_newbcast:4 row_mask:0xf bank_mask:0xf
	v_fmac_f32_dpp v114, -v17, v105 row_newbcast:5 row_mask:0xf bank_mask:0xf
	v_fmac_f32_dpp v114, -v17, v106 row_newbcast:6 row_mask:0xf bank_mask:0xf
	v_fmac_f32_dpp v114, -v17, v107 row_newbcast:7 row_mask:0xf bank_mask:0xf
	v_fmac_f32_dpp v114, -v17, v108 row_newbcast:8 row_mask:0xf bank_mask:0xf
	v_fmac_f32_dpp v114, -v17, v109 row_newbcast:9 row_mask:0xf bank_mask:0xf
	v_fmac_f32_dpp v114, -v17, v110 row_newbcast:10 row_mask:0xf bank_mask:0xf
	v_fmac_f32_dpp v114, -v17, v111 row_newbcast:11 row_mask:0xf bank_mask:0xf
	v_fmac_f32_dpp v114, -v17, v112 row_newbcast:12 row_mask:0xf bank_mask:0xf
	v_fmac_f32_dpp v114, -v17, v113 row_newbcast:13 row_mask:0xf bank_mask:0xf
	ds_write_b32 v169, v114 offset:3808
	v_cmp_eq_u32_e32 vcc, 15, v166
	s_nop 1
	v_cndmask_b32_e64 v115, 0, 1.0, vcc
	ds_read_b32 v17, v0 offset:5232
	s_waitcnt lgkmcnt(13)
	v_fmac_f32_dpp v115, -v18, v100 row_newbcast:0 row_mask:0xf bank_mask:0xf
	v_fmac_f32_dpp v115, -v18, v101 row_newbcast:1 row_mask:0xf bank_mask:0xf
	v_fmac_f32_dpp v115, -v18, v102 row_newbcast:2 row_mask:0xf bank_mask:0xf
	v_fmac_f32_dpp v115, -v18, v103 row_newbcast:3 row_mask:0xf bank_mask:0xf
	v_fmac_f32_dpp v115, -v18, v104 row_newbcast:4 row_mask:0xf bank_mask:0xf
	v_fmac_f32_dpp v115, -v18, v105 row_newbcast:5 row_mask:0xf bank_mask:0xf
	v_fmac_f32_dpp v115, -v18, v106 row_newbcast:6 row_mask:0xf bank_mask:0xf
	v_fmac_f32_dpp v115, -v18, v107 row_newbcast:7 row_mask:0xf bank_mask:0xf
	v_fmac_f32_dpp v115, -v18, v108 row_newbcast:8 row_mask:0xf bank_mask:0xf
	v_fmac_f32_dpp v115, -v18, v109 row_newbcast:9 row_mask:0xf bank_mask:0xf
	v_fmac_f32_dpp v115, -v18, v110 row_newbcast:10 row_mask:0xf bank_mask:0xf
	v_fmac_f32_dpp v115, -v18, v111 row_newbcast:11 row_mask:0xf bank_mask:0xf
	v_fmac_f32_dpp v115, -v18, v112 row_newbcast:12 row_mask:0xf bank_mask:0xf
	v_fmac_f32_dpp v115, -v18, v113 row_newbcast:13 row_mask:0xf bank_mask:0xf
	v_fmac_f32_dpp v115, -v18, v114 row_newbcast:14 row_mask:0xf bank_mask:0xf
	ds_write_b32 v169, v115 offset:4080
	v_cmp_eq_u32_e32 vcc, 16, v166
	s_nop 1
	v_cndmask_b32_e64 v116, 0, 1.0, vcc
	ds_read_b32 v18, v0 offset:5440
	s_waitcnt lgkmcnt(13)
	v_fmac_f32_dpp v116, -v19, v100 row_newbcast:0 row_mask:0xf bank_mask:0xf
	v_fmac_f32_dpp v116, -v19, v101 row_newbcast:1 row_mask:0xf bank_mask:0xf
	v_fmac_f32_dpp v116, -v19, v102 row_newbcast:2 row_mask:0xf bank_mask:0xf
	v_fmac_f32_dpp v116, -v19, v103 row_newbcast:3 row_mask:0xf bank_mask:0xf
	v_fmac_f32_dpp v116, -v19, v104 row_newbcast:4 row_mask:0xf bank_mask:0xf
	v_fmac_f32_dpp v116, -v19, v105 row_newbcast:5 row_mask:0xf bank_mask:0xf
	v_fmac_f32_dpp v116, -v19, v106 row_newbcast:6 row_mask:0xf bank_mask:0xf
	v_fmac_f32_dpp v116, -v19, v107 row_newbcast:7 row_mask:0xf bank_mask:0xf
	v_fmac_f32_dpp v116, -v19, v108 row_newbcast:8 row_mask:0xf bank_mask:0xf
	v_fmac_f32_dpp v116, -v19, v109 row_newbcast:9 row_mask:0xf bank_mask:0xf
	v_fmac_f32_dpp v116, -v19, v110 row_newbcast:10 row_mask:0xf bank_mask:0xf
	v_fmac_f32_dpp v116, -v19, v111 row_newbcast:11 row_mask:0xf bank_mask:0xf
	v_fmac_f32_dpp v116, -v19, v112 row_newbcast:12 row_mask:0xf bank_mask:0xf
	v_fmac_f32_dpp v116, -v19, v113 row_newbcast:13 row_mask:0xf bank_mask:0xf
	v_fmac_f32_dpp v116, -v19, v114 row_newbcast:14 row_mask:0xf bank_mask:0xf
	v_fmac_f32_dpp v116, -v19, v115 row_newbcast:15 row_mask:0xf bank_mask:0xf
	ds_write_b32 v169, v116 offset:4352
	v_cmp_eq_u32_e32 vcc, 17, v166
	s_nop 1
	v_cndmask_b32_e64 v117, 0, 1.0, vcc
	ds_read_b32 v19, v0 offset:5504
	s_waitcnt lgkmcnt(13)
	v_fmac_f32_dpp v117, -v12, v100 row_newbcast:0 row_mask:0xf bank_mask:0xf
	v_fmac_f32_dpp v117, -v12, v101 row_newbcast:1 row_mask:0xf bank_mask:0xf
	v_fmac_f32_dpp v117, -v12, v102 row_newbcast:2 row_mask:0xf bank_mask:0xf
	v_fmac_f32_dpp v117, -v12, v103 row_newbcast:3 row_mask:0xf bank_mask:0xf
	v_fmac_f32_dpp v117, -v12, v104 row_newbcast:4 row_mask:0xf bank_mask:0xf
	v_fmac_f32_dpp v117, -v12, v105 row_newbcast:5 row_mask:0xf bank_mask:0xf
	v_fmac_f32_dpp v117, -v12, v106 row_newbcast:6 row_mask:0xf bank_mask:0xf
	v_fmac_f32_dpp v117, -v12, v107 row_newbcast:7 row_mask:0xf bank_mask:0xf
	v_fmac_f32_dpp v117, -v12, v108 row_newbcast:8 row_mask:0xf bank_mask:0xf
	v_fmac_f32_dpp v117, -v12, v109 row_newbcast:9 row_mask:0xf bank_mask:0xf
	v_fmac_f32_dpp v117, -v12, v110 row_newbcast:10 row_mask:0xf bank_mask:0xf
	v_fmac_f32_dpp v117, -v12, v111 row_newbcast:11 row_mask:0xf bank_mask:0xf
	v_fmac_f32_dpp v117, -v12, v112 row_newbcast:12 row_mask:0xf bank_mask:0xf
	v_fmac_f32_dpp v117, -v12, v113 row_newbcast:13 row_mask:0xf bank_mask:0xf
	v_fmac_f32_dpp v117, -v12, v114 row_newbcast:14 row_mask:0xf bank_mask:0xf
	v_fmac_f32_dpp v117, -v12, v115 row_newbcast:15 row_mask:0xf bank_mask:0xf
	ds_read_b32 v12, v0 offset:5712
	s_waitcnt lgkmcnt(12)
	v_fmac_f32_dpp v117, -v13, v116 row_newbcast:0 row_mask:0xf bank_mask:0xf
	ds_write_b32 v169, v117 offset:4624
	v_cmp_eq_u32_e32 vcc, 18, v166
	s_nop 1
	v_cndmask_b32_e64 v118, 0, 1.0, vcc
	ds_read_b32 v13, v0 offset:5776
	s_waitcnt lgkmcnt(12)
; DI void d2_chunk(const Params& P, int l, int chunk, LAS float* Nm, LAS float* gs, int lane_in) {
;     ...
;         D2_TBLOCK(0); D2_TBLOCK(1); D2_TBLOCK(2); D2_TBLOCK(3);
	v_fmac_f32_dpp v118, -v14, v100 row_newbcast:0 row_mask:0xf bank_mask:0xf
	v_fmac_f32_dpp v118, -v14, v101 row_newbcast:1 row_mask:0xf bank_mask:0xf
	v_fmac_f32_dpp v118, -v14, v102 row_newbcast:2 row_mask:0xf bank_mask:0xf
	v_fmac_f32_dpp v118, -v14, v103 row_newbcast:3 row_mask:0xf bank_mask:0xf
	v_fmac_f32_dpp v118, -v14, v104 row_newbcast:4 row_mask:0xf bank_mask:0xf
	v_fmac_f32_dpp v118, -v14, v105 row_newbcast:5 row_mask:0xf bank_mask:0xf
	v_fmac_f32_dpp v118, -v14, v106 row_newbcast:6 row_mask:0xf bank_mask:0xf
	v_fmac_f32_dpp v118, -v14, v107 row_newbcast:7 row_mask:0xf bank_mask:0xf
	v_fmac_f32_dpp v118, -v14, v108 row_newbcast:8 row_mask:0xf bank_mask:0xf
	v_fmac_f32_dpp v118, -v14, v109 row_newbcast:9 row_mask:0xf bank_mask:0xf
	v_fmac_f32_dpp v118, -v14, v110 row_newbcast:10 row_mask:0xf bank_mask:0xf
	v_fmac_f32_dpp v118, -v14, v111 row_newbcast:11 row_mask:0xf bank_mask:0xf
	v_fmac_f32_dpp v118, -v14, v112 row_newbcast:12 row_mask:0xf bank_mask:0xf
	v_fmac_f32_dpp v118, -v14, v113 row_newbcast:13 row_mask:0xf bank_mask:0xf
	v_fmac_f32_dpp v118, -v14, v114 row_newbcast:14 row_mask:0xf bank_mask:0xf
	v_fmac_f32_dpp v118, -v14, v115 row_newbcast:15 row_mask:0xf bank_mask:0xf
	ds_read_b32 v14, v0 offset:5984
	s_waitcnt lgkmcnt(11)
	v_fmac_f32_dpp v118, -v15, v116 row_newbcast:0 row_mask:0xf bank_mask:0xf
	v_fmac_f32_dpp v118, -v15, v117 row_newbcast:1 row_mask:0xf bank_mask:0xf
	ds_write_b32 v169, v118 offset:4896
	v_cmp_eq_u32_e32 vcc, 19, v166
	s_nop 1
	v_cndmask_b32_e64 v119, 0, 1.0, vcc
	ds_read_b32 v15, v0 offset:6048
	s_waitcnt lgkmcnt(12)
	v_fmac_f32_dpp v119, -v16, v100 row_newbcast:0 row_mask:0xf bank_mask:0xf
	v_fmac_f32_dpp v119, -v16, v101 row_newbcast:1 row_mask:0xf bank_mask:0xf
	v_fmac_f32_dpp v119, -v16, v102 row_newbcast:2 row_mask:0xf bank_mask:0xf
	v_fmac_f32_dpp v119, -v16, v103 row_newbcast:3 row_mask:0xf bank_mask:0xf
	v_fmac_f32_dpp v119, -v16, v104 row_newbcast:4 row_mask:0xf bank_mask:0xf
	v_fmac_f32_dpp v119, -v16, v105 row_newbcast:5 row_mask:0xf bank_mask:0xf
	v_fmac_f32_dpp v119, -v16, v106 row_newbcast:6 row_mask:0xf bank_mask:0xf
	v_fmac_f32_dpp v119, -v16, v107 row_newbcast:7 row_mask:0xf bank_mask:0xf
	v_fmac_f32_dpp v119, -v16, v108 row_newbcast:8 row_mask:0xf bank_mask:0xf
	v_fmac_f32_dpp v119, -v16, v109 row_newbcast:9 row_mask:0xf bank_mask:0xf
	v_fmac_f32_dpp v119, -v16, v110 row_newbcast:10 row_mask:0xf bank_mask:0xf
	v_fmac_f32_dpp v119, -v16, v111 row_newbcast:11 row_mask:0xf bank_mask:0xf
	v_fmac_f32_dpp v119, -v16, v112 row_newbcast:12 row_mask:0xf bank_mask:0xf
	v_fmac_f32_dpp v119, -v16, v113 row_newbcast:13 row_mask:0xf bank_mask:0xf
	v_fmac_f32_dpp v119, -v16, v114 row_newbcast:14 row_mask:0xf bank_mask:0xf
	v_fmac_f32_dpp v119, -v16, v115 row_newbcast:15 row_mask:0xf bank_mask:0xf
	ds_read_b32 v16, v0 offset:6256
	s_waitcnt lgkmcnt(11)
	v_fmac_f32_dpp v119, -v17, v116 row_newbcast:0 row_mask:0xf bank_mask:0xf
	v_fmac_f32_dpp v119, -v17, v117 row_newbcast:1 row_mask:0xf bank_mask:0xf
	v_fmac_f32_dpp v119, -v17, v118 row_newbcast:2 row_mask:0xf bank_mask:0xf
	ds_write_b32 v169, v119 offset:5168
	v_cmp_eq_u32_e32 vcc, 20, v166
	s_nop 1
	v_cndmask_b32_e64 v120, 0, 1.0, vcc
	ds_read_b32 v17, v0 offset:6320
	s_waitcnt lgkmcnt(11)
	v_fmac_f32_dpp v120, -v18, v100 row_newbcast:0 row_mask:0xf bank_mask:0xf
	v_fmac_f32_dpp v120, -v18, v101 row_newbcast:1 row_mask:0xf bank_mask:0xf
	v_fmac_f32_dpp v120, -v18, v102 row_newbcast:2 row_mask:0xf bank_mask:0xf
	v_fmac_f32_dpp v120, -v18, v103 row_newbcast:3 row_mask:0xf bank_mask:0xf
	v_fmac_f32_dpp v120, -v18, v104 row_newbcast:4 row_mask:0xf bank_mask:0xf
	v_fmac_f32_dpp v120, -v18, v105 row_newbcast:5 row_mask:0xf bank_mask:0xf
	v_fmac_f32_dpp v120, -v18, v106 row_newbcast:6 row_mask:0xf bank_mask:0xf
	v_fmac_f32_dpp v120, -v18, v107 row_newbcast:7 row_mask:0xf bank_mask:0xf
	v_fmac_f32_dpp v120, -v18, v108 row_newbcast:8 row_mask:0xf bank_mask:0xf
	v_fmac_f32_dpp v120, -v18, v109 row_newbcast:9 row_mask:0xf bank_mask:0xf
	v_fmac_f32_dpp v120, -v18, v110 row_newbcast:10 row_mask:0xf bank_mask:0xf
	v_fmac_f32_dpp v120, -v18, v111 row_newbcast:11 row_mask:0xf bank_mask:0xf
	v_fmac_f32_dpp v120, -v18, v112 row_newbcast:12 row_mask:0xf bank_mask:0xf
	v_fmac_f32_dpp v120, -v18, v113 row_newbcast:13 row_mask:0xf bank_mask:0xf
	v_fmac_f32_dpp v120, -v18, v114 row_newbcast:14 row_mask:0xf bank_mask:0xf
	v_fmac_f32_dpp v120, -v18, v115 row_newbcast:15 row_mask:0xf bank_mask:0xf
	ds_read_b32 v18, v0 offset:6528
	s_waitcnt lgkmcnt(10)
	v_fmac_f32_dpp v120, -v19, v116 row_newbcast:0 row_mask:0xf bank_mask:0xf
	v_fmac_f32_dpp v120, -v19, v117 row_newbcast:1 row_mask:0xf bank_mask:0xf
	v_fmac_f32_dpp v120, -v19, v118 row_newbcast:2 row_mask:0xf bank_mask:0xf
	v_fmac_f32_dpp v120, -v19, v119 row_newbcast:3 row_mask:0xf bank_mask:0xf
	ds_write_b32 v169, v120 offset:5440
	v_cmp_eq_u32_e32 vcc, 21, v166
	s_nop 1
	v_cndmask_b32_e64 v121, 0, 1.0, vcc
	ds_read_b32 v19, v0 offset:6592
	s_waitcnt lgkmcnt(11)
	v_fmac_f32_dpp v121, -v12, v100 row_newbcast:0 row_mask:0xf bank_mask:0xf
	v_fmac_f32_dpp v121, -v12, v101 row_newbcast:1 row_mask:0xf bank_mask:0xf
	v_fmac_f32_dpp v121, -v12, v102 row_newbcast:2 row_mask:0xf bank_mask:0xf
	v_fmac_f32_dpp v121, -v12, v103 row_newbcast:3 row_mask:0xf bank_mask:0xf
	v_fmac_f32_dpp v121, -v12, v104 row_newbcast:4 row_mask:0xf bank_mask:0xf
	v_fmac_f32_dpp v121, -v12, v105 row_newbcast:5 row_mask:0xf bank_mask:0xf
	v_fmac_f32_dpp v121, -v12, v106 row_newbcast:6 row_mask:0xf bank_mask:0xf
	v_fmac_f32_dpp v121, -v12, v107 row_newbcast:7 row_mask:0xf bank_mask:0xf
	v_fmac_f32_dpp v121, -v12, v108 row_newbcast:8 row_mask:0xf bank_mask:0xf
	v_fmac_f32_dpp v121, -v12, v109 row_newbcast:9 row_mask:0xf bank_mask:0xf
	v_fmac_f32_dpp v121, -v12, v110 row_newbcast:10 row_mask:0xf bank_mask:0xf
	v_fmac_f32_dpp v121, -v12, v111 row_newbcast:11 row_mask:0xf bank_mask:0xf
	v_fmac_f32_dpp v121, -v12, v112 row_newbcast:12 row_mask:0xf bank_mask:0xf
	v_fmac_f32_dpp v121, -v12, v113 row_newbcast:13 row_mask:0xf bank_mask:0xf
	v_fmac_f32_dpp v121, -v12, v114 row_newbcast:14 row_mask:0xf bank_mask:0xf
	v_fmac_f32_dpp v121, -v12, v115 row_newbcast:15 row_mask:0xf bank_mask:0xf
	ds_read_b32 v12, v0 offset:6800
	s_waitcnt lgkmcnt(10)
; DI void d2_chunk(const Params& P, int l, int chunk, LAS float* Nm, LAS float* gs, int lane_in) {
;     ...
;         D2_TBLOCK(0); D2_TBLOCK(1); D2_TBLOCK(2); D2_TBLOCK(3);
	v_fmac_f32_dpp v121, -v13, v116 row_newbcast:0 row_mask:0xf bank_mask:0xf
	v_fmac_f32_dpp v121, -v13, v117 row_newbcast:1 row_mask:0xf bank_mask:0xf
	v_fmac_f32_dpp v121, -v13, v118 row_newbcast:2 row_mask:0xf bank_mask:0xf
	v_fmac_f32_dpp v121, -v13, v119 row_newbcast:3 row_mask:0xf bank_mask:0xf
	v_fmac_f32_dpp v121, -v13, v120 row_newbcast:4 row_mask:0xf bank_mask:0xf
	ds_write_b32 v169, v121 offset:5712
	v_cmp_eq_u32_e32 vcc, 22, v166
	s_nop 1
	v_cndmask_b32_e64 v122, 0, 1.0, vcc
	ds_read_b32 v13, v0 offset:6864
	s_waitcnt lgkmcnt(11)
	v_fmac_f32_dpp v122, -v14, v100 row_newbcast:0 row_mask:0xf bank_mask:0xf
	v_fmac_f32_dpp v122, -v14, v101 row_newbcast:1 row_mask:0xf bank_mask:0xf
	v_fmac_f32_dpp v122, -v14, v102 row_newbcast:2 row_mask:0xf bank_mask:0xf
	v_fmac_f32_dpp v122, -v14, v103 row_newbcast:3 row_mask:0xf bank_mask:0xf
	v_fmac_f32_dpp v122, -v14, v104 row_newbcast:4 row_mask:0xf bank_mask:0xf
	v_fmac_f32_dpp v122, -v14, v105 row_newbcast:5 row_mask:0xf bank_mask:0xf
	v_fmac_f32_dpp v122, -v14, v106 row_newbcast:6 row_mask:0xf bank_mask:0xf
	v_fmac_f32_dpp v122, -v14, v107 row_newbcast:7 row_mask:0xf bank_mask:0xf
	v_fmac_f32_dpp v122, -v14, v108 row_newbcast:8 row_mask:0xf bank_mask:0xf
	v_fmac_f32_dpp v122, -v14, v109 row_newbcast:9 row_mask:0xf bank_mask:0xf
	v_fmac_f32_dpp v122, -v14, v110 row_newbcast:10 row_mask:0xf bank_mask:0xf
	v_fmac_f32_dpp v122, -v14, v111 row_newbcast:11 row_mask:0xf bank_mask:0xf
	v_fmac_f32_dpp v122, -v14, v112 row_newbcast:12 row_mask:0xf bank_mask:0xf
	v_fmac_f32_dpp v122, -v14, v113 row_newbcast:13 row_mask:0xf bank_mask:0xf
	v_fmac_f32_dpp v122, -v14, v114 row_newbcast:14 row_mask:0xf bank_mask:0xf
	v_fmac_f32_dpp v122, -v14, v115 row_newbcast:15 row_mask:0xf bank_mask:0xf
	ds_read_b32 v14, v0 offset:7072
	s_waitcnt lgkmcnt(10)
	v_fmac_f32_dpp v122, -v15, v116 row_newbcast:0 row_mask:0xf bank_mask:0xf
	v_fmac_f32_dpp v122, -v15, v117 row_newbcast:1 row_mask:0xf bank_mask:0xf
	v_fmac_f32_dpp v122, -v15, v118 row_newbcast:2 row_mask:0xf bank_mask:0xf
	v_fmac_f32_dpp v122, -v15, v119 row_newbcast:3 row_mask:0xf bank_mask:0xf
	v_fmac_f32_dpp v122, -v15, v120 row_newbcast:4 row_mask:0xf bank_mask:0xf
	v_fmac_f32_dpp v122, -v15, v121 row_newbcast:5 row_mask:0xf bank_mask:0xf
	ds_write_b32 v169, v122 offset:5984
	v_cmp_eq_u32_e32 vcc, 23, v166
	s_nop 1
	v_cndmask_b32_e64 v123, 0, 1.0, vcc
	ds_read_b32 v15, v0 offset:7136
	s_waitcnt lgkmcnt(11)
	v_fmac_f32_dpp v123, -v16, v100 row_newbcast:0 row_mask:0xf bank_mask:0xf
	v_fmac_f32_dpp v123, -v16, v101 row_newbcast:1 row_mask:0xf bank_mask:0xf
	v_fmac_f32_dpp v123, -v16, v102 row_newbcast:2 row_mask:0xf bank_mask:0xf
	v_fmac_f32_dpp v123, -v16, v103 row_newbcast:3 row_mask:0xf bank_mask:0xf
	v_fmac_f32_dpp v123, -v16, v104 row_newbcast:4 row_mask:0xf bank_mask:0xf
	v_fmac_f32_dpp v123, -v16, v105 row_newbcast:5 row_mask:0xf bank_mask:0xf
	v_fmac_f32_dpp v123, -v16, v106 row_newbcast:6 row_mask:0xf bank_mask:0xf
	v_fmac_f32_dpp v123, -v16, v107 row_newbcast:7 row_mask:0xf bank_mask:0xf
	v_fmac_f32_dpp v123, -v16, v108 row_newbcast:8 row_mask:0xf bank_mask:0xf
	v_fmac_f32_dpp v123, -v16, v109 row_newbcast:9 row_mask:0xf bank_mask:0xf
	v_fmac_f32_dpp v123, -v16, v110 row_newbcast:10 row_mask:0xf bank_mask:0xf
	v_fmac_f32_dpp v123, -v16, v111 row_newbcast:11 row_mask:0xf bank_mask:0xf
	v_fmac_f32_dpp v123, -v16, v112 row_newbcast:12 row_mask:0xf bank_mask:0xf
	v_fmac_f32_dpp v123, -v16, v113 row_newbcast:13 row_mask:0xf bank_mask:0xf
	v_fmac_f32_dpp v123, -v16, v114 row_newbcast:14 row_mask:0xf bank_mask:0xf
	v_fmac_f32_dpp v123, -v16, v115 row_newbcast:15 row_mask:0xf bank_mask:0xf
	ds_read_b32 v16, v0 offset:7344
	s_waitcnt lgkmcnt(10)
	v_fmac_f32_dpp v123, -v17, v116 row_newbcast:0 row_mask:0xf bank_mask:0xf
	v_fmac_f32_dpp v123, -v17, v117 row_newbcast:1 row_mask:0xf bank_mask:0xf
	v_fmac_f32_dpp v123, -v17, v118 row_newbcast:2 row_mask:0xf bank_mask:0xf
	v_fmac_f32_dpp v123, -v17, v119 row_newbcast:3 row_mask:0xf bank_mask:0xf
	v_fmac_f32_dpp v123, -v17, v120 row_newbcast:4 row_mask:0xf bank_mask:0xf
	v_fmac_f32_dpp v123, -v17, v121 row_newbcast:5 row_mask:0xf bank_mask:0xf
	v_fmac_f32_dpp v123, -v17, v122 row_newbcast:6 row_mask:0xf bank_mask:0xf
	ds_write_b32 v169, v123 offset:6256
	v_cmp_eq_u32_e32 vcc, 24, v166
	s_nop 1
	v_cndmask_b32_e64 v124, 0, 1.0, vcc
	ds_read_b32 v17, v0 offset:7408
	s_waitcnt lgkmcnt(11)
	v_fmac_f32_dpp v124, -v18, v100 row_newbcast:0 row_mask:0xf bank_mask:0xf
	v_fmac_f32_dpp v124, -v18, v101 row_newbcast:1 row_mask:0xf bank_mask:0xf
	v_fmac_f32_dpp v124, -v18, v102 row_newbcast:2 row_mask:0xf bank_mask:0xf
	v_fmac_f32_dpp v124, -v18, v103 row_newbcast:3 row_mask:0xf bank_mask:0xf
	v_fmac_f32_dpp v124, -v18, v104 row_newbcast:4 row_mask:0xf bank_mask:0xf
	v_fmac_f32_dpp v124, -v18, v105 row_newbcast:5 row_mask:0xf bank_mask:0xf
	v_fmac_f32_dpp v124, -v18, v106 row_newbcast:6 row_mask:0xf bank_mask:0xf
	v_fmac_f32_dpp v124, -v18, v107 row_newbcast:7 row_mask:0xf bank_mask:0xf
	v_fmac_f32_dpp v124, -v18, v108 row_newbcast:8 row_mask:0xf bank_mask:0xf
	v_fmac_f32_dpp v124, -v18, v109 row_newbcast:9 row_mask:0xf bank_mask:0xf
	v_fmac_f32_dpp v124, -v18, v110 row_newbcast:10 row_mask:0xf bank_mask:0xf
	v_fmac_f32_dpp v124, -v18, v111 row_newbcast:11 row_mask:0xf bank_mask:0xf
	v_fmac_f32_dpp v124, -v18, v112 row_newbcast:12 row_mask:0xf bank_mask:0xf
	v_fmac_f32_dpp v124, -v18, v113 row_newbcast:13 row_mask:0xf bank_mask:0xf
	v_fmac_f32_dpp v124, -v18, v114 row_newbcast:14 row_mask:0xf bank_mask:0xf
	v_fmac_f32_dpp v124, -v18, v115 row_newbcast:15 row_mask:0xf bank_mask:0xf
	ds_read_b32 v18, v0 offset:7616
	s_waitcnt lgkmcnt(10)
; DI void d2_chunk(const Params& P, int l, int chunk, LAS float* Nm, LAS float* gs, int lane_in) {
;     ...
;         D2_TBLOCK(0); D2_TBLOCK(1); D2_TBLOCK(2); D2_TBLOCK(3);
	v_fmac_f32_dpp v124, -v19, v116 row_newbcast:0 row_mask:0xf bank_mask:0xf
	v_fmac_f32_dpp v124, -v19, v117 row_newbcast:1 row_mask:0xf bank_mask:0xf
	v_fmac_f32_dpp v124, -v19, v118 row_newbcast:2 row_mask:0xf bank_mask:0xf
	v_fmac_f32_dpp v124, -v19, v119 row_newbcast:3 row_mask:0xf bank_mask:0xf
	v_fmac_f32_dpp v124, -v19, v120 row_newbcast:4 row_mask:0xf bank_mask:0xf
	v_fmac_f32_dpp v124, -v19, v121 row_newbcast:5 row_mask:0xf bank_mask:0xf
	v_fmac_f32_dpp v124, -v19, v122 row_newbcast:6 row_mask:0xf bank_mask:0xf
	v_fmac_f32_dpp v124, -v19, v123 row_newbcast:7 row_mask:0xf bank_mask:0xf
	ds_write_b32 v169, v124 offset:6528
	v_cmp_eq_u32_e32 vcc, 25, v166
	s_nop 1
	v_cndmask_b32_e64 v125, 0, 1.0, vcc
	ds_read_b32 v19, v0 offset:7680
	s_waitcnt lgkmcnt(11)
	v_fmac_f32_dpp v125, -v12, v100 row_newbcast:0 row_mask:0xf bank_mask:0xf
	v_fmac_f32_dpp v125, -v12, v101 row_newbcast:1 row_mask:0xf bank_mask:0xf
	v_fmac_f32_dpp v125, -v12, v102 row_newbcast:2 row_mask:0xf bank_mask:0xf
	v_fmac_f32_dpp v125, -v12, v103 row_newbcast:3 row_mask:0xf bank_mask:0xf
	v_fmac_f32_dpp v125, -v12, v104 row_newbcast:4 row_mask:0xf bank_mask:0xf
	v_fmac_f32_dpp v125, -v12, v105 row_newbcast:5 row_mask:0xf bank_mask:0xf
	v_fmac_f32_dpp v125, -v12, v106 row_newbcast:6 row_mask:0xf bank_mask:0xf
	v_fmac_f32_dpp v125, -v12, v107 row_newbcast:7 row_mask:0xf bank_mask:0xf
	v_fmac_f32_dpp v125, -v12, v108 row_newbcast:8 row_mask:0xf bank_mask:0xf
	v_fmac_f32_dpp v125, -v12, v109 row_newbcast:9 row_mask:0xf bank_mask:0xf
	v_fmac_f32_dpp v125, -v12, v110 row_newbcast:10 row_mask:0xf bank_mask:0xf
	v_fmac_f32_dpp v125, -v12, v111 row_newbcast:11 row_mask:0xf bank_mask:0xf
	v_fmac_f32_dpp v125, -v12, v112 row_newbcast:12 row_mask:0xf bank_mask:0xf
	v_fmac_f32_dpp v125, -v12, v113 row_newbcast:13 row_mask:0xf bank_mask:0xf
	v_fmac_f32_dpp v125, -v12, v114 row_newbcast:14 row_mask:0xf bank_mask:0xf
	v_fmac_f32_dpp v125, -v12, v115 row_newbcast:15 row_mask:0xf bank_mask:0xf
	ds_read_b32 v12, v0 offset:7888
	s_waitcnt lgkmcnt(10)
	v_fmac_f32_dpp v125, -v13, v116 row_newbcast:0 row_mask:0xf bank_mask:0xf
	v_fmac_f32_dpp v125, -v13, v117 row_newbcast:1 row_mask:0xf bank_mask:0xf
	v_fmac_f32_dpp v125, -v13, v118 row_newbcast:2 row_mask:0xf bank_mask:0xf
	v_fmac_f32_dpp v125, -v13, v119 row_newbcast:3 row_mask:0xf bank_mask:0xf
	v_fmac_f32_dpp v125, -v13, v120 row_newbcast:4 row_mask:0xf bank_mask:0xf
	v_fmac_f32_dpp v125, -v13, v121 row_newbcast:5 row_mask:0xf bank_mask:0xf
	v_fmac_f32_dpp v125, -v13, v122 row_newbcast:6 row_mask:0xf bank_mask:0xf
	v_fmac_f32_dpp v125, -v13, v123 row_newbcast:7 row_mask:0xf bank_mask:0xf
	v_fmac_f32_dpp v125, -v13, v124 row_newbcast:8 row_mask:0xf bank_mask:0xf
	ds_write_b32 v169, v125 offset:6800
	v_cmp_eq_u32_e32 vcc, 26, v166
	s_nop 1
	v_cndmask_b32_e64 v126, 0, 1.0, vcc
	ds_read_b32 v13, v0 offset:7952
	s_waitcnt lgkmcnt(11)
	v_fmac_f32_dpp v126, -v14, v100 row_newbcast:0 row_mask:0xf bank_mask:0xf
	v_fmac_f32_dpp v126, -v14, v101 row_newbcast:1 row_mask:0xf bank_mask:0xf
	v_fmac_f32_dpp v126, -v14, v102 row_newbcast:2 row_mask:0xf bank_mask:0xf
	v_fmac_f32_dpp v126, -v14, v103 row_newbcast:3 row_mask:0xf bank_mask:0xf
	v_fmac_f32_dpp v126, -v14, v104 row_newbcast:4 row_mask:0xf bank_mask:0xf
	v_fmac_f32_dpp v126, -v14, v105 row_newbcast:5 row_mask:0xf bank_mask:0xf
	v_fmac_f32_dpp v126, -v14, v106 row_newbcast:6 row_mask:0xf bank_mask:0xf
	v_fmac_f32_dpp v126, -v14, v107 row_newbcast:7 row_mask:0xf bank_mask:0xf
	v_fmac_f32_dpp v126, -v14, v108 row_newbcast:8 row_mask:0xf bank_mask:0xf
	v_fmac_f32_dpp v126, -v14, v109 row_newbcast:9 row_mask:0xf bank_mask:0xf
	v_fmac_f32_dpp v126, -v14, v110 row_newbcast:10 row_mask:0xf bank_mask:0xf
	v_fmac_f32_dpp v126, -v14, v111 row_newbcast:11 row_mask:0xf bank_mask:0xf
	v_fmac_f32_dpp v126, -v14, v112 row_newbcast:12 row_mask:0xf bank_mask:0xf
	v_fmac_f32_dpp v126, -v14, v113 row_newbcast:13 row_mask:0xf bank_mask:0xf
	v_fmac_f32_dpp v126, -v14, v114 row_newbcast:14 row_mask:0xf bank_mask:0xf
	v_fmac_f32_dpp v126, -v14, v115 row_newbcast:15 row_mask:0xf bank_mask:0xf
	ds_read_b32 v14, v0 offset:8160
	s_waitcnt lgkmcnt(10)
	v_fmac_f32_dpp v126, -v15, v116 row_newbcast:0 row_mask:0xf bank_mask:0xf
	v_fmac_f32_dpp v126, -v15, v117 row_newbcast:1 row_mask:0xf bank_mask:0xf
	v_fmac_f32_dpp v126, -v15, v118 row_newbcast:2 row_mask:0xf bank_mask:0xf
	v_fmac_f32_dpp v126, -v15, v119 row_newbcast:3 row_mask:0xf bank_mask:0xf
	v_fmac_f32_dpp v126, -v15, v120 row_newbcast:4 row_mask:0xf bank_mask:0xf
	v_fmac_f32_dpp v126, -v15, v121 row_newbcast:5 row_mask:0xf bank_mask:0xf
	v_fmac_f32_dpp v126, -v15, v122 row_newbcast:6 row_mask:0xf bank_mask:0xf
	v_fmac_f32_dpp v126, -v15, v123 row_newbcast:7 row_mask:0xf bank_mask:0xf
	v_fmac_f32_dpp v126, -v15, v124 row_newbcast:8 row_mask:0xf bank_mask:0xf
	v_fmac_f32_dpp v126, -v15, v125 row_newbcast:9 row_mask:0xf bank_mask:0xf
	ds_write_b32 v169, v126 offset:7072
	v_cmp_eq_u32_e32 vcc, 27, v166
	s_nop 1
	v_cndmask_b32_e64 v127, 0, 1.0, vcc
	ds_read_b32 v15, v0 offset:8224
	s_waitcnt lgkmcnt(11)
; DI void d2_chunk(const Params& P, int l, int chunk, LAS float* Nm, LAS float* gs, int lane_in) {
;     ...
;         D2_TBLOCK(0); D2_TBLOCK(1); D2_TBLOCK(2); D2_TBLOCK(3);
	v_fmac_f32_dpp v127, -v16, v100 row_newbcast:0 row_mask:0xf bank_mask:0xf
	v_fmac_f32_dpp v127, -v16, v101 row_newbcast:1 row_mask:0xf bank_mask:0xf
	v_fmac_f32_dpp v127, -v16, v102 row_newbcast:2 row_mask:0xf bank_mask:0xf
	v_fmac_f32_dpp v127, -v16, v103 row_newbcast:3 row_mask:0xf bank_mask:0xf
	v_fmac_f32_dpp v127, -v16, v104 row_newbcast:4 row_mask:0xf bank_mask:0xf
	v_fmac_f32_dpp v127, -v16, v105 row_newbcast:5 row_mask:0xf bank_mask:0xf
	v_fmac_f32_dpp v127, -v16, v106 row_newbcast:6 row_mask:0xf bank_mask:0xf
	v_fmac_f32_dpp v127, -v16, v107 row_newbcast:7 row_mask:0xf bank_mask:0xf
	v_fmac_f32_dpp v127, -v16, v108 row_newbcast:8 row_mask:0xf bank_mask:0xf
	v_fmac_f32_dpp v127, -v16, v109 row_newbcast:9 row_mask:0xf bank_mask:0xf
	v_fmac_f32_dpp v127, -v16, v110 row_newbcast:10 row_mask:0xf bank_mask:0xf
	v_fmac_f32_dpp v127, -v16, v111 row_newbcast:11 row_mask:0xf bank_mask:0xf
	v_fmac_f32_dpp v127, -v16, v112 row_newbcast:12 row_mask:0xf bank_mask:0xf
	v_fmac_f32_dpp v127, -v16, v113 row_newbcast:13 row_mask:0xf bank_mask:0xf
	v_fmac_f32_dpp v127, -v16, v114 row_newbcast:14 row_mask:0xf bank_mask:0xf
	v_fmac_f32_dpp v127, -v16, v115 row_newbcast:15 row_mask:0xf bank_mask:0xf
	ds_read_b32 v16, v0 offset:8432
	s_waitcnt lgkmcnt(10)
	v_fmac_f32_dpp v127, -v17, v116 row_newbcast:0 row_mask:0xf bank_mask:0xf
	v_fmac_f32_dpp v127, -v17, v117 row_newbcast:1 row_mask:0xf bank_mask:0xf
	v_fmac_f32_dpp v127, -v17, v118 row_newbcast:2 row_mask:0xf bank_mask:0xf
	v_fmac_f32_dpp v127, -v17, v119 row_newbcast:3 row_mask:0xf bank_mask:0xf
	v_fmac_f32_dpp v127, -v17, v120 row_newbcast:4 row_mask:0xf bank_mask:0xf
	v_fmac_f32_dpp v127, -v17, v121 row_newbcast:5 row_mask:0xf bank_mask:0xf
	v_fmac_f32_dpp v127, -v17, v122 row_newbcast:6 row_mask:0xf bank_mask:0xf
	v_fmac_f32_dpp v127, -v17, v123 row_newbcast:7 row_mask:0xf bank_mask:0xf
	v_fmac_f32_dpp v127, -v17, v124 row_newbcast:8 row_mask:0xf bank_mask:0xf
	v_fmac_f32_dpp v127, -v17, v125 row_newbcast:9 row_mask:0xf bank_mask:0xf
	v_fmac_f32_dpp v127, -v17, v126 row_newbcast:10 row_mask:0xf bank_mask:0xf
	ds_write_b32 v169, v127 offset:7344
	v_cmp_eq_u32_e32 vcc, 28, v166
	s_nop 1
	v_cndmask_b32_e64 v128, 0, 1.0, vcc
	ds_read_b32 v17, v0 offset:8496
	s_waitcnt lgkmcnt(11)
	v_fmac_f32_dpp v128, -v18, v100 row_newbcast:0 row_mask:0xf bank_mask:0xf
	v_fmac_f32_dpp v128, -v18, v101 row_newbcast:1 row_mask:0xf bank_mask:0xf
	v_fmac_f32_dpp v128, -v18, v102 row_newbcast:2 row_mask:0xf bank_mask:0xf
	v_fmac_f32_dpp v128, -v18, v103 row_newbcast:3 row_mask:0xf bank_mask:0xf
	v_fmac_f32_dpp v128, -v18, v104 row_newbcast:4 row_mask:0xf bank_mask:0xf
	v_fmac_f32_dpp v128, -v18, v105 row_newbcast:5 row_mask:0xf bank_mask:0xf
	v_fmac_f32_dpp v128, -v18, v106 row_newbcast:6 row_mask:0xf bank_mask:0xf
	v_fmac_f32_dpp v128, -v18, v107 row_newbcast:7 row_mask:0xf bank_mask:0xf
	v_fmac_f32_dpp v128, -v18, v108 row_newbcast:8 row_mask:0xf bank_mask:0xf
	v_fmac_f32_dpp v128, -v18, v109 row_newbcast:9 row_mask:0xf bank_mask:0xf
	v_fmac_f32_dpp v128, -v18, v110 row_newbcast:10 row_mask:0xf bank_mask:0xf
	v_fmac_f32_dpp v128, -v18, v111 row_newbcast:11 row_mask:0xf bank_mask:0xf
	v_fmac_f32_dpp v128, -v18, v112 row_newbcast:12 row_mask:0xf bank_mask:0xf
	v_fmac_f32_dpp v128, -v18, v113 row_newbcast:13 row_mask:0xf bank_mask:0xf
	v_fmac_f32_dpp v128, -v18, v114 row_newbcast:14 row_mask:0xf bank_mask:0xf
	v_fmac_f32_dpp v128, -v18, v115 row_newbcast:15 row_mask:0xf bank_mask:0xf
	ds_read_b32 v18, v0 offset:8704
	s_waitcnt lgkmcnt(10)
	v_fmac_f32_dpp v128, -v19, v116 row_newbcast:0 row_mask:0xf bank_mask:0xf
	v_fmac_f32_dpp v128, -v19, v117 row_newbcast:1 row_mask:0xf bank_mask:0xf
	v_fmac_f32_dpp v128, -v19, v118 row_newbcast:2 row_mask:0xf bank_mask:0xf
	v_fmac_f32_dpp v128, -v19, v119 row_newbcast:3 row_mask:0xf bank_mask:0xf
	v_fmac_f32_dpp v128, -v19, v120 row_newbcast:4 row_mask:0xf bank_mask:0xf
	v_fmac_f32_dpp v128, -v19, v121 row_newbcast:5 row_mask:0xf bank_mask:0xf
	v_fmac_f32_dpp v128, -v19, v122 row_newbcast:6 row_mask:0xf bank_mask:0xf
	v_fmac_f32_dpp v128, -v19, v123 row_newbcast:7 row_mask:0xf bank_mask:0xf
	v_fmac_f32_dpp v128, -v19, v124 row_newbcast:8 row_mask:0xf bank_mask:0xf
	v_fmac_f32_dpp v128, -v19, v125 row_newbcast:9 row_mask:0xf bank_mask:0xf
	v_fmac_f32_dpp v128, -v19, v126 row_newbcast:10 row_mask:0xf bank_mask:0xf
	v_fmac_f32_dpp v128, -v19, v127 row_newbcast:11 row_mask:0xf bank_mask:0xf
	ds_write_b32 v169, v128 offset:7616
	v_cmp_eq_u32_e32 vcc, 29, v166
	s_nop 1
	v_cndmask_b32_e64 v129, 0, 1.0, vcc
	ds_read_b32 v19, v0 offset:8768
	s_waitcnt lgkmcnt(11)
	v_fmac_f32_dpp v129, -v12, v100 row_newbcast:0 row_mask:0xf bank_mask:0xf
	v_fmac_f32_dpp v129, -v12, v101 row_newbcast:1 row_mask:0xf bank_mask:0xf
	v_fmac_f32_dpp v129, -v12, v102 row_newbcast:2 row_mask:0xf bank_mask:0xf
	v_fmac_f32_dpp v129, -v12, v103 row_newbcast:3 row_mask:0xf bank_mask:0xf
	v_fmac_f32_dpp v129, -v12, v104 row_newbcast:4 row_mask:0xf bank_mask:0xf
	v_fmac_f32_dpp v129, -v12, v105 row_newbcast:5 row_mask:0xf bank_mask:0xf
	v_fmac_f32_dpp v129, -v12, v106 row_newbcast:6 row_mask:0xf bank_mask:0xf
	v_fmac_f32_dpp v129, -v12, v107 row_newbcast:7 row_mask:0xf bank_mask:0xf
	v_fmac_f32_dpp v129, -v12, v108 row_newbcast:8 row_mask:0xf bank_mask:0xf
	v_fmac_f32_dpp v129, -v12, v109 row_newbcast:9 row_mask:0xf bank_mask:0xf
	v_fmac_f32_dpp v129, -v12, v110 row_newbcast:10 row_mask:0xf bank_mask:0xf
	v_fmac_f32_dpp v129, -v12, v111 row_newbcast:11 row_mask:0xf bank_mask:0xf
	v_fmac_f32_dpp v129, -v12, v112 row_newbcast:12 row_mask:0xf bank_mask:0xf
	v_fmac_f32_dpp v129, -v12, v113 row_newbcast:13 row_mask:0xf bank_mask:0xf
	v_fmac_f32_dpp v129, -v12, v114 row_newbcast:14 row_mask:0xf bank_mask:0xf
	v_fmac_f32_dpp v129, -v12, v115 row_newbcast:15 row_mask:0xf bank_mask:0xf
	ds_read_b32 v12, v0 offset:8976
	s_waitcnt lgkmcnt(10)
; DI void d2_chunk(const Params& P, int l, int chunk, LAS float* Nm, LAS float* gs, int lane_in) {
;     ...
;         D2_TBLOCK(0); D2_TBLOCK(1); D2_TBLOCK(2); D2_TBLOCK(3);
	v_fmac_f32_dpp v129, -v13, v116 row_newbcast:0 row_mask:0xf bank_mask:0xf
	v_fmac_f32_dpp v129, -v13, v117 row_newbcast:1 row_mask:0xf bank_mask:0xf
	v_fmac_f32_dpp v129, -v13, v118 row_newbcast:2 row_mask:0xf bank_mask:0xf
	v_fmac_f32_dpp v129, -v13, v119 row_newbcast:3 row_mask:0xf bank_mask:0xf
	v_fmac_f32_dpp v129, -v13, v120 row_newbcast:4 row_mask:0xf bank_mask:0xf
	v_fmac_f32_dpp v129, -v13, v121 row_newbcast:5 row_mask:0xf bank_mask:0xf
	v_fmac_f32_dpp v129, -v13, v122 row_newbcast:6 row_mask:0xf bank_mask:0xf
	v_fmac_f32_dpp v129, -v13, v123 row_newbcast:7 row_mask:0xf bank_mask:0xf
	v_fmac_f32_dpp v129, -v13, v124 row_newbcast:8 row_mask:0xf bank_mask:0xf
	v_fmac_f32_dpp v129, -v13, v125 row_newbcast:9 row_mask:0xf bank_mask:0xf
	v_fmac_f32_dpp v129, -v13, v126 row_newbcast:10 row_mask:0xf bank_mask:0xf
	v_fmac_f32_dpp v129, -v13, v127 row_newbcast:11 row_mask:0xf bank_mask:0xf
	v_fmac_f32_dpp v129, -v13, v128 row_newbcast:12 row_mask:0xf bank_mask:0xf
	ds_write_b32 v169, v129 offset:7888
	v_cmp_eq_u32_e32 vcc, 30, v166
	s_nop 1
	v_cndmask_b32_e64 v130, 0, 1.0, vcc
	ds_read_b32 v13, v0 offset:9040
	s_waitcnt lgkmcnt(11)
	v_fmac_f32_dpp v130, -v14, v100 row_newbcast:0 row_mask:0xf bank_mask:0xf
	v_fmac_f32_dpp v130, -v14, v101 row_newbcast:1 row_mask:0xf bank_mask:0xf
	v_fmac_f32_dpp v130, -v14, v102 row_newbcast:2 row_mask:0xf bank_mask:0xf
	v_fmac_f32_dpp v130, -v14, v103 row_newbcast:3 row_mask:0xf bank_mask:0xf
	v_fmac_f32_dpp v130, -v14, v104 row_newbcast:4 row_mask:0xf bank_mask:0xf
	v_fmac_f32_dpp v130, -v14, v105 row_newbcast:5 row_mask:0xf bank_mask:0xf
	v_fmac_f32_dpp v130, -v14, v106 row_newbcast:6 row_mask:0xf bank_mask:0xf
	v_fmac_f32_dpp v130, -v14, v107 row_newbcast:7 row_mask:0xf bank_mask:0xf
	v_fmac_f32_dpp v130, -v14, v108 row_newbcast:8 row_mask:0xf bank_mask:0xf
	v_fmac_f32_dpp v130, -v14, v109 row_newbcast:9 row_mask:0xf bank_mask:0xf
	v_fmac_f32_dpp v130, -v14, v110 row_newbcast:10 row_mask:0xf bank_mask:0xf
	v_fmac_f32_dpp v130, -v14, v111 row_newbcast:11 row_mask:0xf bank_mask:0xf
	v_fmac_f32_dpp v130, -v14, v112 row_newbcast:12 row_mask:0xf bank_mask:0xf
	v_fmac_f32_dpp v130, -v14, v113 row_newbcast:13 row_mask:0xf bank_mask:0xf
	v_fmac_f32_dpp v130, -v14, v114 row_newbcast:14 row_mask:0xf bank_mask:0xf
	v_fmac_f32_dpp v130, -v14, v115 row_newbcast:15 row_mask:0xf bank_mask:0xf
	ds_read_b32 v14, v0 offset:9104
	s_waitcnt lgkmcnt(10)
	v_fmac_f32_dpp v130, -v15, v116 row_newbcast:0 row_mask:0xf bank_mask:0xf
	v_fmac_f32_dpp v130, -v15, v117 row_newbcast:1 row_mask:0xf bank_mask:0xf
	v_fmac_f32_dpp v130, -v15, v118 row_newbcast:2 row_mask:0xf bank_mask:0xf
	v_fmac_f32_dpp v130, -v15, v119 row_newbcast:3 row_mask:0xf bank_mask:0xf
	v_fmac_f32_dpp v130, -v15, v120 row_newbcast:4 row_mask:0xf bank_mask:0xf
	v_fmac_f32_dpp v130, -v15, v121 row_newbcast:5 row_mask:0xf bank_mask:0xf
	v_fmac_f32_dpp v130, -v15, v122 row_newbcast:6 row_mask:0xf bank_mask:0xf
	v_fmac_f32_dpp v130, -v15, v123 row_newbcast:7 row_mask:0xf bank_mask:0xf
	v_fmac_f32_dpp v130, -v15, v124 row_newbcast:8 row_mask:0xf bank_mask:0xf
	v_fmac_f32_dpp v130, -v15, v125 row_newbcast:9 row_mask:0xf bank_mask:0xf
	v_fmac_f32_dpp v130, -v15, v126 row_newbcast:10 row_mask:0xf bank_mask:0xf
	v_fmac_f32_dpp v130, -v15, v127 row_newbcast:11 row_mask:0xf bank_mask:0xf
	v_fmac_f32_dpp v130, -v15, v128 row_newbcast:12 row_mask:0xf bank_mask:0xf
	v_fmac_f32_dpp v130, -v15, v129 row_newbcast:13 row_mask:0xf bank_mask:0xf
	ds_write_b32 v169, v130 offset:8160
	v_cmp_eq_u32_e32 vcc, 31, v166
	s_nop 1
	v_cndmask_b32_e64 v131, 0, 1.0, vcc
	ds_read_b32 v15, v0 offset:9248
	s_waitcnt lgkmcnt(11)
	v_fmac_f32_dpp v131, -v16, v100 row_newbcast:0 row_mask:0xf bank_mask:0xf
	v_fmac_f32_dpp v131, -v16, v101 row_newbcast:1 row_mask:0xf bank_mask:0xf
	v_fmac_f32_dpp v131, -v16, v102 row_newbcast:2 row_mask:0xf bank_mask:0xf
	v_fmac_f32_dpp v131, -v16, v103 row_newbcast:3 row_mask:0xf bank_mask:0xf
	v_fmac_f32_dpp v131, -v16, v104 row_newbcast:4 row_mask:0xf bank_mask:0xf
	v_fmac_f32_dpp v131, -v16, v105 row_newbcast:5 row_mask:0xf bank_mask:0xf
	v_fmac_f32_dpp v131, -v16, v106 row_newbcast:6 row_mask:0xf bank_mask:0xf
	v_fmac_f32_dpp v131, -v16, v107 row_newbcast:7 row_mask:0xf bank_mask:0xf
	v_fmac_f32_dpp v131, -v16, v108 row_newbcast:8 row_mask:0xf bank_mask:0xf
	v_fmac_f32_dpp v131, -v16, v109 row_newbcast:9 row_mask:0xf bank_mask:0xf
	v_fmac_f32_dpp v131, -v16, v110 row_newbcast:10 row_mask:0xf bank_mask:0xf
	v_fmac_f32_dpp v131, -v16, v111 row_newbcast:11 row_mask:0xf bank_mask:0xf
	v_fmac_f32_dpp v131, -v16, v112 row_newbcast:12 row_mask:0xf bank_mask:0xf
	v_fmac_f32_dpp v131, -v16, v113 row_newbcast:13 row_mask:0xf bank_mask:0xf
	v_fmac_f32_dpp v131, -v16, v114 row_newbcast:14 row_mask:0xf bank_mask:0xf
	v_fmac_f32_dpp v131, -v16, v115 row_newbcast:15 row_mask:0xf bank_mask:0xf
	ds_read_b32 v16, v0 offset:9312
	s_waitcnt lgkmcnt(10)
	v_fmac_f32_dpp v131, -v17, v116 row_newbcast:0 row_mask:0xf bank_mask:0xf
	v_fmac_f32_dpp v131, -v17, v117 row_newbcast:1 row_mask:0xf bank_mask:0xf
	v_fmac_f32_dpp v131, -v17, v118 row_newbcast:2 row_mask:0xf bank_mask:0xf
	v_fmac_f32_dpp v131, -v17, v119 row_newbcast:3 row_mask:0xf bank_mask:0xf
	v_fmac_f32_dpp v131, -v17, v120 row_newbcast:4 row_mask:0xf bank_mask:0xf
	v_fmac_f32_dpp v131, -v17, v121 row_newbcast:5 row_mask:0xf bank_mask:0xf
	v_fmac_f32_dpp v131, -v17, v122 row_newbcast:6 row_mask:0xf bank_mask:0xf
	v_fmac_f32_dpp v131, -v17, v123 row_newbcast:7 row_mask:0xf bank_mask:0xf
	v_fmac_f32_dpp v131, -v17, v124 row_newbcast:8 row_mask:0xf bank_mask:0xf
	v_fmac_f32_dpp v131, -v17, v125 row_newbcast:9 row_mask:0xf bank_mask:0xf
	v_fmac_f32_dpp v131, -v17, v126 row_newbcast:10 row_mask:0xf bank_mask:0xf
	v_fmac_f32_dpp v131, -v17, v127 row_newbcast:11 row_mask:0xf bank_mask:0xf
	v_fmac_f32_dpp v131, -v17, v128 row_newbcast:12 row_mask:0xf bank_mask:0xf
	v_fmac_f32_dpp v131, -v17, v129 row_newbcast:13 row_mask:0xf bank_mask:0xf
	v_fmac_f32_dpp v131, -v17, v130 row_newbcast:14 row_mask:0xf bank_mask:0xf
	ds_write_b32 v169, v131 offset:8432
	v_cmp_eq_u32_e32 vcc, 32, v166
	s_nop 1
	v_cndmask_b32_e64 v132, 0, 1.0, vcc
	ds_read_b32 v17, v0 offset:9376
	s_waitcnt lgkmcnt(11)
; DI void d2_chunk(const Params& P, int l, int chunk, LAS float* Nm, LAS float* gs, int lane_in) {
;     ...
;         D2_TBLOCK(0); D2_TBLOCK(1); D2_TBLOCK(2); D2_TBLOCK(3);
	v_fmac_f32_dpp v132, -v18, v100 row_newbcast:0 row_mask:0xf bank_mask:0xf
	v_fmac_f32_dpp v132, -v18, v101 row_newbcast:1 row_mask:0xf bank_mask:0xf
	v_fmac_f32_dpp v132, -v18, v102 row_newbcast:2 row_mask:0xf bank_mask:0xf
	v_fmac_f32_dpp v132, -v18, v103 row_newbcast:3 row_mask:0xf bank_mask:0xf
	v_fmac_f32_dpp v132, -v18, v104 row_newbcast:4 row_mask:0xf bank_mask:0xf
	v_fmac_f32_dpp v132, -v18, v105 row_newbcast:5 row_mask:0xf bank_mask:0xf
	v_fmac_f32_dpp v132, -v18, v106 row_newbcast:6 row_mask:0xf bank_mask:0xf
	v_fmac_f32_dpp v132, -v18, v107 row_newbcast:7 row_mask:0xf bank_mask:0xf
	v_fmac_f32_dpp v132, -v18, v108 row_newbcast:8 row_mask:0xf bank_mask:0xf
	v_fmac_f32_dpp v132, -v18, v109 row_newbcast:9 row_mask:0xf bank_mask:0xf
	v_fmac_f32_dpp v132, -v18, v110 row_newbcast:10 row_mask:0xf bank_mask:0xf
	v_fmac_f32_dpp v132, -v18, v111 row_newbcast:11 row_mask:0xf bank_mask:0xf
	v_fmac_f32_dpp v132, -v18, v112 row_newbcast:12 row_mask:0xf bank_mask:0xf
	v_fmac_f32_dpp v132, -v18, v113 row_newbcast:13 row_mask:0xf bank_mask:0xf
	v_fmac_f32_dpp v132, -v18, v114 row_newbcast:14 row_mask:0xf bank_mask:0xf
	v_fmac_f32_dpp v132, -v18, v115 row_newbcast:15 row_mask:0xf bank_mask:0xf
	ds_read_b32 v18, v0 offset:9520
	s_waitcnt lgkmcnt(10)
	v_fmac_f32_dpp v132, -v19, v116 row_newbcast:0 row_mask:0xf bank_mask:0xf
	v_fmac_f32_dpp v132, -v19, v117 row_newbcast:1 row_mask:0xf bank_mask:0xf
	v_fmac_f32_dpp v132, -v19, v118 row_newbcast:2 row_mask:0xf bank_mask:0xf
	v_fmac_f32_dpp v132, -v19, v119 row_newbcast:3 row_mask:0xf bank_mask:0xf
	v_fmac_f32_dpp v132, -v19, v120 row_newbcast:4 row_mask:0xf bank_mask:0xf
	v_fmac_f32_dpp v132, -v19, v121 row_newbcast:5 row_mask:0xf bank_mask:0xf
	v_fmac_f32_dpp v132, -v19, v122 row_newbcast:6 row_mask:0xf bank_mask:0xf
	v_fmac_f32_dpp v132, -v19, v123 row_newbcast:7 row_mask:0xf bank_mask:0xf
	v_fmac_f32_dpp v132, -v19, v124 row_newbcast:8 row_mask:0xf bank_mask:0xf
	v_fmac_f32_dpp v132, -v19, v125 row_newbcast:9 row_mask:0xf bank_mask:0xf
	v_fmac_f32_dpp v132, -v19, v126 row_newbcast:10 row_mask:0xf bank_mask:0xf
	v_fmac_f32_dpp v132, -v19, v127 row_newbcast:11 row_mask:0xf bank_mask:0xf
	v_fmac_f32_dpp v132, -v19, v128 row_newbcast:12 row_mask:0xf bank_mask:0xf
	v_fmac_f32_dpp v132, -v19, v129 row_newbcast:13 row_mask:0xf bank_mask:0xf
	v_fmac_f32_dpp v132, -v19, v130 row_newbcast:14 row_mask:0xf bank_mask:0xf
	v_fmac_f32_dpp v132, -v19, v131 row_newbcast:15 row_mask:0xf bank_mask:0xf
	ds_write_b32 v169, v132 offset:8704
	v_cmp_eq_u32_e32 vcc, 33, v166
	s_nop 1
	v_cndmask_b32_e64 v133, 0, 1.0, vcc
	ds_read_b32 v19, v0 offset:9584
	s_waitcnt lgkmcnt(11)
	v_fmac_f32_dpp v133, -v12, v100 row_newbcast:0 row_mask:0xf bank_mask:0xf
	v_fmac_f32_dpp v133, -v12, v101 row_newbcast:1 row_mask:0xf bank_mask:0xf
	v_fmac_f32_dpp v133, -v12, v102 row_newbcast:2 row_mask:0xf bank_mask:0xf
	v_fmac_f32_dpp v133, -v12, v103 row_newbcast:3 row_mask:0xf bank_mask:0xf
	v_fmac_f32_dpp v133, -v12, v104 row_newbcast:4 row_mask:0xf bank_mask:0xf
	v_fmac_f32_dpp v133, -v12, v105 row_newbcast:5 row_mask:0xf bank_mask:0xf
	v_fmac_f32_dpp v133, -v12, v106 row_newbcast:6 row_mask:0xf bank_mask:0xf
	v_fmac_f32_dpp v133, -v12, v107 row_newbcast:7 row_mask:0xf bank_mask:0xf
	v_fmac_f32_dpp v133, -v12, v108 row_newbcast:8 row_mask:0xf bank_mask:0xf
	v_fmac_f32_dpp v133, -v12, v109 row_newbcast:9 row_mask:0xf bank_mask:0xf
	v_fmac_f32_dpp v133, -v12, v110 row_newbcast:10 row_mask:0xf bank_mask:0xf
	v_fmac_f32_dpp v133, -v12, v111 row_newbcast:11 row_mask:0xf bank_mask:0xf
	v_fmac_f32_dpp v133, -v12, v112 row_newbcast:12 row_mask:0xf bank_mask:0xf
	v_fmac_f32_dpp v133, -v12, v113 row_newbcast:13 row_mask:0xf bank_mask:0xf
	v_fmac_f32_dpp v133, -v12, v114 row_newbcast:14 row_mask:0xf bank_mask:0xf
	v_fmac_f32_dpp v133, -v12, v115 row_newbcast:15 row_mask:0xf bank_mask:0xf
	ds_read_b32 v12, v0 offset:9648
	s_waitcnt lgkmcnt(10)
	v_fmac_f32_dpp v133, -v13, v116 row_newbcast:0 row_mask:0xf bank_mask:0xf
	v_fmac_f32_dpp v133, -v13, v117 row_newbcast:1 row_mask:0xf bank_mask:0xf
	v_fmac_f32_dpp v133, -v13, v118 row_newbcast:2 row_mask:0xf bank_mask:0xf
	v_fmac_f32_dpp v133, -v13, v119 row_newbcast:3 row_mask:0xf bank_mask:0xf
	v_fmac_f32_dpp v133, -v13, v120 row_newbcast:4 row_mask:0xf bank_mask:0xf
	v_fmac_f32_dpp v133, -v13, v121 row_newbcast:5 row_mask:0xf bank_mask:0xf
	v_fmac_f32_dpp v133, -v13, v122 row_newbcast:6 row_mask:0xf bank_mask:0xf
	v_fmac_f32_dpp v133, -v13, v123 row_newbcast:7 row_mask:0xf bank_mask:0xf
	v_fmac_f32_dpp v133, -v13, v124 row_newbcast:8 row_mask:0xf bank_mask:0xf
	v_fmac_f32_dpp v133, -v13, v125 row_newbcast:9 row_mask:0xf bank_mask:0xf
	v_fmac_f32_dpp v133, -v13, v126 row_newbcast:10 row_mask:0xf bank_mask:0xf
	v_fmac_f32_dpp v133, -v13, v127 row_newbcast:11 row_mask:0xf bank_mask:0xf
	v_fmac_f32_dpp v133, -v13, v128 row_newbcast:12 row_mask:0xf bank_mask:0xf
	v_fmac_f32_dpp v133, -v13, v129 row_newbcast:13 row_mask:0xf bank_mask:0xf
	v_fmac_f32_dpp v133, -v13, v130 row_newbcast:14 row_mask:0xf bank_mask:0xf
	v_fmac_f32_dpp v133, -v13, v131 row_newbcast:15 row_mask:0xf bank_mask:0xf
	ds_read_b32 v13, v0 offset:9792
	s_waitcnt lgkmcnt(10)
	v_fmac_f32_dpp v133, -v14, v132 row_newbcast:0 row_mask:0xf bank_mask:0xf
	ds_write_b32 v169, v133 offset:8976
	v_cmp_eq_u32_e32 vcc, 34, v166
	s_nop 1
	v_cndmask_b32_e64 v134, 0, 1.0, vcc
	ds_read_b32 v14, v0 offset:9856
	s_waitcnt lgkmcnt(10)
; DI void d2_chunk(const Params& P, int l, int chunk, LAS float* Nm, LAS float* gs, int lane_in) {
;     ...
;         D2_TBLOCK(0); D2_TBLOCK(1); D2_TBLOCK(2); D2_TBLOCK(3);
	v_fmac_f32_dpp v134, -v15, v100 row_newbcast:0 row_mask:0xf bank_mask:0xf
	v_fmac_f32_dpp v134, -v15, v101 row_newbcast:1 row_mask:0xf bank_mask:0xf
	v_fmac_f32_dpp v134, -v15, v102 row_newbcast:2 row_mask:0xf bank_mask:0xf
	v_fmac_f32_dpp v134, -v15, v103 row_newbcast:3 row_mask:0xf bank_mask:0xf
	v_fmac_f32_dpp v134, -v15, v104 row_newbcast:4 row_mask:0xf bank_mask:0xf
	v_fmac_f32_dpp v134, -v15, v105 row_newbcast:5 row_mask:0xf bank_mask:0xf
	v_fmac_f32_dpp v134, -v15, v106 row_newbcast:6 row_mask:0xf bank_mask:0xf
	v_fmac_f32_dpp v134, -v15, v107 row_newbcast:7 row_mask:0xf bank_mask:0xf
	v_fmac_f32_dpp v134, -v15, v108 row_newbcast:8 row_mask:0xf bank_mask:0xf
	v_fmac_f32_dpp v134, -v15, v109 row_newbcast:9 row_mask:0xf bank_mask:0xf
	v_fmac_f32_dpp v134, -v15, v110 row_newbcast:10 row_mask:0xf bank_mask:0xf
	v_fmac_f32_dpp v134, -v15, v111 row_newbcast:11 row_mask:0xf bank_mask:0xf
	v_fmac_f32_dpp v134, -v15, v112 row_newbcast:12 row_mask:0xf bank_mask:0xf
	v_fmac_f32_dpp v134, -v15, v113 row_newbcast:13 row_mask:0xf bank_mask:0xf
	v_fmac_f32_dpp v134, -v15, v114 row_newbcast:14 row_mask:0xf bank_mask:0xf
	v_fmac_f32_dpp v134, -v15, v115 row_newbcast:15 row_mask:0xf bank_mask:0xf
	ds_read_b32 v15, v0 offset:9920
	s_waitcnt lgkmcnt(10)
	v_fmac_f32_dpp v134, -v16, v116 row_newbcast:0 row_mask:0xf bank_mask:0xf
	v_fmac_f32_dpp v134, -v16, v117 row_newbcast:1 row_mask:0xf bank_mask:0xf
	v_fmac_f32_dpp v134, -v16, v118 row_newbcast:2 row_mask:0xf bank_mask:0xf
	v_fmac_f32_dpp v134, -v16, v119 row_newbcast:3 row_mask:0xf bank_mask:0xf
	v_fmac_f32_dpp v134, -v16, v120 row_newbcast:4 row_mask:0xf bank_mask:0xf
	v_fmac_f32_dpp v134, -v16, v121 row_newbcast:5 row_mask:0xf bank_mask:0xf
	v_fmac_f32_dpp v134, -v16, v122 row_newbcast:6 row_mask:0xf bank_mask:0xf
	v_fmac_f32_dpp v134, -v16, v123 row_newbcast:7 row_mask:0xf bank_mask:0xf
	v_fmac_f32_dpp v134, -v16, v124 row_newbcast:8 row_mask:0xf bank_mask:0xf
	v_fmac_f32_dpp v134, -v16, v125 row_newbcast:9 row_mask:0xf bank_mask:0xf
	v_fmac_f32_dpp v134, -v16, v126 row_newbcast:10 row_mask:0xf bank_mask:0xf
	v_fmac_f32_dpp v134, -v16, v127 row_newbcast:11 row_mask:0xf bank_mask:0xf
	v_fmac_f32_dpp v134, -v16, v128 row_newbcast:12 row_mask:0xf bank_mask:0xf
	v_fmac_f32_dpp v134, -v16, v129 row_newbcast:13 row_mask:0xf bank_mask:0xf
	v_fmac_f32_dpp v134, -v16, v130 row_newbcast:14 row_mask:0xf bank_mask:0xf
	v_fmac_f32_dpp v134, -v16, v131 row_newbcast:15 row_mask:0xf bank_mask:0xf
	ds_read_b32 v16, v0 offset:10064
	s_waitcnt lgkmcnt(9)
	v_fmac_f32_dpp v134, -v17, v132 row_newbcast:0 row_mask:0xf bank_mask:0xf
	v_fmac_f32_dpp v134, -v17, v133 row_newbcast:1 row_mask:0xf bank_mask:0xf
	ds_write_b32 v169, v134 offset:9248
	v_cmp_eq_u32_e32 vcc, 35, v166
	s_nop 1
	v_cndmask_b32_e64 v135, 0, 1.0, vcc
	ds_read_b32 v17, v0 offset:10128
	s_waitcnt lgkmcnt(10)
	v_fmac_f32_dpp v135, -v18, v100 row_newbcast:0 row_mask:0xf bank_mask:0xf
	v_fmac_f32_dpp v135, -v18, v101 row_newbcast:1 row_mask:0xf bank_mask:0xf
	v_fmac_f32_dpp v135, -v18, v102 row_newbcast:2 row_mask:0xf bank_mask:0xf
	v_fmac_f32_dpp v135, -v18, v103 row_newbcast:3 row_mask:0xf bank_mask:0xf
	v_fmac_f32_dpp v135, -v18, v104 row_newbcast:4 row_mask:0xf bank_mask:0xf
	v_fmac_f32_dpp v135, -v18, v105 row_newbcast:5 row_mask:0xf bank_mask:0xf
	v_fmac_f32_dpp v135, -v18, v106 row_newbcast:6 row_mask:0xf bank_mask:0xf
	v_fmac_f32_dpp v135, -v18, v107 row_newbcast:7 row_mask:0xf bank_mask:0xf
	v_fmac_f32_dpp v135, -v18, v108 row_newbcast:8 row_mask:0xf bank_mask:0xf
	v_fmac_f32_dpp v135, -v18, v109 row_newbcast:9 row_mask:0xf bank_mask:0xf
	v_fmac_f32_dpp v135, -v18, v110 row_newbcast:10 row_mask:0xf bank_mask:0xf
	v_fmac_f32_dpp v135, -v18, v111 row_newbcast:11 row_mask:0xf bank_mask:0xf
	v_fmac_f32_dpp v135, -v18, v112 row_newbcast:12 row_mask:0xf bank_mask:0xf
	v_fmac_f32_dpp v135, -v18, v113 row_newbcast:13 row_mask:0xf bank_mask:0xf
	v_fmac_f32_dpp v135, -v18, v114 row_newbcast:14 row_mask:0xf bank_mask:0xf
	v_fmac_f32_dpp v135, -v18, v115 row_newbcast:15 row_mask:0xf bank_mask:0xf
	ds_read_b32 v18, v0 offset:10192
	s_waitcnt lgkmcnt(9)
	v_fmac_f32_dpp v135, -v19, v116 row_newbcast:0 row_mask:0xf bank_mask:0xf
	v_fmac_f32_dpp v135, -v19, v117 row_newbcast:1 row_mask:0xf bank_mask:0xf
	v_fmac_f32_dpp v135, -v19, v118 row_newbcast:2 row_mask:0xf bank_mask:0xf
	v_fmac_f32_dpp v135, -v19, v119 row_newbcast:3 row_mask:0xf bank_mask:0xf
	v_fmac_f32_dpp v135, -v19, v120 row_newbcast:4 row_mask:0xf bank_mask:0xf
	v_fmac_f32_dpp v135, -v19, v121 row_newbcast:5 row_mask:0xf bank_mask:0xf
	v_fmac_f32_dpp v135, -v19, v122 row_newbcast:6 row_mask:0xf bank_mask:0xf
	v_fmac_f32_dpp v135, -v19, v123 row_newbcast:7 row_mask:0xf bank_mask:0xf
	v_fmac_f32_dpp v135, -v19, v124 row_newbcast:8 row_mask:0xf bank_mask:0xf
	v_fmac_f32_dpp v135, -v19, v125 row_newbcast:9 row_mask:0xf bank_mask:0xf
	v_fmac_f32_dpp v135, -v19, v126 row_newbcast:10 row_mask:0xf bank_mask:0xf
	v_fmac_f32_dpp v135, -v19, v127 row_newbcast:11 row_mask:0xf bank_mask:0xf
	v_fmac_f32_dpp v135, -v19, v128 row_newbcast:12 row_mask:0xf bank_mask:0xf
	v_fmac_f32_dpp v135, -v19, v129 row_newbcast:13 row_mask:0xf bank_mask:0xf
	v_fmac_f32_dpp v135, -v19, v130 row_newbcast:14 row_mask:0xf bank_mask:0xf
	v_fmac_f32_dpp v135, -v19, v131 row_newbcast:15 row_mask:0xf bank_mask:0xf
	ds_read_b32 v19, v0 offset:10336
	s_waitcnt lgkmcnt(9)
	v_fmac_f32_dpp v135, -v12, v132 row_newbcast:0 row_mask:0xf bank_mask:0xf
	v_fmac_f32_dpp v135, -v12, v133 row_newbcast:1 row_mask:0xf bank_mask:0xf
	v_fmac_f32_dpp v135, -v12, v134 row_newbcast:2 row_mask:0xf bank_mask:0xf
	ds_write_b32 v169, v135 offset:9520
	v_cmp_eq_u32_e32 vcc, 36, v166
	s_nop 1
	v_cndmask_b32_e64 v136, 0, 1.0, vcc
	ds_read_b32 v12, v0 offset:10400
	s_waitcnt lgkmcnt(10)
; DI void d2_chunk(const Params& P, int l, int chunk, LAS float* Nm, LAS float* gs, int lane_in) {
;     ...
;         D2_TBLOCK(0); D2_TBLOCK(1); D2_TBLOCK(2); D2_TBLOCK(3);
	v_fmac_f32_dpp v136, -v13, v100 row_newbcast:0 row_mask:0xf bank_mask:0xf
	v_fmac_f32_dpp v136, -v13, v101 row_newbcast:1 row_mask:0xf bank_mask:0xf
	v_fmac_f32_dpp v136, -v13, v102 row_newbcast:2 row_mask:0xf bank_mask:0xf
	v_fmac_f32_dpp v136, -v13, v103 row_newbcast:3 row_mask:0xf bank_mask:0xf
	v_fmac_f32_dpp v136, -v13, v104 row_newbcast:4 row_mask:0xf bank_mask:0xf
	v_fmac_f32_dpp v136, -v13, v105 row_newbcast:5 row_mask:0xf bank_mask:0xf
	v_fmac_f32_dpp v136, -v13, v106 row_newbcast:6 row_mask:0xf bank_mask:0xf
	v_fmac_f32_dpp v136, -v13, v107 row_newbcast:7 row_mask:0xf bank_mask:0xf
	v_fmac_f32_dpp v136, -v13, v108 row_newbcast:8 row_mask:0xf bank_mask:0xf
	v_fmac_f32_dpp v136, -v13, v109 row_newbcast:9 row_mask:0xf bank_mask:0xf
	v_fmac_f32_dpp v136, -v13, v110 row_newbcast:10 row_mask:0xf bank_mask:0xf
	v_fmac_f32_dpp v136, -v13, v111 row_newbcast:11 row_mask:0xf bank_mask:0xf
	v_fmac_f32_dpp v136, -v13, v112 row_newbcast:12 row_mask:0xf bank_mask:0xf
	v_fmac_f32_dpp v136, -v13, v113 row_newbcast:13 row_mask:0xf bank_mask:0xf
	v_fmac_f32_dpp v136, -v13, v114 row_newbcast:14 row_mask:0xf bank_mask:0xf
	v_fmac_f32_dpp v136, -v13, v115 row_newbcast:15 row_mask:0xf bank_mask:0xf
	ds_read_b32 v13, v0 offset:10464
	s_waitcnt lgkmcnt(9)
	v_fmac_f32_dpp v136, -v14, v116 row_newbcast:0 row_mask:0xf bank_mask:0xf
	v_fmac_f32_dpp v136, -v14, v117 row_newbcast:1 row_mask:0xf bank_mask:0xf
	v_fmac_f32_dpp v136, -v14, v118 row_newbcast:2 row_mask:0xf bank_mask:0xf
	v_fmac_f32_dpp v136, -v14, v119 row_newbcast:3 row_mask:0xf bank_mask:0xf
	v_fmac_f32_dpp v136, -v14, v120 row_newbcast:4 row_mask:0xf bank_mask:0xf
	v_fmac_f32_dpp v136, -v14, v121 row_newbcast:5 row_mask:0xf bank_mask:0xf
	v_fmac_f32_dpp v136, -v14, v122 row_newbcast:6 row_mask:0xf bank_mask:0xf
	v_fmac_f32_dpp v136, -v14, v123 row_newbcast:7 row_mask:0xf bank_mask:0xf
	v_fmac_f32_dpp v136, -v14, v124 row_newbcast:8 row_mask:0xf bank_mask:0xf
	v_fmac_f32_dpp v136, -v14, v125 row_newbcast:9 row_mask:0xf bank_mask:0xf
	v_fmac_f32_dpp v136, -v14, v126 row_newbcast:10 row_mask:0xf bank_mask:0xf
	v_fmac_f32_dpp v136, -v14, v127 row_newbcast:11 row_mask:0xf bank_mask:0xf
	v_fmac_f32_dpp v136, -v14, v128 row_newbcast:12 row_mask:0xf bank_mask:0xf
	v_fmac_f32_dpp v136, -v14, v129 row_newbcast:13 row_mask:0xf bank_mask:0xf
	v_fmac_f32_dpp v136, -v14, v130 row_newbcast:14 row_mask:0xf bank_mask:0xf
	v_fmac_f32_dpp v136, -v14, v131 row_newbcast:15 row_mask:0xf bank_mask:0xf
	ds_read_b32 v14, v0 offset:10608
	s_waitcnt lgkmcnt(9)
	v_fmac_f32_dpp v136, -v15, v132 row_newbcast:0 row_mask:0xf bank_mask:0xf
	v_fmac_f32_dpp v136, -v15, v133 row_newbcast:1 row_mask:0xf bank_mask:0xf
	v_fmac_f32_dpp v136, -v15, v134 row_newbcast:2 row_mask:0xf bank_mask:0xf
	v_fmac_f32_dpp v136, -v15, v135 row_newbcast:3 row_mask:0xf bank_mask:0xf
	ds_write_b32 v169, v136 offset:9792
	v_cmp_eq_u32_e32 vcc, 37, v166
	s_nop 1
	v_cndmask_b32_e64 v137, 0, 1.0, vcc
	ds_read_b32 v15, v0 offset:10672
	s_waitcnt lgkmcnt(10)
	v_fmac_f32_dpp v137, -v16, v100 row_newbcast:0 row_mask:0xf bank_mask:0xf
	v_fmac_f32_dpp v137, -v16, v101 row_newbcast:1 row_mask:0xf bank_mask:0xf
	v_fmac_f32_dpp v137, -v16, v102 row_newbcast:2 row_mask:0xf bank_mask:0xf
	v_fmac_f32_dpp v137, -v16, v103 row_newbcast:3 row_mask:0xf bank_mask:0xf
	v_fmac_f32_dpp v137, -v16, v104 row_newbcast:4 row_mask:0xf bank_mask:0xf
	v_fmac_f32_dpp v137, -v16, v105 row_newbcast:5 row_mask:0xf bank_mask:0xf
	v_fmac_f32_dpp v137, -v16, v106 row_newbcast:6 row_mask:0xf bank_mask:0xf
	v_fmac_f32_dpp v137, -v16, v107 row_newbcast:7 row_mask:0xf bank_mask:0xf
	v_fmac_f32_dpp v137, -v16, v108 row_newbcast:8 row_mask:0xf bank_mask:0xf
	v_fmac_f32_dpp v137, -v16, v109 row_newbcast:9 row_mask:0xf bank_mask:0xf
	v_fmac_f32_dpp v137, -v16, v110 row_newbcast:10 row_mask:0xf bank_mask:0xf
	v_fmac_f32_dpp v137, -v16, v111 row_newbcast:11 row_mask:0xf bank_mask:0xf
	v_fmac_f32_dpp v137, -v16, v112 row_newbcast:12 row_mask:0xf bank_mask:0xf
	v_fmac_f32_dpp v137, -v16, v113 row_newbcast:13 row_mask:0xf bank_mask:0xf
	v_fmac_f32_dpp v137, -v16, v114 row_newbcast:14 row_mask:0xf bank_mask:0xf
	v_fmac_f32_dpp v137, -v16, v115 row_newbcast:15 row_mask:0xf bank_mask:0xf
	ds_read_b32 v16, v0 offset:10736
	s_waitcnt lgkmcnt(9)
	v_fmac_f32_dpp v137, -v17, v116 row_newbcast:0 row_mask:0xf bank_mask:0xf
	v_fmac_f32_dpp v137, -v17, v117 row_newbcast:1 row_mask:0xf bank_mask:0xf
	v_fmac_f32_dpp v137, -v17, v118 row_newbcast:2 row_mask:0xf bank_mask:0xf
	v_fmac_f32_dpp v137, -v17, v119 row_newbcast:3 row_mask:0xf bank_mask:0xf
	v_fmac_f32_dpp v137, -v17, v120 row_newbcast:4 row_mask:0xf bank_mask:0xf
	v_fmac_f32_dpp v137, -v17, v121 row_newbcast:5 row_mask:0xf bank_mask:0xf
	v_fmac_f32_dpp v137, -v17, v122 row_newbcast:6 row_mask:0xf bank_mask:0xf
	v_fmac_f32_dpp v137, -v17, v123 row_newbcast:7 row_mask:0xf bank_mask:0xf
	v_fmac_f32_dpp v137, -v17, v124 row_newbcast:8 row_mask:0xf bank_mask:0xf
	v_fmac_f32_dpp v137, -v17, v125 row_newbcast:9 row_mask:0xf bank_mask:0xf
	v_fmac_f32_dpp v137, -v17, v126 row_newbcast:10 row_mask:0xf bank_mask:0xf
	v_fmac_f32_dpp v137, -v17, v127 row_newbcast:11 row_mask:0xf bank_mask:0xf
	v_fmac_f32_dpp v137, -v17, v128 row_newbcast:12 row_mask:0xf bank_mask:0xf
	v_fmac_f32_dpp v137, -v17, v129 row_newbcast:13 row_mask:0xf bank_mask:0xf
	v_fmac_f32_dpp v137, -v17, v130 row_newbcast:14 row_mask:0xf bank_mask:0xf
	v_fmac_f32_dpp v137, -v17, v131 row_newbcast:15 row_mask:0xf bank_mask:0xf
	ds_read_b32 v17, v0 offset:10880
	s_waitcnt lgkmcnt(9)
; DI void d2_chunk(const Params& P, int l, int chunk, LAS float* Nm, LAS float* gs, int lane_in) {
;     ...
;         D2_TBLOCK(0); D2_TBLOCK(1); D2_TBLOCK(2); D2_TBLOCK(3);
	v_fmac_f32_dpp v137, -v18, v132 row_newbcast:0 row_mask:0xf bank_mask:0xf
	v_fmac_f32_dpp v137, -v18, v133 row_newbcast:1 row_mask:0xf bank_mask:0xf
	v_fmac_f32_dpp v137, -v18, v134 row_newbcast:2 row_mask:0xf bank_mask:0xf
	v_fmac_f32_dpp v137, -v18, v135 row_newbcast:3 row_mask:0xf bank_mask:0xf
	v_fmac_f32_dpp v137, -v18, v136 row_newbcast:4 row_mask:0xf bank_mask:0xf
	ds_write_b32 v169, v137 offset:10064
	v_cmp_eq_u32_e32 vcc, 38, v166
	s_nop 1
	v_cndmask_b32_e64 v138, 0, 1.0, vcc
	ds_read_b32 v18, v0 offset:10944
	s_waitcnt lgkmcnt(10)
	v_fmac_f32_dpp v138, -v19, v100 row_newbcast:0 row_mask:0xf bank_mask:0xf
	v_fmac_f32_dpp v138, -v19, v101 row_newbcast:1 row_mask:0xf bank_mask:0xf
	v_fmac_f32_dpp v138, -v19, v102 row_newbcast:2 row_mask:0xf bank_mask:0xf
	v_fmac_f32_dpp v138, -v19, v103 row_newbcast:3 row_mask:0xf bank_mask:0xf
	v_fmac_f32_dpp v138, -v19, v104 row_newbcast:4 row_mask:0xf bank_mask:0xf
	v_fmac_f32_dpp v138, -v19, v105 row_newbcast:5 row_mask:0xf bank_mask:0xf
	v_fmac_f32_dpp v138, -v19, v106 row_newbcast:6 row_mask:0xf bank_mask:0xf
	v_fmac_f32_dpp v138, -v19, v107 row_newbcast:7 row_mask:0xf bank_mask:0xf
	v_fmac_f32_dpp v138, -v19, v108 row_newbcast:8 row_mask:0xf bank_mask:0xf
	v_fmac_f32_dpp v138, -v19, v109 row_newbcast:9 row_mask:0xf bank_mask:0xf
	v_fmac_f32_dpp v138, -v19, v110 row_newbcast:10 row_mask:0xf bank_mask:0xf
	v_fmac_f32_dpp v138, -v19, v111 row_newbcast:11 row_mask:0xf bank_mask:0xf
	v_fmac_f32_dpp v138, -v19, v112 row_newbcast:12 row_mask:0xf bank_mask:0xf
	v_fmac_f32_dpp v138, -v19, v113 row_newbcast:13 row_mask:0xf bank_mask:0xf
	v_fmac_f32_dpp v138, -v19, v114 row_newbcast:14 row_mask:0xf bank_mask:0xf
	v_fmac_f32_dpp v138, -v19, v115 row_newbcast:15 row_mask:0xf bank_mask:0xf
	ds_read_b32 v19, v0 offset:11008
	s_waitcnt lgkmcnt(9)
	v_fmac_f32_dpp v138, -v12, v116 row_newbcast:0 row_mask:0xf bank_mask:0xf
	v_fmac_f32_dpp v138, -v12, v117 row_newbcast:1 row_mask:0xf bank_mask:0xf
	v_fmac_f32_dpp v138, -v12, v118 row_newbcast:2 row_mask:0xf bank_mask:0xf
	v_fmac_f32_dpp v138, -v12, v119 row_newbcast:3 row_mask:0xf bank_mask:0xf
	v_fmac_f32_dpp v138, -v12, v120 row_newbcast:4 row_mask:0xf bank_mask:0xf
	v_fmac_f32_dpp v138, -v12, v121 row_newbcast:5 row_mask:0xf bank_mask:0xf
	v_fmac_f32_dpp v138, -v12, v122 row_newbcast:6 row_mask:0xf bank_mask:0xf
	v_fmac_f32_dpp v138, -v12, v123 row_newbcast:7 row_mask:0xf bank_mask:0xf
	v_fmac_f32_dpp v138, -v12, v124 row_newbcast:8 row_mask:0xf bank_mask:0xf
	v_fmac_f32_dpp v138, -v12, v125 row_newbcast:9 row_mask:0xf bank_mask:0xf
	v_fmac_f32_dpp v138, -v12, v126 row_newbcast:10 row_mask:0xf bank_mask:0xf
	v_fmac_f32_dpp v138, -v12, v127 row_newbcast:11 row_mask:0xf bank_mask:0xf
	v_fmac_f32_dpp v138, -v12, v128 row_newbcast:12 row_mask:0xf bank_mask:0xf
	v_fmac_f32_dpp v138, -v12, v129 row_newbcast:13 row_mask:0xf bank_mask:0xf
	v_fmac_f32_dpp v138, -v12, v130 row_newbcast:14 row_mask:0xf bank_mask:0xf
	v_fmac_f32_dpp v138, -v12, v131 row_newbcast:15 row_mask:0xf bank_mask:0xf
	ds_read_b32 v12, v0 offset:11152
	s_waitcnt lgkmcnt(9)
	v_fmac_f32_dpp v138, -v13, v132 row_newbcast:0 row_mask:0xf bank_mask:0xf
	v_fmac_f32_dpp v138, -v13, v133 row_newbcast:1 row_mask:0xf bank_mask:0xf
	v_fmac_f32_dpp v138, -v13, v134 row_newbcast:2 row_mask:0xf bank_mask:0xf
	v_fmac_f32_dpp v138, -v13, v135 row_newbcast:3 row_mask:0xf bank_mask:0xf
	v_fmac_f32_dpp v138, -v13, v136 row_newbcast:4 row_mask:0xf bank_mask:0xf
	v_fmac_f32_dpp v138, -v13, v137 row_newbcast:5 row_mask:0xf bank_mask:0xf
	ds_write_b32 v169, v138 offset:10336
	v_cmp_eq_u32_e32 vcc, 39, v166
	s_nop 1
	v_cndmask_b32_e64 v139, 0, 1.0, vcc
	ds_read_b32 v13, v0 offset:11216
	s_waitcnt lgkmcnt(10)
	v_fmac_f32_dpp v139, -v14, v100 row_newbcast:0 row_mask:0xf bank_mask:0xf
	v_fmac_f32_dpp v139, -v14, v101 row_newbcast:1 row_mask:0xf bank_mask:0xf
	v_fmac_f32_dpp v139, -v14, v102 row_newbcast:2 row_mask:0xf bank_mask:0xf
	v_fmac_f32_dpp v139, -v14, v103 row_newbcast:3 row_mask:0xf bank_mask:0xf
	v_fmac_f32_dpp v139, -v14, v104 row_newbcast:4 row_mask:0xf bank_mask:0xf
	v_fmac_f32_dpp v139, -v14, v105 row_newbcast:5 row_mask:0xf bank_mask:0xf
	v_fmac_f32_dpp v139, -v14, v106 row_newbcast:6 row_mask:0xf bank_mask:0xf
	v_fmac_f32_dpp v139, -v14, v107 row_newbcast:7 row_mask:0xf bank_mask:0xf
	v_fmac_f32_dpp v139, -v14, v108 row_newbcast:8 row_mask:0xf bank_mask:0xf
	v_fmac_f32_dpp v139, -v14, v109 row_newbcast:9 row_mask:0xf bank_mask:0xf
	v_fmac_f32_dpp v139, -v14, v110 row_newbcast:10 row_mask:0xf bank_mask:0xf
	v_fmac_f32_dpp v139, -v14, v111 row_newbcast:11 row_mask:0xf bank_mask:0xf
	v_fmac_f32_dpp v139, -v14, v112 row_newbcast:12 row_mask:0xf bank_mask:0xf
	v_fmac_f32_dpp v139, -v14, v113 row_newbcast:13 row_mask:0xf bank_mask:0xf
	v_fmac_f32_dpp v139, -v14, v114 row_newbcast:14 row_mask:0xf bank_mask:0xf
	v_fmac_f32_dpp v139, -v14, v115 row_newbcast:15 row_mask:0xf bank_mask:0xf
	ds_read_b32 v14, v0 offset:11280
	s_waitcnt lgkmcnt(9)
	v_fmac_f32_dpp v139, -v15, v116 row_newbcast:0 row_mask:0xf bank_mask:0xf
	v_fmac_f32_dpp v139, -v15, v117 row_newbcast:1 row_mask:0xf bank_mask:0xf
	v_fmac_f32_dpp v139, -v15, v118 row_newbcast:2 row_mask:0xf bank_mask:0xf
	v_fmac_f32_dpp v139, -v15, v119 row_newbcast:3 row_mask:0xf bank_mask:0xf
	v_fmac_f32_dpp v139, -v15, v120 row_newbcast:4 row_mask:0xf bank_mask:0xf
	v_fmac_f32_dpp v139, -v15, v121 row_newbcast:5 row_mask:0xf bank_mask:0xf
	v_fmac_f32_dpp v139, -v15, v122 row_newbcast:6 row_mask:0xf bank_mask:0xf
	v_fmac_f32_dpp v139, -v15, v123 row_newbcast:7 row_mask:0xf bank_mask:0xf
	v_fmac_f32_dpp v139, -v15, v124 row_newbcast:8 row_mask:0xf bank_mask:0xf
	v_fmac_f32_dpp v139, -v15, v125 row_newbcast:9 row_mask:0xf bank_mask:0xf
	v_fmac_f32_dpp v139, -v15, v126 row_newbcast:10 row_mask:0xf bank_mask:0xf
	v_fmac_f32_dpp v139, -v15, v127 row_newbcast:11 row_mask:0xf bank_mask:0xf
	v_fmac_f32_dpp v139, -v15, v128 row_newbcast:12 row_mask:0xf bank_mask:0xf
	v_fmac_f32_dpp v139, -v15, v129 row_newbcast:13 row_mask:0xf bank_mask:0xf
	v_fmac_f32_dpp v139, -v15, v130 row_newbcast:14 row_mask:0xf bank_mask:0xf
	v_fmac_f32_dpp v139, -v15, v131 row_newbcast:15 row_mask:0xf bank_mask:0xf
	ds_read_b32 v15, v0 offset:11424
	s_waitcnt lgkmcnt(9)
; DI void d2_chunk(const Params& P, int l, int chunk, LAS float* Nm, LAS float* gs, int lane_in) {
;     ...
;         D2_TBLOCK(0); D2_TBLOCK(1); D2_TBLOCK(2); D2_TBLOCK(3);
	v_fmac_f32_dpp v139, -v16, v132 row_newbcast:0 row_mask:0xf bank_mask:0xf
	v_fmac_f32_dpp v139, -v16, v133 row_newbcast:1 row_mask:0xf bank_mask:0xf
	v_fmac_f32_dpp v139, -v16, v134 row_newbcast:2 row_mask:0xf bank_mask:0xf
	v_fmac_f32_dpp v139, -v16, v135 row_newbcast:3 row_mask:0xf bank_mask:0xf
	v_fmac_f32_dpp v139, -v16, v136 row_newbcast:4 row_mask:0xf bank_mask:0xf
	v_fmac_f32_dpp v139, -v16, v137 row_newbcast:5 row_mask:0xf bank_mask:0xf
	v_fmac_f32_dpp v139, -v16, v138 row_newbcast:6 row_mask:0xf bank_mask:0xf
	ds_write_b32 v169, v139 offset:10608
	v_cmp_eq_u32_e32 vcc, 40, v166
	s_nop 1
	v_cndmask_b32_e64 v140, 0, 1.0, vcc
	ds_read_b32 v16, v0 offset:11488
	s_waitcnt lgkmcnt(10)
	v_fmac_f32_dpp v140, -v17, v100 row_newbcast:0 row_mask:0xf bank_mask:0xf
	v_fmac_f32_dpp v140, -v17, v101 row_newbcast:1 row_mask:0xf bank_mask:0xf
	v_fmac_f32_dpp v140, -v17, v102 row_newbcast:2 row_mask:0xf bank_mask:0xf
	v_fmac_f32_dpp v140, -v17, v103 row_newbcast:3 row_mask:0xf bank_mask:0xf
	v_fmac_f32_dpp v140, -v17, v104 row_newbcast:4 row_mask:0xf bank_mask:0xf
	v_fmac_f32_dpp v140, -v17, v105 row_newbcast:5 row_mask:0xf bank_mask:0xf
	v_fmac_f32_dpp v140, -v17, v106 row_newbcast:6 row_mask:0xf bank_mask:0xf
	v_fmac_f32_dpp v140, -v17, v107 row_newbcast:7 row_mask:0xf bank_mask:0xf
	v_fmac_f32_dpp v140, -v17, v108 row_newbcast:8 row_mask:0xf bank_mask:0xf
	v_fmac_f32_dpp v140, -v17, v109 row_newbcast:9 row_mask:0xf bank_mask:0xf
	v_fmac_f32_dpp v140, -v17, v110 row_newbcast:10 row_mask:0xf bank_mask:0xf
	v_fmac_f32_dpp v140, -v17, v111 row_newbcast:11 row_mask:0xf bank_mask:0xf
	v_fmac_f32_dpp v140, -v17, v112 row_newbcast:12 row_mask:0xf bank_mask:0xf
	v_fmac_f32_dpp v140, -v17, v113 row_newbcast:13 row_mask:0xf bank_mask:0xf
	v_fmac_f32_dpp v140, -v17, v114 row_newbcast:14 row_mask:0xf bank_mask:0xf
	v_fmac_f32_dpp v140, -v17, v115 row_newbcast:15 row_mask:0xf bank_mask:0xf
	ds_read_b32 v17, v0 offset:11552
	s_waitcnt lgkmcnt(9)
	v_fmac_f32_dpp v140, -v18, v116 row_newbcast:0 row_mask:0xf bank_mask:0xf
	v_fmac_f32_dpp v140, -v18, v117 row_newbcast:1 row_mask:0xf bank_mask:0xf
	v_fmac_f32_dpp v140, -v18, v118 row_newbcast:2 row_mask:0xf bank_mask:0xf
	v_fmac_f32_dpp v140, -v18, v119 row_newbcast:3 row_mask:0xf bank_mask:0xf
	v_fmac_f32_dpp v140, -v18, v120 row_newbcast:4 row_mask:0xf bank_mask:0xf
	v_fmac_f32_dpp v140, -v18, v121 row_newbcast:5 row_mask:0xf bank_mask:0xf
	v_fmac_f32_dpp v140, -v18, v122 row_newbcast:6 row_mask:0xf bank_mask:0xf
	v_fmac_f32_dpp v140, -v18, v123 row_newbcast:7 row_mask:0xf bank_mask:0xf
	v_fmac_f32_dpp v140, -v18, v124 row_newbcast:8 row_mask:0xf bank_mask:0xf
	v_fmac_f32_dpp v140, -v18, v125 row_newbcast:9 row_mask:0xf bank_mask:0xf
	v_fmac_f32_dpp v140, -v18, v126 row_newbcast:10 row_mask:0xf bank_mask:0xf
	v_fmac_f32_dpp v140, -v18, v127 row_newbcast:11 row_mask:0xf bank_mask:0xf
	v_fmac_f32_dpp v140, -v18, v128 row_newbcast:12 row_mask:0xf bank_mask:0xf
	v_fmac_f32_dpp v140, -v18, v129 row_newbcast:13 row_mask:0xf bank_mask:0xf
	v_fmac_f32_dpp v140, -v18, v130 row_newbcast:14 row_mask:0xf bank_mask:0xf
	v_fmac_f32_dpp v140, -v18, v131 row_newbcast:15 row_mask:0xf bank_mask:0xf
	ds_read_b32 v18, v0 offset:11696
	s_waitcnt lgkmcnt(9)
	v_fmac_f32_dpp v140, -v19, v132 row_newbcast:0 row_mask:0xf bank_mask:0xf
	v_fmac_f32_dpp v140, -v19, v133 row_newbcast:1 row_mask:0xf bank_mask:0xf
	v_fmac_f32_dpp v140, -v19, v134 row_newbcast:2 row_mask:0xf bank_mask:0xf
	v_fmac_f32_dpp v140, -v19, v135 row_newbcast:3 row_mask:0xf bank_mask:0xf
	v_fmac_f32_dpp v140, -v19, v136 row_newbcast:4 row_mask:0xf bank_mask:0xf
	v_fmac_f32_dpp v140, -v19, v137 row_newbcast:5 row_mask:0xf bank_mask:0xf
	v_fmac_f32_dpp v140, -v19, v138 row_newbcast:6 row_mask:0xf bank_mask:0xf
	v_fmac_f32_dpp v140, -v19, v139 row_newbcast:7 row_mask:0xf bank_mask:0xf
	ds_write_b32 v169, v140 offset:10880
	v_cmp_eq_u32_e32 vcc, 41, v166
	s_nop 1
	v_cndmask_b32_e64 v141, 0, 1.0, vcc
	ds_read_b32 v19, v0 offset:11760
	s_waitcnt lgkmcnt(10)
	v_fmac_f32_dpp v141, -v12, v100 row_newbcast:0 row_mask:0xf bank_mask:0xf
	v_fmac_f32_dpp v141, -v12, v101 row_newbcast:1 row_mask:0xf bank_mask:0xf
	v_fmac_f32_dpp v141, -v12, v102 row_newbcast:2 row_mask:0xf bank_mask:0xf
	v_fmac_f32_dpp v141, -v12, v103 row_newbcast:3 row_mask:0xf bank_mask:0xf
	v_fmac_f32_dpp v141, -v12, v104 row_newbcast:4 row_mask:0xf bank_mask:0xf
	v_fmac_f32_dpp v141, -v12, v105 row_newbcast:5 row_mask:0xf bank_mask:0xf
	v_fmac_f32_dpp v141, -v12, v106 row_newbcast:6 row_mask:0xf bank_mask:0xf
	v_fmac_f32_dpp v141, -v12, v107 row_newbcast:7 row_mask:0xf bank_mask:0xf
	v_fmac_f32_dpp v141, -v12, v108 row_newbcast:8 row_mask:0xf bank_mask:0xf
	v_fmac_f32_dpp v141, -v12, v109 row_newbcast:9 row_mask:0xf bank_mask:0xf
	v_fmac_f32_dpp v141, -v12, v110 row_newbcast:10 row_mask:0xf bank_mask:0xf
	v_fmac_f32_dpp v141, -v12, v111 row_newbcast:11 row_mask:0xf bank_mask:0xf
	v_fmac_f32_dpp v141, -v12, v112 row_newbcast:12 row_mask:0xf bank_mask:0xf
	v_fmac_f32_dpp v141, -v12, v113 row_newbcast:13 row_mask:0xf bank_mask:0xf
	v_fmac_f32_dpp v141, -v12, v114 row_newbcast:14 row_mask:0xf bank_mask:0xf
	v_fmac_f32_dpp v141, -v12, v115 row_newbcast:15 row_mask:0xf bank_mask:0xf
	ds_read_b32 v12, v0 offset:11824
	s_waitcnt lgkmcnt(9)
; DI void d2_chunk(const Params& P, int l, int chunk, LAS float* Nm, LAS float* gs, int lane_in) {
;     ...
;         D2_TBLOCK(0); D2_TBLOCK(1); D2_TBLOCK(2); D2_TBLOCK(3);
	v_fmac_f32_dpp v141, -v13, v116 row_newbcast:0 row_mask:0xf bank_mask:0xf
	v_fmac_f32_dpp v141, -v13, v117 row_newbcast:1 row_mask:0xf bank_mask:0xf
	v_fmac_f32_dpp v141, -v13, v118 row_newbcast:2 row_mask:0xf bank_mask:0xf
	v_fmac_f32_dpp v141, -v13, v119 row_newbcast:3 row_mask:0xf bank_mask:0xf
	v_fmac_f32_dpp v141, -v13, v120 row_newbcast:4 row_mask:0xf bank_mask:0xf
	v_fmac_f32_dpp v141, -v13, v121 row_newbcast:5 row_mask:0xf bank_mask:0xf
	v_fmac_f32_dpp v141, -v13, v122 row_newbcast:6 row_mask:0xf bank_mask:0xf
	v_fmac_f32_dpp v141, -v13, v123 row_newbcast:7 row_mask:0xf bank_mask:0xf
	v_fmac_f32_dpp v141, -v13, v124 row_newbcast:8 row_mask:0xf bank_mask:0xf
	v_fmac_f32_dpp v141, -v13, v125 row_newbcast:9 row_mask:0xf bank_mask:0xf
	v_fmac_f32_dpp v141, -v13, v126 row_newbcast:10 row_mask:0xf bank_mask:0xf
	v_fmac_f32_dpp v141, -v13, v127 row_newbcast:11 row_mask:0xf bank_mask:0xf
	v_fmac_f32_dpp v141, -v13, v128 row_newbcast:12 row_mask:0xf bank_mask:0xf
	v_fmac_f32_dpp v141, -v13, v129 row_newbcast:13 row_mask:0xf bank_mask:0xf
	v_fmac_f32_dpp v141, -v13, v130 row_newbcast:14 row_mask:0xf bank_mask:0xf
	v_fmac_f32_dpp v141, -v13, v131 row_newbcast:15 row_mask:0xf bank_mask:0xf
	ds_read_b32 v13, v0 offset:11968
	s_waitcnt lgkmcnt(9)
	v_fmac_f32_dpp v141, -v14, v132 row_newbcast:0 row_mask:0xf bank_mask:0xf
	v_fmac_f32_dpp v141, -v14, v133 row_newbcast:1 row_mask:0xf bank_mask:0xf
	v_fmac_f32_dpp v141, -v14, v134 row_newbcast:2 row_mask:0xf bank_mask:0xf
	v_fmac_f32_dpp v141, -v14, v135 row_newbcast:3 row_mask:0xf bank_mask:0xf
	v_fmac_f32_dpp v141, -v14, v136 row_newbcast:4 row_mask:0xf bank_mask:0xf
	v_fmac_f32_dpp v141, -v14, v137 row_newbcast:5 row_mask:0xf bank_mask:0xf
	v_fmac_f32_dpp v141, -v14, v138 row_newbcast:6 row_mask:0xf bank_mask:0xf
	v_fmac_f32_dpp v141, -v14, v139 row_newbcast:7 row_mask:0xf bank_mask:0xf
	v_fmac_f32_dpp v141, -v14, v140 row_newbcast:8 row_mask:0xf bank_mask:0xf
	ds_write_b32 v169, v141 offset:11152
	v_cmp_eq_u32_e32 vcc, 42, v166
	s_nop 1
	v_cndmask_b32_e64 v142, 0, 1.0, vcc
	ds_read_b32 v14, v0 offset:12032
	s_waitcnt lgkmcnt(10)
	v_fmac_f32_dpp v142, -v15, v100 row_newbcast:0 row_mask:0xf bank_mask:0xf
	v_fmac_f32_dpp v142, -v15, v101 row_newbcast:1 row_mask:0xf bank_mask:0xf
	v_fmac_f32_dpp v142, -v15, v102 row_newbcast:2 row_mask:0xf bank_mask:0xf
	v_fmac_f32_dpp v142, -v15, v103 row_newbcast:3 row_mask:0xf bank_mask:0xf
	v_fmac_f32_dpp v142, -v15, v104 row_newbcast:4 row_mask:0xf bank_mask:0xf
	v_fmac_f32_dpp v142, -v15, v105 row_newbcast:5 row_mask:0xf bank_mask:0xf
	v_fmac_f32_dpp v142, -v15, v106 row_newbcast:6 row_mask:0xf bank_mask:0xf
	v_fmac_f32_dpp v142, -v15, v107 row_newbcast:7 row_mask:0xf bank_mask:0xf
	v_fmac_f32_dpp v142, -v15, v108 row_newbcast:8 row_mask:0xf bank_mask:0xf
	v_fmac_f32_dpp v142, -v15, v109 row_newbcast:9 row_mask:0xf bank_mask:0xf
	v_fmac_f32_dpp v142, -v15, v110 row_newbcast:10 row_mask:0xf bank_mask:0xf
	v_fmac_f32_dpp v142, -v15, v111 row_newbcast:11 row_mask:0xf bank_mask:0xf
	v_fmac_f32_dpp v142, -v15, v112 row_newbcast:12 row_mask:0xf bank_mask:0xf
	v_fmac_f32_dpp v142, -v15, v113 row_newbcast:13 row_mask:0xf bank_mask:0xf
	v_fmac_f32_dpp v142, -v15, v114 row_newbcast:14 row_mask:0xf bank_mask:0xf
	v_fmac_f32_dpp v142, -v15, v115 row_newbcast:15 row_mask:0xf bank_mask:0xf
	ds_read_b32 v15, v0 offset:12096
	s_waitcnt lgkmcnt(9)
	v_fmac_f32_dpp v142, -v16, v116 row_newbcast:0 row_mask:0xf bank_mask:0xf
	v_fmac_f32_dpp v142, -v16, v117 row_newbcast:1 row_mask:0xf bank_mask:0xf
	v_fmac_f32_dpp v142, -v16, v118 row_newbcast:2 row_mask:0xf bank_mask:0xf
	v_fmac_f32_dpp v142, -v16, v119 row_newbcast:3 row_mask:0xf bank_mask:0xf
	v_fmac_f32_dpp v142, -v16, v120 row_newbcast:4 row_mask:0xf bank_mask:0xf
	v_fmac_f32_dpp v142, -v16, v121 row_newbcast:5 row_mask:0xf bank_mask:0xf
	v_fmac_f32_dpp v142, -v16, v122 row_newbcast:6 row_mask:0xf bank_mask:0xf
	v_fmac_f32_dpp v142, -v16, v123 row_newbcast:7 row_mask:0xf bank_mask:0xf
	v_fmac_f32_dpp v142, -v16, v124 row_newbcast:8 row_mask:0xf bank_mask:0xf
	v_fmac_f32_dpp v142, -v16, v125 row_newbcast:9 row_mask:0xf bank_mask:0xf
	v_fmac_f32_dpp v142, -v16, v126 row_newbcast:10 row_mask:0xf bank_mask:0xf
	v_fmac_f32_dpp v142, -v16, v127 row_newbcast:11 row_mask:0xf bank_mask:0xf
	v_fmac_f32_dpp v142, -v16, v128 row_newbcast:12 row_mask:0xf bank_mask:0xf
	v_fmac_f32_dpp v142, -v16, v129 row_newbcast:13 row_mask:0xf bank_mask:0xf
	v_fmac_f32_dpp v142, -v16, v130 row_newbcast:14 row_mask:0xf bank_mask:0xf
	v_fmac_f32_dpp v142, -v16, v131 row_newbcast:15 row_mask:0xf bank_mask:0xf
	ds_read_b32 v16, v0 offset:12240
	s_waitcnt lgkmcnt(9)
	v_fmac_f32_dpp v142, -v17, v132 row_newbcast:0 row_mask:0xf bank_mask:0xf
	v_fmac_f32_dpp v142, -v17, v133 row_newbcast:1 row_mask:0xf bank_mask:0xf
	v_fmac_f32_dpp v142, -v17, v134 row_newbcast:2 row_mask:0xf bank_mask:0xf
	v_fmac_f32_dpp v142, -v17, v135 row_newbcast:3 row_mask:0xf bank_mask:0xf
	v_fmac_f32_dpp v142, -v17, v136 row_newbcast:4 row_mask:0xf bank_mask:0xf
	v_fmac_f32_dpp v142, -v17, v137 row_newbcast:5 row_mask:0xf bank_mask:0xf
	v_fmac_f32_dpp v142, -v17, v138 row_newbcast:6 row_mask:0xf bank_mask:0xf
	v_fmac_f32_dpp v142, -v17, v139 row_newbcast:7 row_mask:0xf bank_mask:0xf
	v_fmac_f32_dpp v142, -v17, v140 row_newbcast:8 row_mask:0xf bank_mask:0xf
	v_fmac_f32_dpp v142, -v17, v141 row_newbcast:9 row_mask:0xf bank_mask:0xf
	ds_write_b32 v169, v142 offset:11424
	v_cmp_eq_u32_e32 vcc, 43, v166
	s_nop 1
	v_cndmask_b32_e64 v143, 0, 1.0, vcc
	ds_read_b32 v17, v0 offset:12304
	s_waitcnt lgkmcnt(10)
; DI void d2_chunk(const Params& P, int l, int chunk, LAS float* Nm, LAS float* gs, int lane_in) {
;     ...
;         D2_TBLOCK(0); D2_TBLOCK(1); D2_TBLOCK(2); D2_TBLOCK(3);
	v_fmac_f32_dpp v143, -v18, v100 row_newbcast:0 row_mask:0xf bank_mask:0xf
	v_fmac_f32_dpp v143, -v18, v101 row_newbcast:1 row_mask:0xf bank_mask:0xf
	v_fmac_f32_dpp v143, -v18, v102 row_newbcast:2 row_mask:0xf bank_mask:0xf
	v_fmac_f32_dpp v143, -v18, v103 row_newbcast:3 row_mask:0xf bank_mask:0xf
	v_fmac_f32_dpp v143, -v18, v104 row_newbcast:4 row_mask:0xf bank_mask:0xf
	v_fmac_f32_dpp v143, -v18, v105 row_newbcast:5 row_mask:0xf bank_mask:0xf
	v_fmac_f32_dpp v143, -v18, v106 row_newbcast:6 row_mask:0xf bank_mask:0xf
	v_fmac_f32_dpp v143, -v18, v107 row_newbcast:7 row_mask:0xf bank_mask:0xf
	v_fmac_f32_dpp v143, -v18, v108 row_newbcast:8 row_mask:0xf bank_mask:0xf
	v_fmac_f32_dpp v143, -v18, v109 row_newbcast:9 row_mask:0xf bank_mask:0xf
	v_fmac_f32_dpp v143, -v18, v110 row_newbcast:10 row_mask:0xf bank_mask:0xf
	v_fmac_f32_dpp v143, -v18, v111 row_newbcast:11 row_mask:0xf bank_mask:0xf
	v_fmac_f32_dpp v143, -v18, v112 row_newbcast:12 row_mask:0xf bank_mask:0xf
	v_fmac_f32_dpp v143, -v18, v113 row_newbcast:13 row_mask:0xf bank_mask:0xf
	v_fmac_f32_dpp v143, -v18, v114 row_newbcast:14 row_mask:0xf bank_mask:0xf
	v_fmac_f32_dpp v143, -v18, v115 row_newbcast:15 row_mask:0xf bank_mask:0xf
	ds_read_b32 v18, v0 offset:12368
	s_waitcnt lgkmcnt(9)
	v_fmac_f32_dpp v143, -v19, v116 row_newbcast:0 row_mask:0xf bank_mask:0xf
	v_fmac_f32_dpp v143, -v19, v117 row_newbcast:1 row_mask:0xf bank_mask:0xf
	v_fmac_f32_dpp v143, -v19, v118 row_newbcast:2 row_mask:0xf bank_mask:0xf
	v_fmac_f32_dpp v143, -v19, v119 row_newbcast:3 row_mask:0xf bank_mask:0xf
	v_fmac_f32_dpp v143, -v19, v120 row_newbcast:4 row_mask:0xf bank_mask:0xf
	v_fmac_f32_dpp v143, -v19, v121 row_newbcast:5 row_mask:0xf bank_mask:0xf
	v_fmac_f32_dpp v143, -v19, v122 row_newbcast:6 row_mask:0xf bank_mask:0xf
	v_fmac_f32_dpp v143, -v19, v123 row_newbcast:7 row_mask:0xf bank_mask:0xf
	v_fmac_f32_dpp v143, -v19, v124 row_newbcast:8 row_mask:0xf bank_mask:0xf
	v_fmac_f32_dpp v143, -v19, v125 row_newbcast:9 row_mask:0xf bank_mask:0xf
	v_fmac_f32_dpp v143, -v19, v126 row_newbcast:10 row_mask:0xf bank_mask:0xf
	v_fmac_f32_dpp v143, -v19, v127 row_newbcast:11 row_mask:0xf bank_mask:0xf
	v_fmac_f32_dpp v143, -v19, v128 row_newbcast:12 row_mask:0xf bank_mask:0xf
	v_fmac_f32_dpp v143, -v19, v129 row_newbcast:13 row_mask:0xf bank_mask:0xf
	v_fmac_f32_dpp v143, -v19, v130 row_newbcast:14 row_mask:0xf bank_mask:0xf
	v_fmac_f32_dpp v143, -v19, v131 row_newbcast:15 row_mask:0xf bank_mask:0xf
	ds_read_b32 v19, v0 offset:12512
	s_waitcnt lgkmcnt(9)
	v_fmac_f32_dpp v143, -v12, v132 row_newbcast:0 row_mask:0xf bank_mask:0xf
	v_fmac_f32_dpp v143, -v12, v133 row_newbcast:1 row_mask:0xf bank_mask:0xf
	v_fmac_f32_dpp v143, -v12, v134 row_newbcast:2 row_mask:0xf bank_mask:0xf
	v_fmac_f32_dpp v143, -v12, v135 row_newbcast:3 row_mask:0xf bank_mask:0xf
	v_fmac_f32_dpp v143, -v12, v136 row_newbcast:4 row_mask:0xf bank_mask:0xf
	v_fmac_f32_dpp v143, -v12, v137 row_newbcast:5 row_mask:0xf bank_mask:0xf
	v_fmac_f32_dpp v143, -v12, v138 row_newbcast:6 row_mask:0xf bank_mask:0xf
	v_fmac_f32_dpp v143, -v12, v139 row_newbcast:7 row_mask:0xf bank_mask:0xf
	v_fmac_f32_dpp v143, -v12, v140 row_newbcast:8 row_mask:0xf bank_mask:0xf
	v_fmac_f32_dpp v143, -v12, v141 row_newbcast:9 row_mask:0xf bank_mask:0xf
	v_fmac_f32_dpp v143, -v12, v142 row_newbcast:10 row_mask:0xf bank_mask:0xf
	ds_write_b32 v169, v143 offset:11696
	v_cmp_eq_u32_e32 vcc, 44, v166
	s_nop 1
	v_cndmask_b32_e64 v144, 0, 1.0, vcc
	ds_read_b32 v12, v0 offset:12576
	s_waitcnt lgkmcnt(10)
	v_fmac_f32_dpp v144, -v13, v100 row_newbcast:0 row_mask:0xf bank_mask:0xf
	v_fmac_f32_dpp v144, -v13, v101 row_newbcast:1 row_mask:0xf bank_mask:0xf
	v_fmac_f32_dpp v144, -v13, v102 row_newbcast:2 row_mask:0xf bank_mask:0xf
	v_fmac_f32_dpp v144, -v13, v103 row_newbcast:3 row_mask:0xf bank_mask:0xf
	v_fmac_f32_dpp v144, -v13, v104 row_newbcast:4 row_mask:0xf bank_mask:0xf
	v_fmac_f32_dpp v144, -v13, v105 row_newbcast:5 row_mask:0xf bank_mask:0xf
	v_fmac_f32_dpp v144, -v13, v106 row_newbcast:6 row_mask:0xf bank_mask:0xf
	v_fmac_f32_dpp v144, -v13, v107 row_newbcast:7 row_mask:0xf bank_mask:0xf
	v_fmac_f32_dpp v144, -v13, v108 row_newbcast:8 row_mask:0xf bank_mask:0xf
	v_fmac_f32_dpp v144, -v13, v109 row_newbcast:9 row_mask:0xf bank_mask:0xf
	v_fmac_f32_dpp v144, -v13, v110 row_newbcast:10 row_mask:0xf bank_mask:0xf
	v_fmac_f32_dpp v144, -v13, v111 row_newbcast:11 row_mask:0xf bank_mask:0xf
	v_fmac_f32_dpp v144, -v13, v112 row_newbcast:12 row_mask:0xf bank_mask:0xf
	v_fmac_f32_dpp v144, -v13, v113 row_newbcast:13 row_mask:0xf bank_mask:0xf
	v_fmac_f32_dpp v144, -v13, v114 row_newbcast:14 row_mask:0xf bank_mask:0xf
	v_fmac_f32_dpp v144, -v13, v115 row_newbcast:15 row_mask:0xf bank_mask:0xf
	ds_read_b32 v13, v0 offset:12640
	s_waitcnt lgkmcnt(9)
	v_fmac_f32_dpp v144, -v14, v116 row_newbcast:0 row_mask:0xf bank_mask:0xf
	v_fmac_f32_dpp v144, -v14, v117 row_newbcast:1 row_mask:0xf bank_mask:0xf
	v_fmac_f32_dpp v144, -v14, v118 row_newbcast:2 row_mask:0xf bank_mask:0xf
	v_fmac_f32_dpp v144, -v14, v119 row_newbcast:3 row_mask:0xf bank_mask:0xf
	v_fmac_f32_dpp v144, -v14, v120 row_newbcast:4 row_mask:0xf bank_mask:0xf
	v_fmac_f32_dpp v144, -v14, v121 row_newbcast:5 row_mask:0xf bank_mask:0xf
	v_fmac_f32_dpp v144, -v14, v122 row_newbcast:6 row_mask:0xf bank_mask:0xf
	v_fmac_f32_dpp v144, -v14, v123 row_newbcast:7 row_mask:0xf bank_mask:0xf
	v_fmac_f32_dpp v144, -v14, v124 row_newbcast:8 row_mask:0xf bank_mask:0xf
	v_fmac_f32_dpp v144, -v14, v125 row_newbcast:9 row_mask:0xf bank_mask:0xf
	v_fmac_f32_dpp v144, -v14, v126 row_newbcast:10 row_mask:0xf bank_mask:0xf
	v_fmac_f32_dpp v144, -v14, v127 row_newbcast:11 row_mask:0xf bank_mask:0xf
	v_fmac_f32_dpp v144, -v14, v128 row_newbcast:12 row_mask:0xf bank_mask:0xf
	v_fmac_f32_dpp v144, -v14, v129 row_newbcast:13 row_mask:0xf bank_mask:0xf
	v_fmac_f32_dpp v144, -v14, v130 row_newbcast:14 row_mask:0xf bank_mask:0xf
	v_fmac_f32_dpp v144, -v14, v131 row_newbcast:15 row_mask:0xf bank_mask:0xf
	ds_read_b32 v14, v0 offset:12784
	s_waitcnt lgkmcnt(9)
; DI void d2_chunk(const Params& P, int l, int chunk, LAS float* Nm, LAS float* gs, int lane_in) {
;     ...
;         D2_TBLOCK(0); D2_TBLOCK(1); D2_TBLOCK(2); D2_TBLOCK(3);
	v_fmac_f32_dpp v144, -v15, v132 row_newbcast:0 row_mask:0xf bank_mask:0xf
	v_fmac_f32_dpp v144, -v15, v133 row_newbcast:1 row_mask:0xf bank_mask:0xf
	v_fmac_f32_dpp v144, -v15, v134 row_newbcast:2 row_mask:0xf bank_mask:0xf
	v_fmac_f32_dpp v144, -v15, v135 row_newbcast:3 row_mask:0xf bank_mask:0xf
	v_fmac_f32_dpp v144, -v15, v136 row_newbcast:4 row_mask:0xf bank_mask:0xf
	v_fmac_f32_dpp v144, -v15, v137 row_newbcast:5 row_mask:0xf bank_mask:0xf
	v_fmac_f32_dpp v144, -v15, v138 row_newbcast:6 row_mask:0xf bank_mask:0xf
	v_fmac_f32_dpp v144, -v15, v139 row_newbcast:7 row_mask:0xf bank_mask:0xf
	v_fmac_f32_dpp v144, -v15, v140 row_newbcast:8 row_mask:0xf bank_mask:0xf
	v_fmac_f32_dpp v144, -v15, v141 row_newbcast:9 row_mask:0xf bank_mask:0xf
	v_fmac_f32_dpp v144, -v15, v142 row_newbcast:10 row_mask:0xf bank_mask:0xf
	v_fmac_f32_dpp v144, -v15, v143 row_newbcast:11 row_mask:0xf bank_mask:0xf
	ds_write_b32 v169, v144 offset:11968
	v_cmp_eq_u32_e32 vcc, 45, v166
	s_nop 1
	v_cndmask_b32_e64 v145, 0, 1.0, vcc
	ds_read_b32 v15, v0 offset:12848
	s_waitcnt lgkmcnt(10)
	v_fmac_f32_dpp v145, -v16, v100 row_newbcast:0 row_mask:0xf bank_mask:0xf
	v_fmac_f32_dpp v145, -v16, v101 row_newbcast:1 row_mask:0xf bank_mask:0xf
	v_fmac_f32_dpp v145, -v16, v102 row_newbcast:2 row_mask:0xf bank_mask:0xf
	v_fmac_f32_dpp v145, -v16, v103 row_newbcast:3 row_mask:0xf bank_mask:0xf
	v_fmac_f32_dpp v145, -v16, v104 row_newbcast:4 row_mask:0xf bank_mask:0xf
	v_fmac_f32_dpp v145, -v16, v105 row_newbcast:5 row_mask:0xf bank_mask:0xf
	v_fmac_f32_dpp v145, -v16, v106 row_newbcast:6 row_mask:0xf bank_mask:0xf
	v_fmac_f32_dpp v145, -v16, v107 row_newbcast:7 row_mask:0xf bank_mask:0xf
	v_fmac_f32_dpp v145, -v16, v108 row_newbcast:8 row_mask:0xf bank_mask:0xf
	v_fmac_f32_dpp v145, -v16, v109 row_newbcast:9 row_mask:0xf bank_mask:0xf
	v_fmac_f32_dpp v145, -v16, v110 row_newbcast:10 row_mask:0xf bank_mask:0xf
	v_fmac_f32_dpp v145, -v16, v111 row_newbcast:11 row_mask:0xf bank_mask:0xf
	v_fmac_f32_dpp v145, -v16, v112 row_newbcast:12 row_mask:0xf bank_mask:0xf
	v_fmac_f32_dpp v145, -v16, v113 row_newbcast:13 row_mask:0xf bank_mask:0xf
	v_fmac_f32_dpp v145, -v16, v114 row_newbcast:14 row_mask:0xf bank_mask:0xf
	v_fmac_f32_dpp v145, -v16, v115 row_newbcast:15 row_mask:0xf bank_mask:0xf
	ds_read_b32 v16, v0 offset:12912
	s_waitcnt lgkmcnt(9)
	v_fmac_f32_dpp v145, -v17, v116 row_newbcast:0 row_mask:0xf bank_mask:0xf
	v_fmac_f32_dpp v145, -v17, v117 row_newbcast:1 row_mask:0xf bank_mask:0xf
	v_fmac_f32_dpp v145, -v17, v118 row_newbcast:2 row_mask:0xf bank_mask:0xf
	v_fmac_f32_dpp v145, -v17, v119 row_newbcast:3 row_mask:0xf bank_mask:0xf
	v_fmac_f32_dpp v145, -v17, v120 row_newbcast:4 row_mask:0xf bank_mask:0xf
	v_fmac_f32_dpp v145, -v17, v121 row_newbcast:5 row_mask:0xf bank_mask:0xf
	v_fmac_f32_dpp v145, -v17, v122 row_newbcast:6 row_mask:0xf bank_mask:0xf
	v_fmac_f32_dpp v145, -v17, v123 row_newbcast:7 row_mask:0xf bank_mask:0xf
	v_fmac_f32_dpp v145, -v17, v124 row_newbcast:8 row_mask:0xf bank_mask:0xf
	v_fmac_f32_dpp v145, -v17, v125 row_newbcast:9 row_mask:0xf bank_mask:0xf
	v_fmac_f32_dpp v145, -v17, v126 row_newbcast:10 row_mask:0xf bank_mask:0xf
	v_fmac_f32_dpp v145, -v17, v127 row_newbcast:11 row_mask:0xf bank_mask:0xf
	v_fmac_f32_dpp v145, -v17, v128 row_newbcast:12 row_mask:0xf bank_mask:0xf
	v_fmac_f32_dpp v145, -v17, v129 row_newbcast:13 row_mask:0xf bank_mask:0xf
	v_fmac_f32_dpp v145, -v17, v130 row_newbcast:14 row_mask:0xf bank_mask:0xf
	v_fmac_f32_dpp v145, -v17, v131 row_newbcast:15 row_mask:0xf bank_mask:0xf
	ds_read_b32 v17, v0 offset:13056
	s_waitcnt lgkmcnt(9)
	v_fmac_f32_dpp v145, -v18, v132 row_newbcast:0 row_mask:0xf bank_mask:0xf
	v_fmac_f32_dpp v145, -v18, v133 row_newbcast:1 row_mask:0xf bank_mask:0xf
	v_fmac_f32_dpp v145, -v18, v134 row_newbcast:2 row_mask:0xf bank_mask:0xf
	v_fmac_f32_dpp v145, -v18, v135 row_newbcast:3 row_mask:0xf bank_mask:0xf
	v_fmac_f32_dpp v145, -v18, v136 row_newbcast:4 row_mask:0xf bank_mask:0xf
	v_fmac_f32_dpp v145, -v18, v137 row_newbcast:5 row_mask:0xf bank_mask:0xf
	v_fmac_f32_dpp v145, -v18, v138 row_newbcast:6 row_mask:0xf bank_mask:0xf
	v_fmac_f32_dpp v145, -v18, v139 row_newbcast:7 row_mask:0xf bank_mask:0xf
	v_fmac_f32_dpp v145, -v18, v140 row_newbcast:8 row_mask:0xf bank_mask:0xf
	v_fmac_f32_dpp v145, -v18, v141 row_newbcast:9 row_mask:0xf bank_mask:0xf
	v_fmac_f32_dpp v145, -v18, v142 row_newbcast:10 row_mask:0xf bank_mask:0xf
	v_fmac_f32_dpp v145, -v18, v143 row_newbcast:11 row_mask:0xf bank_mask:0xf
	v_fmac_f32_dpp v145, -v18, v144 row_newbcast:12 row_mask:0xf bank_mask:0xf
	ds_write_b32 v169, v145 offset:12240
	v_cmp_eq_u32_e32 vcc, 46, v166
	s_nop 1
	v_cndmask_b32_e64 v146, 0, 1.0, vcc
	ds_read_b32 v18, v0 offset:13120
	s_waitcnt lgkmcnt(10)
	v_fmac_f32_dpp v146, -v19, v100 row_newbcast:0 row_mask:0xf bank_mask:0xf
	v_fmac_f32_dpp v146, -v19, v101 row_newbcast:1 row_mask:0xf bank_mask:0xf
	v_fmac_f32_dpp v146, -v19, v102 row_newbcast:2 row_mask:0xf bank_mask:0xf
	v_fmac_f32_dpp v146, -v19, v103 row_newbcast:3 row_mask:0xf bank_mask:0xf
	v_fmac_f32_dpp v146, -v19, v104 row_newbcast:4 row_mask:0xf bank_mask:0xf
	v_fmac_f32_dpp v146, -v19, v105 row_newbcast:5 row_mask:0xf bank_mask:0xf
	v_fmac_f32_dpp v146, -v19, v106 row_newbcast:6 row_mask:0xf bank_mask:0xf
	v_fmac_f32_dpp v146, -v19, v107 row_newbcast:7 row_mask:0xf bank_mask:0xf
	v_fmac_f32_dpp v146, -v19, v108 row_newbcast:8 row_mask:0xf bank_mask:0xf
	v_fmac_f32_dpp v146, -v19, v109 row_newbcast:9 row_mask:0xf bank_mask:0xf
	v_fmac_f32_dpp v146, -v19, v110 row_newbcast:10 row_mask:0xf bank_mask:0xf
	v_fmac_f32_dpp v146, -v19, v111 row_newbcast:11 row_mask:0xf bank_mask:0xf
	v_fmac_f32_dpp v146, -v19, v112 row_newbcast:12 row_mask:0xf bank_mask:0xf
	v_fmac_f32_dpp v146, -v19, v113 row_newbcast:13 row_mask:0xf bank_mask:0xf
	v_fmac_f32_dpp v146, -v19, v114 row_newbcast:14 row_mask:0xf bank_mask:0xf
	v_fmac_f32_dpp v146, -v19, v115 row_newbcast:15 row_mask:0xf bank_mask:0xf
	ds_read_b32 v19, v0 offset:13184
	s_waitcnt lgkmcnt(9)
; DI void d2_chunk(const Params& P, int l, int chunk, LAS float* Nm, LAS float* gs, int lane_in) {
;     ...
;         D2_TBLOCK(0); D2_TBLOCK(1); D2_TBLOCK(2); D2_TBLOCK(3);
	v_fmac_f32_dpp v146, -v12, v116 row_newbcast:0 row_mask:0xf bank_mask:0xf
	v_fmac_f32_dpp v146, -v12, v117 row_newbcast:1 row_mask:0xf bank_mask:0xf
	v_fmac_f32_dpp v146, -v12, v118 row_newbcast:2 row_mask:0xf bank_mask:0xf
	v_fmac_f32_dpp v146, -v12, v119 row_newbcast:3 row_mask:0xf bank_mask:0xf
	v_fmac_f32_dpp v146, -v12, v120 row_newbcast:4 row_mask:0xf bank_mask:0xf
	v_fmac_f32_dpp v146, -v12, v121 row_newbcast:5 row_mask:0xf bank_mask:0xf
	v_fmac_f32_dpp v146, -v12, v122 row_newbcast:6 row_mask:0xf bank_mask:0xf
	v_fmac_f32_dpp v146, -v12, v123 row_newbcast:7 row_mask:0xf bank_mask:0xf
	v_fmac_f32_dpp v146, -v12, v124 row_newbcast:8 row_mask:0xf bank_mask:0xf
	v_fmac_f32_dpp v146, -v12, v125 row_newbcast:9 row_mask:0xf bank_mask:0xf
	v_fmac_f32_dpp v146, -v12, v126 row_newbcast:10 row_mask:0xf bank_mask:0xf
	v_fmac_f32_dpp v146, -v12, v127 row_newbcast:11 row_mask:0xf bank_mask:0xf
	v_fmac_f32_dpp v146, -v12, v128 row_newbcast:12 row_mask:0xf bank_mask:0xf
	v_fmac_f32_dpp v146, -v12, v129 row_newbcast:13 row_mask:0xf bank_mask:0xf
	v_fmac_f32_dpp v146, -v12, v130 row_newbcast:14 row_mask:0xf bank_mask:0xf
	v_fmac_f32_dpp v146, -v12, v131 row_newbcast:15 row_mask:0xf bank_mask:0xf
	ds_read_b32 v12, v0 offset:13328
	s_waitcnt lgkmcnt(9)
	v_fmac_f32_dpp v146, -v13, v132 row_newbcast:0 row_mask:0xf bank_mask:0xf
	v_fmac_f32_dpp v146, -v13, v133 row_newbcast:1 row_mask:0xf bank_mask:0xf
	v_fmac_f32_dpp v146, -v13, v134 row_newbcast:2 row_mask:0xf bank_mask:0xf
	v_fmac_f32_dpp v146, -v13, v135 row_newbcast:3 row_mask:0xf bank_mask:0xf
	v_fmac_f32_dpp v146, -v13, v136 row_newbcast:4 row_mask:0xf bank_mask:0xf
	v_fmac_f32_dpp v146, -v13, v137 row_newbcast:5 row_mask:0xf bank_mask:0xf
	v_fmac_f32_dpp v146, -v13, v138 row_newbcast:6 row_mask:0xf bank_mask:0xf
	v_fmac_f32_dpp v146, -v13, v139 row_newbcast:7 row_mask:0xf bank_mask:0xf
	v_fmac_f32_dpp v146, -v13, v140 row_newbcast:8 row_mask:0xf bank_mask:0xf
	v_fmac_f32_dpp v146, -v13, v141 row_newbcast:9 row_mask:0xf bank_mask:0xf
	v_fmac_f32_dpp v146, -v13, v142 row_newbcast:10 row_mask:0xf bank_mask:0xf
	v_fmac_f32_dpp v146, -v13, v143 row_newbcast:11 row_mask:0xf bank_mask:0xf
	v_fmac_f32_dpp v146, -v13, v144 row_newbcast:12 row_mask:0xf bank_mask:0xf
	v_fmac_f32_dpp v146, -v13, v145 row_newbcast:13 row_mask:0xf bank_mask:0xf
	ds_write_b32 v169, v146 offset:12512
	v_cmp_eq_u32_e32 vcc, 47, v166
	s_nop 1
	v_cndmask_b32_e64 v147, 0, 1.0, vcc
	ds_read_b32 v13, v0 offset:13392
	s_waitcnt lgkmcnt(10)
	v_fmac_f32_dpp v147, -v14, v100 row_newbcast:0 row_mask:0xf bank_mask:0xf
	v_fmac_f32_dpp v147, -v14, v101 row_newbcast:1 row_mask:0xf bank_mask:0xf
	v_fmac_f32_dpp v147, -v14, v102 row_newbcast:2 row_mask:0xf bank_mask:0xf
	v_fmac_f32_dpp v147, -v14, v103 row_newbcast:3 row_mask:0xf bank_mask:0xf
	v_fmac_f32_dpp v147, -v14, v104 row_newbcast:4 row_mask:0xf bank_mask:0xf
	v_fmac_f32_dpp v147, -v14, v105 row_newbcast:5 row_mask:0xf bank_mask:0xf
	v_fmac_f32_dpp v147, -v14, v106 row_newbcast:6 row_mask:0xf bank_mask:0xf
	v_fmac_f32_dpp v147, -v14, v107 row_newbcast:7 row_mask:0xf bank_mask:0xf
	v_fmac_f32_dpp v147, -v14, v108 row_newbcast:8 row_mask:0xf bank_mask:0xf
	v_fmac_f32_dpp v147, -v14, v109 row_newbcast:9 row_mask:0xf bank_mask:0xf
	v_fmac_f32_dpp v147, -v14, v110 row_newbcast:10 row_mask:0xf bank_mask:0xf
	v_fmac_f32_dpp v147, -v14, v111 row_newbcast:11 row_mask:0xf bank_mask:0xf
	v_fmac_f32_dpp v147, -v14, v112 row_newbcast:12 row_mask:0xf bank_mask:0xf
	v_fmac_f32_dpp v147, -v14, v113 row_newbcast:13 row_mask:0xf bank_mask:0xf
	v_fmac_f32_dpp v147, -v14, v114 row_newbcast:14 row_mask:0xf bank_mask:0xf
	v_fmac_f32_dpp v147, -v14, v115 row_newbcast:15 row_mask:0xf bank_mask:0xf
	ds_read_b32 v14, v0 offset:13456
	s_waitcnt lgkmcnt(9)
	v_fmac_f32_dpp v147, -v15, v116 row_newbcast:0 row_mask:0xf bank_mask:0xf
	v_fmac_f32_dpp v147, -v15, v117 row_newbcast:1 row_mask:0xf bank_mask:0xf
	v_fmac_f32_dpp v147, -v15, v118 row_newbcast:2 row_mask:0xf bank_mask:0xf
	v_fmac_f32_dpp v147, -v15, v119 row_newbcast:3 row_mask:0xf bank_mask:0xf
	v_fmac_f32_dpp v147, -v15, v120 row_newbcast:4 row_mask:0xf bank_mask:0xf
	v_fmac_f32_dpp v147, -v15, v121 row_newbcast:5 row_mask:0xf bank_mask:0xf
	v_fmac_f32_dpp v147, -v15, v122 row_newbcast:6 row_mask:0xf bank_mask:0xf
	v_fmac_f32_dpp v147, -v15, v123 row_newbcast:7 row_mask:0xf bank_mask:0xf
	v_fmac_f32_dpp v147, -v15, v124 row_newbcast:8 row_mask:0xf bank_mask:0xf
	v_fmac_f32_dpp v147, -v15, v125 row_newbcast:9 row_mask:0xf bank_mask:0xf
	v_fmac_f32_dpp v147, -v15, v126 row_newbcast:10 row_mask:0xf bank_mask:0xf
	v_fmac_f32_dpp v147, -v15, v127 row_newbcast:11 row_mask:0xf bank_mask:0xf
	v_fmac_f32_dpp v147, -v15, v128 row_newbcast:12 row_mask:0xf bank_mask:0xf
	v_fmac_f32_dpp v147, -v15, v129 row_newbcast:13 row_mask:0xf bank_mask:0xf
	v_fmac_f32_dpp v147, -v15, v130 row_newbcast:14 row_mask:0xf bank_mask:0xf
	v_fmac_f32_dpp v147, -v15, v131 row_newbcast:15 row_mask:0xf bank_mask:0xf
	ds_read_b32 v15, v0 offset:13520
	s_waitcnt lgkmcnt(9)
; DI void d2_chunk(const Params& P, int l, int chunk, LAS float* Nm, LAS float* gs, int lane_in) {
;     ...
;         D2_TBLOCK(0); D2_TBLOCK(1); D2_TBLOCK(2); D2_TBLOCK(3);
	v_fmac_f32_dpp v147, -v16, v132 row_newbcast:0 row_mask:0xf bank_mask:0xf
	v_fmac_f32_dpp v147, -v16, v133 row_newbcast:1 row_mask:0xf bank_mask:0xf
	v_fmac_f32_dpp v147, -v16, v134 row_newbcast:2 row_mask:0xf bank_mask:0xf
	v_fmac_f32_dpp v147, -v16, v135 row_newbcast:3 row_mask:0xf bank_mask:0xf
	v_fmac_f32_dpp v147, -v16, v136 row_newbcast:4 row_mask:0xf bank_mask:0xf
	v_fmac_f32_dpp v147, -v16, v137 row_newbcast:5 row_mask:0xf bank_mask:0xf
	v_fmac_f32_dpp v147, -v16, v138 row_newbcast:6 row_mask:0xf bank_mask:0xf
	v_fmac_f32_dpp v147, -v16, v139 row_newbcast:7 row_mask:0xf bank_mask:0xf
	v_fmac_f32_dpp v147, -v16, v140 row_newbcast:8 row_mask:0xf bank_mask:0xf
	v_fmac_f32_dpp v147, -v16, v141 row_newbcast:9 row_mask:0xf bank_mask:0xf
	v_fmac_f32_dpp v147, -v16, v142 row_newbcast:10 row_mask:0xf bank_mask:0xf
	v_fmac_f32_dpp v147, -v16, v143 row_newbcast:11 row_mask:0xf bank_mask:0xf
	v_fmac_f32_dpp v147, -v16, v144 row_newbcast:12 row_mask:0xf bank_mask:0xf
	v_fmac_f32_dpp v147, -v16, v145 row_newbcast:13 row_mask:0xf bank_mask:0xf
	v_fmac_f32_dpp v147, -v16, v146 row_newbcast:14 row_mask:0xf bank_mask:0xf
	ds_write_b32 v169, v147 offset:12784
	v_cmp_eq_u32_e32 vcc, 48, v166
	s_nop 1
	v_cndmask_b32_e64 v148, 0, 1.0, vcc
	ds_read_b32 v16, v0 offset:13600
	s_waitcnt lgkmcnt(10)
	v_fmac_f32_dpp v148, -v17, v100 row_newbcast:0 row_mask:0xf bank_mask:0xf
	v_fmac_f32_dpp v148, -v17, v101 row_newbcast:1 row_mask:0xf bank_mask:0xf
	v_fmac_f32_dpp v148, -v17, v102 row_newbcast:2 row_mask:0xf bank_mask:0xf
	v_fmac_f32_dpp v148, -v17, v103 row_newbcast:3 row_mask:0xf bank_mask:0xf
	v_fmac_f32_dpp v148, -v17, v104 row_newbcast:4 row_mask:0xf bank_mask:0xf
	v_fmac_f32_dpp v148, -v17, v105 row_newbcast:5 row_mask:0xf bank_mask:0xf
	v_fmac_f32_dpp v148, -v17, v106 row_newbcast:6 row_mask:0xf bank_mask:0xf
	v_fmac_f32_dpp v148, -v17, v107 row_newbcast:7 row_mask:0xf bank_mask:0xf
	v_fmac_f32_dpp v148, -v17, v108 row_newbcast:8 row_mask:0xf bank_mask:0xf
	v_fmac_f32_dpp v148, -v17, v109 row_newbcast:9 row_mask:0xf bank_mask:0xf
	v_fmac_f32_dpp v148, -v17, v110 row_newbcast:10 row_mask:0xf bank_mask:0xf
	v_fmac_f32_dpp v148, -v17, v111 row_newbcast:11 row_mask:0xf bank_mask:0xf
	v_fmac_f32_dpp v148, -v17, v112 row_newbcast:12 row_mask:0xf bank_mask:0xf
	v_fmac_f32_dpp v148, -v17, v113 row_newbcast:13 row_mask:0xf bank_mask:0xf
	v_fmac_f32_dpp v148, -v17, v114 row_newbcast:14 row_mask:0xf bank_mask:0xf
	v_fmac_f32_dpp v148, -v17, v115 row_newbcast:15 row_mask:0xf bank_mask:0xf
	ds_read_b32 v17, v0 offset:13664
	s_waitcnt lgkmcnt(9)
	v_fmac_f32_dpp v148, -v18, v116 row_newbcast:0 row_mask:0xf bank_mask:0xf
	v_fmac_f32_dpp v148, -v18, v117 row_newbcast:1 row_mask:0xf bank_mask:0xf
	v_fmac_f32_dpp v148, -v18, v118 row_newbcast:2 row_mask:0xf bank_mask:0xf
	v_fmac_f32_dpp v148, -v18, v119 row_newbcast:3 row_mask:0xf bank_mask:0xf
	v_fmac_f32_dpp v148, -v18, v120 row_newbcast:4 row_mask:0xf bank_mask:0xf
	v_fmac_f32_dpp v148, -v18, v121 row_newbcast:5 row_mask:0xf bank_mask:0xf
	v_fmac_f32_dpp v148, -v18, v122 row_newbcast:6 row_mask:0xf bank_mask:0xf
	v_fmac_f32_dpp v148, -v18, v123 row_newbcast:7 row_mask:0xf bank_mask:0xf
	v_fmac_f32_dpp v148, -v18, v124 row_newbcast:8 row_mask:0xf bank_mask:0xf
	v_fmac_f32_dpp v148, -v18, v125 row_newbcast:9 row_mask:0xf bank_mask:0xf
	v_fmac_f32_dpp v148, -v18, v126 row_newbcast:10 row_mask:0xf bank_mask:0xf
	v_fmac_f32_dpp v148, -v18, v127 row_newbcast:11 row_mask:0xf bank_mask:0xf
	v_fmac_f32_dpp v148, -v18, v128 row_newbcast:12 row_mask:0xf bank_mask:0xf
	v_fmac_f32_dpp v148, -v18, v129 row_newbcast:13 row_mask:0xf bank_mask:0xf
	v_fmac_f32_dpp v148, -v18, v130 row_newbcast:14 row_mask:0xf bank_mask:0xf
	v_fmac_f32_dpp v148, -v18, v131 row_newbcast:15 row_mask:0xf bank_mask:0xf
	ds_read_b32 v18, v0 offset:13728
	s_waitcnt lgkmcnt(9)
	v_fmac_f32_dpp v148, -v19, v132 row_newbcast:0 row_mask:0xf bank_mask:0xf
	v_fmac_f32_dpp v148, -v19, v133 row_newbcast:1 row_mask:0xf bank_mask:0xf
	v_fmac_f32_dpp v148, -v19, v134 row_newbcast:2 row_mask:0xf bank_mask:0xf
	v_fmac_f32_dpp v148, -v19, v135 row_newbcast:3 row_mask:0xf bank_mask:0xf
	v_fmac_f32_dpp v148, -v19, v136 row_newbcast:4 row_mask:0xf bank_mask:0xf
	v_fmac_f32_dpp v148, -v19, v137 row_newbcast:5 row_mask:0xf bank_mask:0xf
	v_fmac_f32_dpp v148, -v19, v138 row_newbcast:6 row_mask:0xf bank_mask:0xf
	v_fmac_f32_dpp v148, -v19, v139 row_newbcast:7 row_mask:0xf bank_mask:0xf
	v_fmac_f32_dpp v148, -v19, v140 row_newbcast:8 row_mask:0xf bank_mask:0xf
	v_fmac_f32_dpp v148, -v19, v141 row_newbcast:9 row_mask:0xf bank_mask:0xf
	v_fmac_f32_dpp v148, -v19, v142 row_newbcast:10 row_mask:0xf bank_mask:0xf
	v_fmac_f32_dpp v148, -v19, v143 row_newbcast:11 row_mask:0xf bank_mask:0xf
	v_fmac_f32_dpp v148, -v19, v144 row_newbcast:12 row_mask:0xf bank_mask:0xf
	v_fmac_f32_dpp v148, -v19, v145 row_newbcast:13 row_mask:0xf bank_mask:0xf
	v_fmac_f32_dpp v148, -v19, v146 row_newbcast:14 row_mask:0xf bank_mask:0xf
	v_fmac_f32_dpp v148, -v19, v147 row_newbcast:15 row_mask:0xf bank_mask:0xf
	ds_write_b32 v169, v148 offset:13056
	v_cmp_eq_u32_e32 vcc, 49, v166
	s_nop 1
	v_cndmask_b32_e64 v149, 0, 1.0, vcc
	ds_read_b32 v19, v0 offset:13792
	s_waitcnt lgkmcnt(10)
; DI void d2_chunk(const Params& P, int l, int chunk, LAS float* Nm, LAS float* gs, int lane_in) {
;     ...
;         D2_TBLOCK(0); D2_TBLOCK(1); D2_TBLOCK(2); D2_TBLOCK(3);
	v_fmac_f32_dpp v149, -v12, v100 row_newbcast:0 row_mask:0xf bank_mask:0xf
	v_fmac_f32_dpp v149, -v12, v101 row_newbcast:1 row_mask:0xf bank_mask:0xf
	v_fmac_f32_dpp v149, -v12, v102 row_newbcast:2 row_mask:0xf bank_mask:0xf
	v_fmac_f32_dpp v149, -v12, v103 row_newbcast:3 row_mask:0xf bank_mask:0xf
	v_fmac_f32_dpp v149, -v12, v104 row_newbcast:4 row_mask:0xf bank_mask:0xf
	v_fmac_f32_dpp v149, -v12, v105 row_newbcast:5 row_mask:0xf bank_mask:0xf
	v_fmac_f32_dpp v149, -v12, v106 row_newbcast:6 row_mask:0xf bank_mask:0xf
	v_fmac_f32_dpp v149, -v12, v107 row_newbcast:7 row_mask:0xf bank_mask:0xf
	v_fmac_f32_dpp v149, -v12, v108 row_newbcast:8 row_mask:0xf bank_mask:0xf
	v_fmac_f32_dpp v149, -v12, v109 row_newbcast:9 row_mask:0xf bank_mask:0xf
	v_fmac_f32_dpp v149, -v12, v110 row_newbcast:10 row_mask:0xf bank_mask:0xf
	v_fmac_f32_dpp v149, -v12, v111 row_newbcast:11 row_mask:0xf bank_mask:0xf
	v_fmac_f32_dpp v149, -v12, v112 row_newbcast:12 row_mask:0xf bank_mask:0xf
	v_fmac_f32_dpp v149, -v12, v113 row_newbcast:13 row_mask:0xf bank_mask:0xf
	v_fmac_f32_dpp v149, -v12, v114 row_newbcast:14 row_mask:0xf bank_mask:0xf
	v_fmac_f32_dpp v149, -v12, v115 row_newbcast:15 row_mask:0xf bank_mask:0xf
	ds_read_b32 v12, v0 offset:13872
	s_waitcnt lgkmcnt(9)
	v_fmac_f32_dpp v149, -v13, v116 row_newbcast:0 row_mask:0xf bank_mask:0xf
	v_fmac_f32_dpp v149, -v13, v117 row_newbcast:1 row_mask:0xf bank_mask:0xf
	v_fmac_f32_dpp v149, -v13, v118 row_newbcast:2 row_mask:0xf bank_mask:0xf
	v_fmac_f32_dpp v149, -v13, v119 row_newbcast:3 row_mask:0xf bank_mask:0xf
	v_fmac_f32_dpp v149, -v13, v120 row_newbcast:4 row_mask:0xf bank_mask:0xf
	v_fmac_f32_dpp v149, -v13, v121 row_newbcast:5 row_mask:0xf bank_mask:0xf
	v_fmac_f32_dpp v149, -v13, v122 row_newbcast:6 row_mask:0xf bank_mask:0xf
	v_fmac_f32_dpp v149, -v13, v123 row_newbcast:7 row_mask:0xf bank_mask:0xf
	v_fmac_f32_dpp v149, -v13, v124 row_newbcast:8 row_mask:0xf bank_mask:0xf
	v_fmac_f32_dpp v149, -v13, v125 row_newbcast:9 row_mask:0xf bank_mask:0xf
	v_fmac_f32_dpp v149, -v13, v126 row_newbcast:10 row_mask:0xf bank_mask:0xf
	v_fmac_f32_dpp v149, -v13, v127 row_newbcast:11 row_mask:0xf bank_mask:0xf
	v_fmac_f32_dpp v149, -v13, v128 row_newbcast:12 row_mask:0xf bank_mask:0xf
	v_fmac_f32_dpp v149, -v13, v129 row_newbcast:13 row_mask:0xf bank_mask:0xf
	v_fmac_f32_dpp v149, -v13, v130 row_newbcast:14 row_mask:0xf bank_mask:0xf
	v_fmac_f32_dpp v149, -v13, v131 row_newbcast:15 row_mask:0xf bank_mask:0xf
	ds_read_b32 v13, v0 offset:13936
	s_waitcnt lgkmcnt(9)
	v_fmac_f32_dpp v149, -v14, v132 row_newbcast:0 row_mask:0xf bank_mask:0xf
	v_fmac_f32_dpp v149, -v14, v133 row_newbcast:1 row_mask:0xf bank_mask:0xf
	v_fmac_f32_dpp v149, -v14, v134 row_newbcast:2 row_mask:0xf bank_mask:0xf
	v_fmac_f32_dpp v149, -v14, v135 row_newbcast:3 row_mask:0xf bank_mask:0xf
	v_fmac_f32_dpp v149, -v14, v136 row_newbcast:4 row_mask:0xf bank_mask:0xf
	v_fmac_f32_dpp v149, -v14, v137 row_newbcast:5 row_mask:0xf bank_mask:0xf
	v_fmac_f32_dpp v149, -v14, v138 row_newbcast:6 row_mask:0xf bank_mask:0xf
	v_fmac_f32_dpp v149, -v14, v139 row_newbcast:7 row_mask:0xf bank_mask:0xf
	v_fmac_f32_dpp v149, -v14, v140 row_newbcast:8 row_mask:0xf bank_mask:0xf
	v_fmac_f32_dpp v149, -v14, v141 row_newbcast:9 row_mask:0xf bank_mask:0xf
	v_fmac_f32_dpp v149, -v14, v142 row_newbcast:10 row_mask:0xf bank_mask:0xf
	v_fmac_f32_dpp v149, -v14, v143 row_newbcast:11 row_mask:0xf bank_mask:0xf
	v_fmac_f32_dpp v149, -v14, v144 row_newbcast:12 row_mask:0xf bank_mask:0xf
	v_fmac_f32_dpp v149, -v14, v145 row_newbcast:13 row_mask:0xf bank_mask:0xf
	v_fmac_f32_dpp v149, -v14, v146 row_newbcast:14 row_mask:0xf bank_mask:0xf
	v_fmac_f32_dpp v149, -v14, v147 row_newbcast:15 row_mask:0xf bank_mask:0xf
	ds_read_b32 v14, v0 offset:14000
	s_waitcnt lgkmcnt(9)
	v_fmac_f32_dpp v149, -v15, v148 row_newbcast:0 row_mask:0xf bank_mask:0xf
	ds_write_b32 v169, v149 offset:13328
	v_cmp_eq_u32_e32 vcc, 50, v166
	s_nop 1
	v_cndmask_b32_e64 v150, 0, 1.0, vcc
	ds_read_b32 v15, v0 offset:14064
	s_waitcnt lgkmcnt(9)
	v_fmac_f32_dpp v150, -v16, v100 row_newbcast:0 row_mask:0xf bank_mask:0xf
	v_fmac_f32_dpp v150, -v16, v101 row_newbcast:1 row_mask:0xf bank_mask:0xf
	v_fmac_f32_dpp v150, -v16, v102 row_newbcast:2 row_mask:0xf bank_mask:0xf
	v_fmac_f32_dpp v150, -v16, v103 row_newbcast:3 row_mask:0xf bank_mask:0xf
	v_fmac_f32_dpp v150, -v16, v104 row_newbcast:4 row_mask:0xf bank_mask:0xf
	v_fmac_f32_dpp v150, -v16, v105 row_newbcast:5 row_mask:0xf bank_mask:0xf
	v_fmac_f32_dpp v150, -v16, v106 row_newbcast:6 row_mask:0xf bank_mask:0xf
	v_fmac_f32_dpp v150, -v16, v107 row_newbcast:7 row_mask:0xf bank_mask:0xf
	v_fmac_f32_dpp v150, -v16, v108 row_newbcast:8 row_mask:0xf bank_mask:0xf
	v_fmac_f32_dpp v150, -v16, v109 row_newbcast:9 row_mask:0xf bank_mask:0xf
	v_fmac_f32_dpp v150, -v16, v110 row_newbcast:10 row_mask:0xf bank_mask:0xf
	v_fmac_f32_dpp v150, -v16, v111 row_newbcast:11 row_mask:0xf bank_mask:0xf
	v_fmac_f32_dpp v150, -v16, v112 row_newbcast:12 row_mask:0xf bank_mask:0xf
	v_fmac_f32_dpp v150, -v16, v113 row_newbcast:13 row_mask:0xf bank_mask:0xf
	v_fmac_f32_dpp v150, -v16, v114 row_newbcast:14 row_mask:0xf bank_mask:0xf
	v_fmac_f32_dpp v150, -v16, v115 row_newbcast:15 row_mask:0xf bank_mask:0xf
	ds_read_b32 v16, v0 offset:14144
	s_waitcnt lgkmcnt(9)
; DI void d2_chunk(const Params& P, int l, int chunk, LAS float* Nm, LAS float* gs, int lane_in) {
;     ...
;         D2_TBLOCK(0); D2_TBLOCK(1); D2_TBLOCK(2); D2_TBLOCK(3);
	v_fmac_f32_dpp v150, -v17, v116 row_newbcast:0 row_mask:0xf bank_mask:0xf
	v_fmac_f32_dpp v150, -v17, v117 row_newbcast:1 row_mask:0xf bank_mask:0xf
	v_fmac_f32_dpp v150, -v17, v118 row_newbcast:2 row_mask:0xf bank_mask:0xf
	v_fmac_f32_dpp v150, -v17, v119 row_newbcast:3 row_mask:0xf bank_mask:0xf
	v_fmac_f32_dpp v150, -v17, v120 row_newbcast:4 row_mask:0xf bank_mask:0xf
	v_fmac_f32_dpp v150, -v17, v121 row_newbcast:5 row_mask:0xf bank_mask:0xf
	v_fmac_f32_dpp v150, -v17, v122 row_newbcast:6 row_mask:0xf bank_mask:0xf
	v_fmac_f32_dpp v150, -v17, v123 row_newbcast:7 row_mask:0xf bank_mask:0xf
	v_fmac_f32_dpp v150, -v17, v124 row_newbcast:8 row_mask:0xf bank_mask:0xf
	v_fmac_f32_dpp v150, -v17, v125 row_newbcast:9 row_mask:0xf bank_mask:0xf
	v_fmac_f32_dpp v150, -v17, v126 row_newbcast:10 row_mask:0xf bank_mask:0xf
	v_fmac_f32_dpp v150, -v17, v127 row_newbcast:11 row_mask:0xf bank_mask:0xf
	v_fmac_f32_dpp v150, -v17, v128 row_newbcast:12 row_mask:0xf bank_mask:0xf
	v_fmac_f32_dpp v150, -v17, v129 row_newbcast:13 row_mask:0xf bank_mask:0xf
	v_fmac_f32_dpp v150, -v17, v130 row_newbcast:14 row_mask:0xf bank_mask:0xf
	v_fmac_f32_dpp v150, -v17, v131 row_newbcast:15 row_mask:0xf bank_mask:0xf
	ds_read_b32 v17, v0 offset:14208
	s_waitcnt lgkmcnt(9)
	v_fmac_f32_dpp v150, -v18, v132 row_newbcast:0 row_mask:0xf bank_mask:0xf
	v_fmac_f32_dpp v150, -v18, v133 row_newbcast:1 row_mask:0xf bank_mask:0xf
	v_fmac_f32_dpp v150, -v18, v134 row_newbcast:2 row_mask:0xf bank_mask:0xf
	v_fmac_f32_dpp v150, -v18, v135 row_newbcast:3 row_mask:0xf bank_mask:0xf
	v_fmac_f32_dpp v150, -v18, v136 row_newbcast:4 row_mask:0xf bank_mask:0xf
	v_fmac_f32_dpp v150, -v18, v137 row_newbcast:5 row_mask:0xf bank_mask:0xf
	v_fmac_f32_dpp v150, -v18, v138 row_newbcast:6 row_mask:0xf bank_mask:0xf
	v_fmac_f32_dpp v150, -v18, v139 row_newbcast:7 row_mask:0xf bank_mask:0xf
	v_fmac_f32_dpp v150, -v18, v140 row_newbcast:8 row_mask:0xf bank_mask:0xf
	v_fmac_f32_dpp v150, -v18, v141 row_newbcast:9 row_mask:0xf bank_mask:0xf
	v_fmac_f32_dpp v150, -v18, v142 row_newbcast:10 row_mask:0xf bank_mask:0xf
	v_fmac_f32_dpp v150, -v18, v143 row_newbcast:11 row_mask:0xf bank_mask:0xf
	v_fmac_f32_dpp v150, -v18, v144 row_newbcast:12 row_mask:0xf bank_mask:0xf
	v_fmac_f32_dpp v150, -v18, v145 row_newbcast:13 row_mask:0xf bank_mask:0xf
	v_fmac_f32_dpp v150, -v18, v146 row_newbcast:14 row_mask:0xf bank_mask:0xf
	v_fmac_f32_dpp v150, -v18, v147 row_newbcast:15 row_mask:0xf bank_mask:0xf
	ds_read_b32 v18, v0 offset:14272
	s_waitcnt lgkmcnt(8)
	v_fmac_f32_dpp v150, -v19, v148 row_newbcast:0 row_mask:0xf bank_mask:0xf
	v_fmac_f32_dpp v150, -v19, v149 row_newbcast:1 row_mask:0xf bank_mask:0xf
	ds_write_b32 v169, v150 offset:13600
	v_cmp_eq_u32_e32 vcc, 51, v166
	s_nop 1
	v_cndmask_b32_e64 v151, 0, 1.0, vcc
	ds_read_b32 v19, v0 offset:14336
	s_waitcnt lgkmcnt(9)
	v_fmac_f32_dpp v151, -v12, v100 row_newbcast:0 row_mask:0xf bank_mask:0xf
	v_fmac_f32_dpp v151, -v12, v101 row_newbcast:1 row_mask:0xf bank_mask:0xf
	v_fmac_f32_dpp v151, -v12, v102 row_newbcast:2 row_mask:0xf bank_mask:0xf
	v_fmac_f32_dpp v151, -v12, v103 row_newbcast:3 row_mask:0xf bank_mask:0xf
	v_fmac_f32_dpp v151, -v12, v104 row_newbcast:4 row_mask:0xf bank_mask:0xf
	v_fmac_f32_dpp v151, -v12, v105 row_newbcast:5 row_mask:0xf bank_mask:0xf
	v_fmac_f32_dpp v151, -v12, v106 row_newbcast:6 row_mask:0xf bank_mask:0xf
	v_fmac_f32_dpp v151, -v12, v107 row_newbcast:7 row_mask:0xf bank_mask:0xf
	v_fmac_f32_dpp v151, -v12, v108 row_newbcast:8 row_mask:0xf bank_mask:0xf
	v_fmac_f32_dpp v151, -v12, v109 row_newbcast:9 row_mask:0xf bank_mask:0xf
	v_fmac_f32_dpp v151, -v12, v110 row_newbcast:10 row_mask:0xf bank_mask:0xf
	v_fmac_f32_dpp v151, -v12, v111 row_newbcast:11 row_mask:0xf bank_mask:0xf
	v_fmac_f32_dpp v151, -v12, v112 row_newbcast:12 row_mask:0xf bank_mask:0xf
	v_fmac_f32_dpp v151, -v12, v113 row_newbcast:13 row_mask:0xf bank_mask:0xf
	v_fmac_f32_dpp v151, -v12, v114 row_newbcast:14 row_mask:0xf bank_mask:0xf
	v_fmac_f32_dpp v151, -v12, v115 row_newbcast:15 row_mask:0xf bank_mask:0xf
	ds_read_b32 v12, v0 offset:14416
	s_waitcnt lgkmcnt(9)
	v_fmac_f32_dpp v151, -v13, v116 row_newbcast:0 row_mask:0xf bank_mask:0xf
	v_fmac_f32_dpp v151, -v13, v117 row_newbcast:1 row_mask:0xf bank_mask:0xf
	v_fmac_f32_dpp v151, -v13, v118 row_newbcast:2 row_mask:0xf bank_mask:0xf
	v_fmac_f32_dpp v151, -v13, v119 row_newbcast:3 row_mask:0xf bank_mask:0xf
	v_fmac_f32_dpp v151, -v13, v120 row_newbcast:4 row_mask:0xf bank_mask:0xf
	v_fmac_f32_dpp v151, -v13, v121 row_newbcast:5 row_mask:0xf bank_mask:0xf
	v_fmac_f32_dpp v151, -v13, v122 row_newbcast:6 row_mask:0xf bank_mask:0xf
	v_fmac_f32_dpp v151, -v13, v123 row_newbcast:7 row_mask:0xf bank_mask:0xf
	v_fmac_f32_dpp v151, -v13, v124 row_newbcast:8 row_mask:0xf bank_mask:0xf
	v_fmac_f32_dpp v151, -v13, v125 row_newbcast:9 row_mask:0xf bank_mask:0xf
	v_fmac_f32_dpp v151, -v13, v126 row_newbcast:10 row_mask:0xf bank_mask:0xf
	v_fmac_f32_dpp v151, -v13, v127 row_newbcast:11 row_mask:0xf bank_mask:0xf
	v_fmac_f32_dpp v151, -v13, v128 row_newbcast:12 row_mask:0xf bank_mask:0xf
	v_fmac_f32_dpp v151, -v13, v129 row_newbcast:13 row_mask:0xf bank_mask:0xf
	v_fmac_f32_dpp v151, -v13, v130 row_newbcast:14 row_mask:0xf bank_mask:0xf
	v_fmac_f32_dpp v151, -v13, v131 row_newbcast:15 row_mask:0xf bank_mask:0xf
	ds_read_b32 v13, v0 offset:14480
	s_waitcnt lgkmcnt(9)
; DI void d2_chunk(const Params& P, int l, int chunk, LAS float* Nm, LAS float* gs, int lane_in) {
;     ...
;         D2_TBLOCK(0); D2_TBLOCK(1); D2_TBLOCK(2); D2_TBLOCK(3);
	v_fmac_f32_dpp v151, -v14, v132 row_newbcast:0 row_mask:0xf bank_mask:0xf
	v_fmac_f32_dpp v151, -v14, v133 row_newbcast:1 row_mask:0xf bank_mask:0xf
	v_fmac_f32_dpp v151, -v14, v134 row_newbcast:2 row_mask:0xf bank_mask:0xf
	v_fmac_f32_dpp v151, -v14, v135 row_newbcast:3 row_mask:0xf bank_mask:0xf
	v_fmac_f32_dpp v151, -v14, v136 row_newbcast:4 row_mask:0xf bank_mask:0xf
	v_fmac_f32_dpp v151, -v14, v137 row_newbcast:5 row_mask:0xf bank_mask:0xf
	v_fmac_f32_dpp v151, -v14, v138 row_newbcast:6 row_mask:0xf bank_mask:0xf
	v_fmac_f32_dpp v151, -v14, v139 row_newbcast:7 row_mask:0xf bank_mask:0xf
	v_fmac_f32_dpp v151, -v14, v140 row_newbcast:8 row_mask:0xf bank_mask:0xf
	v_fmac_f32_dpp v151, -v14, v141 row_newbcast:9 row_mask:0xf bank_mask:0xf
	v_fmac_f32_dpp v151, -v14, v142 row_newbcast:10 row_mask:0xf bank_mask:0xf
	v_fmac_f32_dpp v151, -v14, v143 row_newbcast:11 row_mask:0xf bank_mask:0xf
	v_fmac_f32_dpp v151, -v14, v144 row_newbcast:12 row_mask:0xf bank_mask:0xf
	v_fmac_f32_dpp v151, -v14, v145 row_newbcast:13 row_mask:0xf bank_mask:0xf
	v_fmac_f32_dpp v151, -v14, v146 row_newbcast:14 row_mask:0xf bank_mask:0xf
	v_fmac_f32_dpp v151, -v14, v147 row_newbcast:15 row_mask:0xf bank_mask:0xf
	ds_read_b32 v14, v0 offset:14544
	s_waitcnt lgkmcnt(8)
	v_fmac_f32_dpp v151, -v15, v148 row_newbcast:0 row_mask:0xf bank_mask:0xf
	v_fmac_f32_dpp v151, -v15, v149 row_newbcast:1 row_mask:0xf bank_mask:0xf
	v_fmac_f32_dpp v151, -v15, v150 row_newbcast:2 row_mask:0xf bank_mask:0xf
	ds_write_b32 v169, v151 offset:13872
	v_cmp_eq_u32_e32 vcc, 52, v166
	s_nop 1
	v_cndmask_b32_e64 v152, 0, 1.0, vcc
	ds_read_b32 v15, v0 offset:14608
	s_waitcnt lgkmcnt(9)
	v_fmac_f32_dpp v152, -v16, v100 row_newbcast:0 row_mask:0xf bank_mask:0xf
	v_fmac_f32_dpp v152, -v16, v101 row_newbcast:1 row_mask:0xf bank_mask:0xf
	v_fmac_f32_dpp v152, -v16, v102 row_newbcast:2 row_mask:0xf bank_mask:0xf
	v_fmac_f32_dpp v152, -v16, v103 row_newbcast:3 row_mask:0xf bank_mask:0xf
	v_fmac_f32_dpp v152, -v16, v104 row_newbcast:4 row_mask:0xf bank_mask:0xf
	v_fmac_f32_dpp v152, -v16, v105 row_newbcast:5 row_mask:0xf bank_mask:0xf
	v_fmac_f32_dpp v152, -v16, v106 row_newbcast:6 row_mask:0xf bank_mask:0xf
	v_fmac_f32_dpp v152, -v16, v107 row_newbcast:7 row_mask:0xf bank_mask:0xf
	v_fmac_f32_dpp v152, -v16, v108 row_newbcast:8 row_mask:0xf bank_mask:0xf
	v_fmac_f32_dpp v152, -v16, v109 row_newbcast:9 row_mask:0xf bank_mask:0xf
	v_fmac_f32_dpp v152, -v16, v110 row_newbcast:10 row_mask:0xf bank_mask:0xf
	v_fmac_f32_dpp v152, -v16, v111 row_newbcast:11 row_mask:0xf bank_mask:0xf
	v_fmac_f32_dpp v152, -v16, v112 row_newbcast:12 row_mask:0xf bank_mask:0xf
	v_fmac_f32_dpp v152, -v16, v113 row_newbcast:13 row_mask:0xf bank_mask:0xf
	v_fmac_f32_dpp v152, -v16, v114 row_newbcast:14 row_mask:0xf bank_mask:0xf
	v_fmac_f32_dpp v152, -v16, v115 row_newbcast:15 row_mask:0xf bank_mask:0xf
	ds_read_b32 v16, v0 offset:14688
	s_waitcnt lgkmcnt(9)
	v_fmac_f32_dpp v152, -v17, v116 row_newbcast:0 row_mask:0xf bank_mask:0xf
	v_fmac_f32_dpp v152, -v17, v117 row_newbcast:1 row_mask:0xf bank_mask:0xf
	v_fmac_f32_dpp v152, -v17, v118 row_newbcast:2 row_mask:0xf bank_mask:0xf
	v_fmac_f32_dpp v152, -v17, v119 row_newbcast:3 row_mask:0xf bank_mask:0xf
	v_fmac_f32_dpp v152, -v17, v120 row_newbcast:4 row_mask:0xf bank_mask:0xf
	v_fmac_f32_dpp v152, -v17, v121 row_newbcast:5 row_mask:0xf bank_mask:0xf
	v_fmac_f32_dpp v152, -v17, v122 row_newbcast:6 row_mask:0xf bank_mask:0xf
	v_fmac_f32_dpp v152, -v17, v123 row_newbcast:7 row_mask:0xf bank_mask:0xf
	v_fmac_f32_dpp v152, -v17, v124 row_newbcast:8 row_mask:0xf bank_mask:0xf
	v_fmac_f32_dpp v152, -v17, v125 row_newbcast:9 row_mask:0xf bank_mask:0xf
	v_fmac_f32_dpp v152, -v17, v126 row_newbcast:10 row_mask:0xf bank_mask:0xf
	v_fmac_f32_dpp v152, -v17, v127 row_newbcast:11 row_mask:0xf bank_mask:0xf
	v_fmac_f32_dpp v152, -v17, v128 row_newbcast:12 row_mask:0xf bank_mask:0xf
	v_fmac_f32_dpp v152, -v17, v129 row_newbcast:13 row_mask:0xf bank_mask:0xf
	v_fmac_f32_dpp v152, -v17, v130 row_newbcast:14 row_mask:0xf bank_mask:0xf
	v_fmac_f32_dpp v152, -v17, v131 row_newbcast:15 row_mask:0xf bank_mask:0xf
	ds_read_b32 v17, v0 offset:14752
	s_waitcnt lgkmcnt(9)
	v_fmac_f32_dpp v152, -v18, v132 row_newbcast:0 row_mask:0xf bank_mask:0xf
	v_fmac_f32_dpp v152, -v18, v133 row_newbcast:1 row_mask:0xf bank_mask:0xf
	v_fmac_f32_dpp v152, -v18, v134 row_newbcast:2 row_mask:0xf bank_mask:0xf
	v_fmac_f32_dpp v152, -v18, v135 row_newbcast:3 row_mask:0xf bank_mask:0xf
	v_fmac_f32_dpp v152, -v18, v136 row_newbcast:4 row_mask:0xf bank_mask:0xf
	v_fmac_f32_dpp v152, -v18, v137 row_newbcast:5 row_mask:0xf bank_mask:0xf
	v_fmac_f32_dpp v152, -v18, v138 row_newbcast:6 row_mask:0xf bank_mask:0xf
	v_fmac_f32_dpp v152, -v18, v139 row_newbcast:7 row_mask:0xf bank_mask:0xf
	v_fmac_f32_dpp v152, -v18, v140 row_newbcast:8 row_mask:0xf bank_mask:0xf
	v_fmac_f32_dpp v152, -v18, v141 row_newbcast:9 row_mask:0xf bank_mask:0xf
	v_fmac_f32_dpp v152, -v18, v142 row_newbcast:10 row_mask:0xf bank_mask:0xf
	v_fmac_f32_dpp v152, -v18, v143 row_newbcast:11 row_mask:0xf bank_mask:0xf
	v_fmac_f32_dpp v152, -v18, v144 row_newbcast:12 row_mask:0xf bank_mask:0xf
	v_fmac_f32_dpp v152, -v18, v145 row_newbcast:13 row_mask:0xf bank_mask:0xf
	v_fmac_f32_dpp v152, -v18, v146 row_newbcast:14 row_mask:0xf bank_mask:0xf
	v_fmac_f32_dpp v152, -v18, v147 row_newbcast:15 row_mask:0xf bank_mask:0xf
	ds_read_b32 v18, v0 offset:14816
	s_waitcnt lgkmcnt(8)
; DI void d2_chunk(const Params& P, int l, int chunk, LAS float* Nm, LAS float* gs, int lane_in) {
;     ...
;         D2_TBLOCK(0); D2_TBLOCK(1); D2_TBLOCK(2); D2_TBLOCK(3);
	v_fmac_f32_dpp v152, -v19, v148 row_newbcast:0 row_mask:0xf bank_mask:0xf
	v_fmac_f32_dpp v152, -v19, v149 row_newbcast:1 row_mask:0xf bank_mask:0xf
	v_fmac_f32_dpp v152, -v19, v150 row_newbcast:2 row_mask:0xf bank_mask:0xf
	v_fmac_f32_dpp v152, -v19, v151 row_newbcast:3 row_mask:0xf bank_mask:0xf
	ds_write_b32 v169, v152 offset:14144
	v_cmp_eq_u32_e32 vcc, 53, v166
	s_nop 1
	v_cndmask_b32_e64 v153, 0, 1.0, vcc
	ds_read_b32 v19, v0 offset:14880
	s_waitcnt lgkmcnt(9)
	v_fmac_f32_dpp v153, -v12, v100 row_newbcast:0 row_mask:0xf bank_mask:0xf
	v_fmac_f32_dpp v153, -v12, v101 row_newbcast:1 row_mask:0xf bank_mask:0xf
	v_fmac_f32_dpp v153, -v12, v102 row_newbcast:2 row_mask:0xf bank_mask:0xf
	v_fmac_f32_dpp v153, -v12, v103 row_newbcast:3 row_mask:0xf bank_mask:0xf
	v_fmac_f32_dpp v153, -v12, v104 row_newbcast:4 row_mask:0xf bank_mask:0xf
	v_fmac_f32_dpp v153, -v12, v105 row_newbcast:5 row_mask:0xf bank_mask:0xf
	v_fmac_f32_dpp v153, -v12, v106 row_newbcast:6 row_mask:0xf bank_mask:0xf
	v_fmac_f32_dpp v153, -v12, v107 row_newbcast:7 row_mask:0xf bank_mask:0xf
	v_fmac_f32_dpp v153, -v12, v108 row_newbcast:8 row_mask:0xf bank_mask:0xf
	v_fmac_f32_dpp v153, -v12, v109 row_newbcast:9 row_mask:0xf bank_mask:0xf
	v_fmac_f32_dpp v153, -v12, v110 row_newbcast:10 row_mask:0xf bank_mask:0xf
	v_fmac_f32_dpp v153, -v12, v111 row_newbcast:11 row_mask:0xf bank_mask:0xf
	v_fmac_f32_dpp v153, -v12, v112 row_newbcast:12 row_mask:0xf bank_mask:0xf
	v_fmac_f32_dpp v153, -v12, v113 row_newbcast:13 row_mask:0xf bank_mask:0xf
	v_fmac_f32_dpp v153, -v12, v114 row_newbcast:14 row_mask:0xf bank_mask:0xf
	v_fmac_f32_dpp v153, -v12, v115 row_newbcast:15 row_mask:0xf bank_mask:0xf
	ds_read_b32 v12, v0 offset:14960
	s_waitcnt lgkmcnt(9)
	v_fmac_f32_dpp v153, -v13, v116 row_newbcast:0 row_mask:0xf bank_mask:0xf
	v_fmac_f32_dpp v153, -v13, v117 row_newbcast:1 row_mask:0xf bank_mask:0xf
	v_fmac_f32_dpp v153, -v13, v118 row_newbcast:2 row_mask:0xf bank_mask:0xf
	v_fmac_f32_dpp v153, -v13, v119 row_newbcast:3 row_mask:0xf bank_mask:0xf
	v_fmac_f32_dpp v153, -v13, v120 row_newbcast:4 row_mask:0xf bank_mask:0xf
	v_fmac_f32_dpp v153, -v13, v121 row_newbcast:5 row_mask:0xf bank_mask:0xf
	v_fmac_f32_dpp v153, -v13, v122 row_newbcast:6 row_mask:0xf bank_mask:0xf
	v_fmac_f32_dpp v153, -v13, v123 row_newbcast:7 row_mask:0xf bank_mask:0xf
	v_fmac_f32_dpp v153, -v13, v124 row_newbcast:8 row_mask:0xf bank_mask:0xf
	v_fmac_f32_dpp v153, -v13, v125 row_newbcast:9 row_mask:0xf bank_mask:0xf
	v_fmac_f32_dpp v153, -v13, v126 row_newbcast:10 row_mask:0xf bank_mask:0xf
	v_fmac_f32_dpp v153, -v13, v127 row_newbcast:11 row_mask:0xf bank_mask:0xf
	v_fmac_f32_dpp v153, -v13, v128 row_newbcast:12 row_mask:0xf bank_mask:0xf
	v_fmac_f32_dpp v153, -v13, v129 row_newbcast:13 row_mask:0xf bank_mask:0xf
	v_fmac_f32_dpp v153, -v13, v130 row_newbcast:14 row_mask:0xf bank_mask:0xf
	v_fmac_f32_dpp v153, -v13, v131 row_newbcast:15 row_mask:0xf bank_mask:0xf
	ds_read_b32 v13, v0 offset:15024
	s_waitcnt lgkmcnt(9)
	v_fmac_f32_dpp v153, -v14, v132 row_newbcast:0 row_mask:0xf bank_mask:0xf
	v_fmac_f32_dpp v153, -v14, v133 row_newbcast:1 row_mask:0xf bank_mask:0xf
	v_fmac_f32_dpp v153, -v14, v134 row_newbcast:2 row_mask:0xf bank_mask:0xf
	v_fmac_f32_dpp v153, -v14, v135 row_newbcast:3 row_mask:0xf bank_mask:0xf
	v_fmac_f32_dpp v153, -v14, v136 row_newbcast:4 row_mask:0xf bank_mask:0xf
	v_fmac_f32_dpp v153, -v14, v137 row_newbcast:5 row_mask:0xf bank_mask:0xf
	v_fmac_f32_dpp v153, -v14, v138 row_newbcast:6 row_mask:0xf bank_mask:0xf
	v_fmac_f32_dpp v153, -v14, v139 row_newbcast:7 row_mask:0xf bank_mask:0xf
	v_fmac_f32_dpp v153, -v14, v140 row_newbcast:8 row_mask:0xf bank_mask:0xf
	v_fmac_f32_dpp v153, -v14, v141 row_newbcast:9 row_mask:0xf bank_mask:0xf
	v_fmac_f32_dpp v153, -v14, v142 row_newbcast:10 row_mask:0xf bank_mask:0xf
	v_fmac_f32_dpp v153, -v14, v143 row_newbcast:11 row_mask:0xf bank_mask:0xf
	v_fmac_f32_dpp v153, -v14, v144 row_newbcast:12 row_mask:0xf bank_mask:0xf
	v_fmac_f32_dpp v153, -v14, v145 row_newbcast:13 row_mask:0xf bank_mask:0xf
	v_fmac_f32_dpp v153, -v14, v146 row_newbcast:14 row_mask:0xf bank_mask:0xf
	v_fmac_f32_dpp v153, -v14, v147 row_newbcast:15 row_mask:0xf bank_mask:0xf
	ds_read_b32 v14, v0 offset:15088
	s_waitcnt lgkmcnt(8)
	v_fmac_f32_dpp v153, -v15, v148 row_newbcast:0 row_mask:0xf bank_mask:0xf
	v_fmac_f32_dpp v153, -v15, v149 row_newbcast:1 row_mask:0xf bank_mask:0xf
	v_fmac_f32_dpp v153, -v15, v150 row_newbcast:2 row_mask:0xf bank_mask:0xf
	v_fmac_f32_dpp v153, -v15, v151 row_newbcast:3 row_mask:0xf bank_mask:0xf
	v_fmac_f32_dpp v153, -v15, v152 row_newbcast:4 row_mask:0xf bank_mask:0xf
	ds_write_b32 v169, v153 offset:14416
	v_cmp_eq_u32_e32 vcc, 54, v166
	s_nop 1
	v_cndmask_b32_e64 v154, 0, 1.0, vcc
	ds_read_b32 v15, v0 offset:15152
	s_waitcnt lgkmcnt(9)
	v_fmac_f32_dpp v154, -v16, v100 row_newbcast:0 row_mask:0xf bank_mask:0xf
	v_fmac_f32_dpp v154, -v16, v101 row_newbcast:1 row_mask:0xf bank_mask:0xf
	v_fmac_f32_dpp v154, -v16, v102 row_newbcast:2 row_mask:0xf bank_mask:0xf
	v_fmac_f32_dpp v154, -v16, v103 row_newbcast:3 row_mask:0xf bank_mask:0xf
	v_fmac_f32_dpp v154, -v16, v104 row_newbcast:4 row_mask:0xf bank_mask:0xf
	v_fmac_f32_dpp v154, -v16, v105 row_newbcast:5 row_mask:0xf bank_mask:0xf
	v_fmac_f32_dpp v154, -v16, v106 row_newbcast:6 row_mask:0xf bank_mask:0xf
	v_fmac_f32_dpp v154, -v16, v107 row_newbcast:7 row_mask:0xf bank_mask:0xf
	v_fmac_f32_dpp v154, -v16, v108 row_newbcast:8 row_mask:0xf bank_mask:0xf
	v_fmac_f32_dpp v154, -v16, v109 row_newbcast:9 row_mask:0xf bank_mask:0xf
	v_fmac_f32_dpp v154, -v16, v110 row_newbcast:10 row_mask:0xf bank_mask:0xf
	v_fmac_f32_dpp v154, -v16, v111 row_newbcast:11 row_mask:0xf bank_mask:0xf
	v_fmac_f32_dpp v154, -v16, v112 row_newbcast:12 row_mask:0xf bank_mask:0xf
	v_fmac_f32_dpp v154, -v16, v113 row_newbcast:13 row_mask:0xf bank_mask:0xf
	v_fmac_f32_dpp v154, -v16, v114 row_newbcast:14 row_mask:0xf bank_mask:0xf
	v_fmac_f32_dpp v154, -v16, v115 row_newbcast:15 row_mask:0xf bank_mask:0xf
	ds_read_b32 v16, v0 offset:15232
	s_waitcnt lgkmcnt(9)
; DI void d2_chunk(const Params& P, int l, int chunk, LAS float* Nm, LAS float* gs, int lane_in) {
;     ...
;         D2_TBLOCK(0); D2_TBLOCK(1); D2_TBLOCK(2); D2_TBLOCK(3);
	v_fmac_f32_dpp v154, -v17, v116 row_newbcast:0 row_mask:0xf bank_mask:0xf
	v_fmac_f32_dpp v154, -v17, v117 row_newbcast:1 row_mask:0xf bank_mask:0xf
	v_fmac_f32_dpp v154, -v17, v118 row_newbcast:2 row_mask:0xf bank_mask:0xf
	v_fmac_f32_dpp v154, -v17, v119 row_newbcast:3 row_mask:0xf bank_mask:0xf
	v_fmac_f32_dpp v154, -v17, v120 row_newbcast:4 row_mask:0xf bank_mask:0xf
	v_fmac_f32_dpp v154, -v17, v121 row_newbcast:5 row_mask:0xf bank_mask:0xf
	v_fmac_f32_dpp v154, -v17, v122 row_newbcast:6 row_mask:0xf bank_mask:0xf
	v_fmac_f32_dpp v154, -v17, v123 row_newbcast:7 row_mask:0xf bank_mask:0xf
	v_fmac_f32_dpp v154, -v17, v124 row_newbcast:8 row_mask:0xf bank_mask:0xf
	v_fmac_f32_dpp v154, -v17, v125 row_newbcast:9 row_mask:0xf bank_mask:0xf
	v_fmac_f32_dpp v154, -v17, v126 row_newbcast:10 row_mask:0xf bank_mask:0xf
	v_fmac_f32_dpp v154, -v17, v127 row_newbcast:11 row_mask:0xf bank_mask:0xf
	v_fmac_f32_dpp v154, -v17, v128 row_newbcast:12 row_mask:0xf bank_mask:0xf
	v_fmac_f32_dpp v154, -v17, v129 row_newbcast:13 row_mask:0xf bank_mask:0xf
	v_fmac_f32_dpp v154, -v17, v130 row_newbcast:14 row_mask:0xf bank_mask:0xf
	v_fmac_f32_dpp v154, -v17, v131 row_newbcast:15 row_mask:0xf bank_mask:0xf
	ds_read_b32 v17, v0 offset:15296
	s_waitcnt lgkmcnt(9)
	v_fmac_f32_dpp v154, -v18, v132 row_newbcast:0 row_mask:0xf bank_mask:0xf
	v_fmac_f32_dpp v154, -v18, v133 row_newbcast:1 row_mask:0xf bank_mask:0xf
	v_fmac_f32_dpp v154, -v18, v134 row_newbcast:2 row_mask:0xf bank_mask:0xf
	v_fmac_f32_dpp v154, -v18, v135 row_newbcast:3 row_mask:0xf bank_mask:0xf
	v_fmac_f32_dpp v154, -v18, v136 row_newbcast:4 row_mask:0xf bank_mask:0xf
	v_fmac_f32_dpp v154, -v18, v137 row_newbcast:5 row_mask:0xf bank_mask:0xf
	v_fmac_f32_dpp v154, -v18, v138 row_newbcast:6 row_mask:0xf bank_mask:0xf
	v_fmac_f32_dpp v154, -v18, v139 row_newbcast:7 row_mask:0xf bank_mask:0xf
	v_fmac_f32_dpp v154, -v18, v140 row_newbcast:8 row_mask:0xf bank_mask:0xf
	v_fmac_f32_dpp v154, -v18, v141 row_newbcast:9 row_mask:0xf bank_mask:0xf
	v_fmac_f32_dpp v154, -v18, v142 row_newbcast:10 row_mask:0xf bank_mask:0xf
	v_fmac_f32_dpp v154, -v18, v143 row_newbcast:11 row_mask:0xf bank_mask:0xf
	v_fmac_f32_dpp v154, -v18, v144 row_newbcast:12 row_mask:0xf bank_mask:0xf
	v_fmac_f32_dpp v154, -v18, v145 row_newbcast:13 row_mask:0xf bank_mask:0xf
	v_fmac_f32_dpp v154, -v18, v146 row_newbcast:14 row_mask:0xf bank_mask:0xf
	v_fmac_f32_dpp v154, -v18, v147 row_newbcast:15 row_mask:0xf bank_mask:0xf
	ds_read_b32 v18, v0 offset:15360
	s_waitcnt lgkmcnt(8)
	v_fmac_f32_dpp v154, -v19, v148 row_newbcast:0 row_mask:0xf bank_mask:0xf
	v_fmac_f32_dpp v154, -v19, v149 row_newbcast:1 row_mask:0xf bank_mask:0xf
	v_fmac_f32_dpp v154, -v19, v150 row_newbcast:2 row_mask:0xf bank_mask:0xf
	v_fmac_f32_dpp v154, -v19, v151 row_newbcast:3 row_mask:0xf bank_mask:0xf
	v_fmac_f32_dpp v154, -v19, v152 row_newbcast:4 row_mask:0xf bank_mask:0xf
	v_fmac_f32_dpp v154, -v19, v153 row_newbcast:5 row_mask:0xf bank_mask:0xf
	ds_write_b32 v169, v154 offset:14688
	v_cmp_eq_u32_e32 vcc, 55, v166
	s_nop 1
	v_cndmask_b32_e64 v155, 0, 1.0, vcc
	ds_read_b32 v19, v0 offset:15424
	s_waitcnt lgkmcnt(9)
	v_fmac_f32_dpp v155, -v12, v100 row_newbcast:0 row_mask:0xf bank_mask:0xf
	v_fmac_f32_dpp v155, -v12, v101 row_newbcast:1 row_mask:0xf bank_mask:0xf
	v_fmac_f32_dpp v155, -v12, v102 row_newbcast:2 row_mask:0xf bank_mask:0xf
	v_fmac_f32_dpp v155, -v12, v103 row_newbcast:3 row_mask:0xf bank_mask:0xf
	v_fmac_f32_dpp v155, -v12, v104 row_newbcast:4 row_mask:0xf bank_mask:0xf
	v_fmac_f32_dpp v155, -v12, v105 row_newbcast:5 row_mask:0xf bank_mask:0xf
	v_fmac_f32_dpp v155, -v12, v106 row_newbcast:6 row_mask:0xf bank_mask:0xf
	v_fmac_f32_dpp v155, -v12, v107 row_newbcast:7 row_mask:0xf bank_mask:0xf
	v_fmac_f32_dpp v155, -v12, v108 row_newbcast:8 row_mask:0xf bank_mask:0xf
	v_fmac_f32_dpp v155, -v12, v109 row_newbcast:9 row_mask:0xf bank_mask:0xf
	v_fmac_f32_dpp v155, -v12, v110 row_newbcast:10 row_mask:0xf bank_mask:0xf
	v_fmac_f32_dpp v155, -v12, v111 row_newbcast:11 row_mask:0xf bank_mask:0xf
	v_fmac_f32_dpp v155, -v12, v112 row_newbcast:12 row_mask:0xf bank_mask:0xf
	v_fmac_f32_dpp v155, -v12, v113 row_newbcast:13 row_mask:0xf bank_mask:0xf
	v_fmac_f32_dpp v155, -v12, v114 row_newbcast:14 row_mask:0xf bank_mask:0xf
	v_fmac_f32_dpp v155, -v12, v115 row_newbcast:15 row_mask:0xf bank_mask:0xf
	ds_read_b32 v12, v0 offset:15504
	s_waitcnt lgkmcnt(9)
	v_fmac_f32_dpp v155, -v13, v116 row_newbcast:0 row_mask:0xf bank_mask:0xf
	v_fmac_f32_dpp v155, -v13, v117 row_newbcast:1 row_mask:0xf bank_mask:0xf
	v_fmac_f32_dpp v155, -v13, v118 row_newbcast:2 row_mask:0xf bank_mask:0xf
	v_fmac_f32_dpp v155, -v13, v119 row_newbcast:3 row_mask:0xf bank_mask:0xf
	v_fmac_f32_dpp v155, -v13, v120 row_newbcast:4 row_mask:0xf bank_mask:0xf
	v_fmac_f32_dpp v155, -v13, v121 row_newbcast:5 row_mask:0xf bank_mask:0xf
	v_fmac_f32_dpp v155, -v13, v122 row_newbcast:6 row_mask:0xf bank_mask:0xf
	v_fmac_f32_dpp v155, -v13, v123 row_newbcast:7 row_mask:0xf bank_mask:0xf
	v_fmac_f32_dpp v155, -v13, v124 row_newbcast:8 row_mask:0xf bank_mask:0xf
	v_fmac_f32_dpp v155, -v13, v125 row_newbcast:9 row_mask:0xf bank_mask:0xf
	v_fmac_f32_dpp v155, -v13, v126 row_newbcast:10 row_mask:0xf bank_mask:0xf
	v_fmac_f32_dpp v155, -v13, v127 row_newbcast:11 row_mask:0xf bank_mask:0xf
	v_fmac_f32_dpp v155, -v13, v128 row_newbcast:12 row_mask:0xf bank_mask:0xf
	v_fmac_f32_dpp v155, -v13, v129 row_newbcast:13 row_mask:0xf bank_mask:0xf
	v_fmac_f32_dpp v155, -v13, v130 row_newbcast:14 row_mask:0xf bank_mask:0xf
	v_fmac_f32_dpp v155, -v13, v131 row_newbcast:15 row_mask:0xf bank_mask:0xf
	ds_read_b32 v13, v0 offset:15568
	s_waitcnt lgkmcnt(9)
; DI void d2_chunk(const Params& P, int l, int chunk, LAS float* Nm, LAS float* gs, int lane_in) {
;     ...
;         D2_TBLOCK(0); D2_TBLOCK(1); D2_TBLOCK(2); D2_TBLOCK(3);
	v_fmac_f32_dpp v155, -v14, v132 row_newbcast:0 row_mask:0xf bank_mask:0xf
	v_fmac_f32_dpp v155, -v14, v133 row_newbcast:1 row_mask:0xf bank_mask:0xf
	v_fmac_f32_dpp v155, -v14, v134 row_newbcast:2 row_mask:0xf bank_mask:0xf
	v_fmac_f32_dpp v155, -v14, v135 row_newbcast:3 row_mask:0xf bank_mask:0xf
	v_fmac_f32_dpp v155, -v14, v136 row_newbcast:4 row_mask:0xf bank_mask:0xf
	v_fmac_f32_dpp v155, -v14, v137 row_newbcast:5 row_mask:0xf bank_mask:0xf
	v_fmac_f32_dpp v155, -v14, v138 row_newbcast:6 row_mask:0xf bank_mask:0xf
	v_fmac_f32_dpp v155, -v14, v139 row_newbcast:7 row_mask:0xf bank_mask:0xf
	v_fmac_f32_dpp v155, -v14, v140 row_newbcast:8 row_mask:0xf bank_mask:0xf
	v_fmac_f32_dpp v155, -v14, v141 row_newbcast:9 row_mask:0xf bank_mask:0xf
	v_fmac_f32_dpp v155, -v14, v142 row_newbcast:10 row_mask:0xf bank_mask:0xf
	v_fmac_f32_dpp v155, -v14, v143 row_newbcast:11 row_mask:0xf bank_mask:0xf
	v_fmac_f32_dpp v155, -v14, v144 row_newbcast:12 row_mask:0xf bank_mask:0xf
	v_fmac_f32_dpp v155, -v14, v145 row_newbcast:13 row_mask:0xf bank_mask:0xf
	v_fmac_f32_dpp v155, -v14, v146 row_newbcast:14 row_mask:0xf bank_mask:0xf
	v_fmac_f32_dpp v155, -v14, v147 row_newbcast:15 row_mask:0xf bank_mask:0xf
	ds_read_b32 v14, v0 offset:15632
	s_waitcnt lgkmcnt(8)
	v_fmac_f32_dpp v155, -v15, v148 row_newbcast:0 row_mask:0xf bank_mask:0xf
	v_fmac_f32_dpp v155, -v15, v149 row_newbcast:1 row_mask:0xf bank_mask:0xf
	v_fmac_f32_dpp v155, -v15, v150 row_newbcast:2 row_mask:0xf bank_mask:0xf
	v_fmac_f32_dpp v155, -v15, v151 row_newbcast:3 row_mask:0xf bank_mask:0xf
	v_fmac_f32_dpp v155, -v15, v152 row_newbcast:4 row_mask:0xf bank_mask:0xf
	v_fmac_f32_dpp v155, -v15, v153 row_newbcast:5 row_mask:0xf bank_mask:0xf
	v_fmac_f32_dpp v155, -v15, v154 row_newbcast:6 row_mask:0xf bank_mask:0xf
	ds_write_b32 v169, v155 offset:14960
	v_cmp_eq_u32_e32 vcc, 56, v166
	s_nop 1
	v_cndmask_b32_e64 v156, 0, 1.0, vcc
	ds_read_b32 v15, v0 offset:15696
	s_waitcnt lgkmcnt(9)
	v_fmac_f32_dpp v156, -v16, v100 row_newbcast:0 row_mask:0xf bank_mask:0xf
	v_fmac_f32_dpp v156, -v16, v101 row_newbcast:1 row_mask:0xf bank_mask:0xf
	v_fmac_f32_dpp v156, -v16, v102 row_newbcast:2 row_mask:0xf bank_mask:0xf
	v_fmac_f32_dpp v156, -v16, v103 row_newbcast:3 row_mask:0xf bank_mask:0xf
	v_fmac_f32_dpp v156, -v16, v104 row_newbcast:4 row_mask:0xf bank_mask:0xf
	v_fmac_f32_dpp v156, -v16, v105 row_newbcast:5 row_mask:0xf bank_mask:0xf
	v_fmac_f32_dpp v156, -v16, v106 row_newbcast:6 row_mask:0xf bank_mask:0xf
	v_fmac_f32_dpp v156, -v16, v107 row_newbcast:7 row_mask:0xf bank_mask:0xf
	v_fmac_f32_dpp v156, -v16, v108 row_newbcast:8 row_mask:0xf bank_mask:0xf
	v_fmac_f32_dpp v156, -v16, v109 row_newbcast:9 row_mask:0xf bank_mask:0xf
	v_fmac_f32_dpp v156, -v16, v110 row_newbcast:10 row_mask:0xf bank_mask:0xf
	v_fmac_f32_dpp v156, -v16, v111 row_newbcast:11 row_mask:0xf bank_mask:0xf
	v_fmac_f32_dpp v156, -v16, v112 row_newbcast:12 row_mask:0xf bank_mask:0xf
	v_fmac_f32_dpp v156, -v16, v113 row_newbcast:13 row_mask:0xf bank_mask:0xf
	v_fmac_f32_dpp v156, -v16, v114 row_newbcast:14 row_mask:0xf bank_mask:0xf
	v_fmac_f32_dpp v156, -v16, v115 row_newbcast:15 row_mask:0xf bank_mask:0xf
	ds_read_b32 v16, v0 offset:15776
	s_waitcnt lgkmcnt(9)
	v_fmac_f32_dpp v156, -v17, v116 row_newbcast:0 row_mask:0xf bank_mask:0xf
	v_fmac_f32_dpp v156, -v17, v117 row_newbcast:1 row_mask:0xf bank_mask:0xf
	v_fmac_f32_dpp v156, -v17, v118 row_newbcast:2 row_mask:0xf bank_mask:0xf
	v_fmac_f32_dpp v156, -v17, v119 row_newbcast:3 row_mask:0xf bank_mask:0xf
	v_fmac_f32_dpp v156, -v17, v120 row_newbcast:4 row_mask:0xf bank_mask:0xf
	v_fmac_f32_dpp v156, -v17, v121 row_newbcast:5 row_mask:0xf bank_mask:0xf
	v_fmac_f32_dpp v156, -v17, v122 row_newbcast:6 row_mask:0xf bank_mask:0xf
	v_fmac_f32_dpp v156, -v17, v123 row_newbcast:7 row_mask:0xf bank_mask:0xf
	v_fmac_f32_dpp v156, -v17, v124 row_newbcast:8 row_mask:0xf bank_mask:0xf
	v_fmac_f32_dpp v156, -v17, v125 row_newbcast:9 row_mask:0xf bank_mask:0xf
	v_fmac_f32_dpp v156, -v17, v126 row_newbcast:10 row_mask:0xf bank_mask:0xf
	v_fmac_f32_dpp v156, -v17, v127 row_newbcast:11 row_mask:0xf bank_mask:0xf
	v_fmac_f32_dpp v156, -v17, v128 row_newbcast:12 row_mask:0xf bank_mask:0xf
	v_fmac_f32_dpp v156, -v17, v129 row_newbcast:13 row_mask:0xf bank_mask:0xf
	v_fmac_f32_dpp v156, -v17, v130 row_newbcast:14 row_mask:0xf bank_mask:0xf
	v_fmac_f32_dpp v156, -v17, v131 row_newbcast:15 row_mask:0xf bank_mask:0xf
	ds_read_b32 v17, v0 offset:15840
	s_waitcnt lgkmcnt(9)
	v_fmac_f32_dpp v156, -v18, v132 row_newbcast:0 row_mask:0xf bank_mask:0xf
	v_fmac_f32_dpp v156, -v18, v133 row_newbcast:1 row_mask:0xf bank_mask:0xf
	v_fmac_f32_dpp v156, -v18, v134 row_newbcast:2 row_mask:0xf bank_mask:0xf
	v_fmac_f32_dpp v156, -v18, v135 row_newbcast:3 row_mask:0xf bank_mask:0xf
	v_fmac_f32_dpp v156, -v18, v136 row_newbcast:4 row_mask:0xf bank_mask:0xf
	v_fmac_f32_dpp v156, -v18, v137 row_newbcast:5 row_mask:0xf bank_mask:0xf
	v_fmac_f32_dpp v156, -v18, v138 row_newbcast:6 row_mask:0xf bank_mask:0xf
	v_fmac_f32_dpp v156, -v18, v139 row_newbcast:7 row_mask:0xf bank_mask:0xf
	v_fmac_f32_dpp v156, -v18, v140 row_newbcast:8 row_mask:0xf bank_mask:0xf
	v_fmac_f32_dpp v156, -v18, v141 row_newbcast:9 row_mask:0xf bank_mask:0xf
	v_fmac_f32_dpp v156, -v18, v142 row_newbcast:10 row_mask:0xf bank_mask:0xf
	v_fmac_f32_dpp v156, -v18, v143 row_newbcast:11 row_mask:0xf bank_mask:0xf
	v_fmac_f32_dpp v156, -v18, v144 row_newbcast:12 row_mask:0xf bank_mask:0xf
	v_fmac_f32_dpp v156, -v18, v145 row_newbcast:13 row_mask:0xf bank_mask:0xf
	v_fmac_f32_dpp v156, -v18, v146 row_newbcast:14 row_mask:0xf bank_mask:0xf
	v_fmac_f32_dpp v156, -v18, v147 row_newbcast:15 row_mask:0xf bank_mask:0xf
	ds_read_b32 v18, v0 offset:15904
	s_waitcnt lgkmcnt(8)
; DI void d2_chunk(const Params& P, int l, int chunk, LAS float* Nm, LAS float* gs, int lane_in) {
;     ...
;         D2_TBLOCK(0); D2_TBLOCK(1); D2_TBLOCK(2); D2_TBLOCK(3);
	v_fmac_f32_dpp v156, -v19, v148 row_newbcast:0 row_mask:0xf bank_mask:0xf
	v_fmac_f32_dpp v156, -v19, v149 row_newbcast:1 row_mask:0xf bank_mask:0xf
	v_fmac_f32_dpp v156, -v19, v150 row_newbcast:2 row_mask:0xf bank_mask:0xf
	v_fmac_f32_dpp v156, -v19, v151 row_newbcast:3 row_mask:0xf bank_mask:0xf
	v_fmac_f32_dpp v156, -v19, v152 row_newbcast:4 row_mask:0xf bank_mask:0xf
	v_fmac_f32_dpp v156, -v19, v153 row_newbcast:5 row_mask:0xf bank_mask:0xf
	v_fmac_f32_dpp v156, -v19, v154 row_newbcast:6 row_mask:0xf bank_mask:0xf
	v_fmac_f32_dpp v156, -v19, v155 row_newbcast:7 row_mask:0xf bank_mask:0xf
	ds_write_b32 v169, v156 offset:15232
	v_cmp_eq_u32_e32 vcc, 57, v166
	s_nop 1
	v_cndmask_b32_e64 v157, 0, 1.0, vcc
	ds_read_b32 v19, v0 offset:15968
	s_waitcnt lgkmcnt(9)
	v_fmac_f32_dpp v157, -v12, v100 row_newbcast:0 row_mask:0xf bank_mask:0xf
	v_fmac_f32_dpp v157, -v12, v101 row_newbcast:1 row_mask:0xf bank_mask:0xf
	v_fmac_f32_dpp v157, -v12, v102 row_newbcast:2 row_mask:0xf bank_mask:0xf
	v_fmac_f32_dpp v157, -v12, v103 row_newbcast:3 row_mask:0xf bank_mask:0xf
	v_fmac_f32_dpp v157, -v12, v104 row_newbcast:4 row_mask:0xf bank_mask:0xf
	v_fmac_f32_dpp v157, -v12, v105 row_newbcast:5 row_mask:0xf bank_mask:0xf
	v_fmac_f32_dpp v157, -v12, v106 row_newbcast:6 row_mask:0xf bank_mask:0xf
	v_fmac_f32_dpp v157, -v12, v107 row_newbcast:7 row_mask:0xf bank_mask:0xf
	v_fmac_f32_dpp v157, -v12, v108 row_newbcast:8 row_mask:0xf bank_mask:0xf
	v_fmac_f32_dpp v157, -v12, v109 row_newbcast:9 row_mask:0xf bank_mask:0xf
	v_fmac_f32_dpp v157, -v12, v110 row_newbcast:10 row_mask:0xf bank_mask:0xf
	v_fmac_f32_dpp v157, -v12, v111 row_newbcast:11 row_mask:0xf bank_mask:0xf
	v_fmac_f32_dpp v157, -v12, v112 row_newbcast:12 row_mask:0xf bank_mask:0xf
	v_fmac_f32_dpp v157, -v12, v113 row_newbcast:13 row_mask:0xf bank_mask:0xf
	v_fmac_f32_dpp v157, -v12, v114 row_newbcast:14 row_mask:0xf bank_mask:0xf
	v_fmac_f32_dpp v157, -v12, v115 row_newbcast:15 row_mask:0xf bank_mask:0xf
	ds_read_b32 v12, v0 offset:16048
	s_waitcnt lgkmcnt(9)
	v_fmac_f32_dpp v157, -v13, v116 row_newbcast:0 row_mask:0xf bank_mask:0xf
	v_fmac_f32_dpp v157, -v13, v117 row_newbcast:1 row_mask:0xf bank_mask:0xf
	v_fmac_f32_dpp v157, -v13, v118 row_newbcast:2 row_mask:0xf bank_mask:0xf
	v_fmac_f32_dpp v157, -v13, v119 row_newbcast:3 row_mask:0xf bank_mask:0xf
	v_fmac_f32_dpp v157, -v13, v120 row_newbcast:4 row_mask:0xf bank_mask:0xf
	v_fmac_f32_dpp v157, -v13, v121 row_newbcast:5 row_mask:0xf bank_mask:0xf
	v_fmac_f32_dpp v157, -v13, v122 row_newbcast:6 row_mask:0xf bank_mask:0xf
	v_fmac_f32_dpp v157, -v13, v123 row_newbcast:7 row_mask:0xf bank_mask:0xf
	v_fmac_f32_dpp v157, -v13, v124 row_newbcast:8 row_mask:0xf bank_mask:0xf
	v_fmac_f32_dpp v157, -v13, v125 row_newbcast:9 row_mask:0xf bank_mask:0xf
	v_fmac_f32_dpp v157, -v13, v126 row_newbcast:10 row_mask:0xf bank_mask:0xf
	v_fmac_f32_dpp v157, -v13, v127 row_newbcast:11 row_mask:0xf bank_mask:0xf
	v_fmac_f32_dpp v157, -v13, v128 row_newbcast:12 row_mask:0xf bank_mask:0xf
	v_fmac_f32_dpp v157, -v13, v129 row_newbcast:13 row_mask:0xf bank_mask:0xf
	v_fmac_f32_dpp v157, -v13, v130 row_newbcast:14 row_mask:0xf bank_mask:0xf
	v_fmac_f32_dpp v157, -v13, v131 row_newbcast:15 row_mask:0xf bank_mask:0xf
	ds_read_b32 v13, v0 offset:16112
	s_waitcnt lgkmcnt(9)
	v_fmac_f32_dpp v157, -v14, v132 row_newbcast:0 row_mask:0xf bank_mask:0xf
	v_fmac_f32_dpp v157, -v14, v133 row_newbcast:1 row_mask:0xf bank_mask:0xf
	v_fmac_f32_dpp v157, -v14, v134 row_newbcast:2 row_mask:0xf bank_mask:0xf
	v_fmac_f32_dpp v157, -v14, v135 row_newbcast:3 row_mask:0xf bank_mask:0xf
	v_fmac_f32_dpp v157, -v14, v136 row_newbcast:4 row_mask:0xf bank_mask:0xf
	v_fmac_f32_dpp v157, -v14, v137 row_newbcast:5 row_mask:0xf bank_mask:0xf
	v_fmac_f32_dpp v157, -v14, v138 row_newbcast:6 row_mask:0xf bank_mask:0xf
	v_fmac_f32_dpp v157, -v14, v139 row_newbcast:7 row_mask:0xf bank_mask:0xf
	v_fmac_f32_dpp v157, -v14, v140 row_newbcast:8 row_mask:0xf bank_mask:0xf
	v_fmac_f32_dpp v157, -v14, v141 row_newbcast:9 row_mask:0xf bank_mask:0xf
	v_fmac_f32_dpp v157, -v14, v142 row_newbcast:10 row_mask:0xf bank_mask:0xf
	v_fmac_f32_dpp v157, -v14, v143 row_newbcast:11 row_mask:0xf bank_mask:0xf
	v_fmac_f32_dpp v157, -v14, v144 row_newbcast:12 row_mask:0xf bank_mask:0xf
	v_fmac_f32_dpp v157, -v14, v145 row_newbcast:13 row_mask:0xf bank_mask:0xf
	v_fmac_f32_dpp v157, -v14, v146 row_newbcast:14 row_mask:0xf bank_mask:0xf
	v_fmac_f32_dpp v157, -v14, v147 row_newbcast:15 row_mask:0xf bank_mask:0xf
	ds_read_b32 v14, v0 offset:16176
	s_waitcnt lgkmcnt(8)
	v_fmac_f32_dpp v157, -v15, v148 row_newbcast:0 row_mask:0xf bank_mask:0xf
	v_fmac_f32_dpp v157, -v15, v149 row_newbcast:1 row_mask:0xf bank_mask:0xf
	v_fmac_f32_dpp v157, -v15, v150 row_newbcast:2 row_mask:0xf bank_mask:0xf
	v_fmac_f32_dpp v157, -v15, v151 row_newbcast:3 row_mask:0xf bank_mask:0xf
	v_fmac_f32_dpp v157, -v15, v152 row_newbcast:4 row_mask:0xf bank_mask:0xf
	v_fmac_f32_dpp v157, -v15, v153 row_newbcast:5 row_mask:0xf bank_mask:0xf
	v_fmac_f32_dpp v157, -v15, v154 row_newbcast:6 row_mask:0xf bank_mask:0xf
	v_fmac_f32_dpp v157, -v15, v155 row_newbcast:7 row_mask:0xf bank_mask:0xf
	v_fmac_f32_dpp v157, -v15, v156 row_newbcast:8 row_mask:0xf bank_mask:0xf
	ds_write_b32 v169, v157 offset:15504
	v_cmp_eq_u32_e32 vcc, 58, v166
	s_nop 1
	v_cndmask_b32_e64 v158, 0, 1.0, vcc
	ds_read_b32 v15, v0 offset:16240
	s_waitcnt lgkmcnt(9)
; DI void d2_chunk(const Params& P, int l, int chunk, LAS float* Nm, LAS float* gs, int lane_in) {
;     ...
;         D2_TBLOCK(0); D2_TBLOCK(1); D2_TBLOCK(2); D2_TBLOCK(3);
	v_fmac_f32_dpp v158, -v16, v100 row_newbcast:0 row_mask:0xf bank_mask:0xf
	v_fmac_f32_dpp v158, -v16, v101 row_newbcast:1 row_mask:0xf bank_mask:0xf
	v_fmac_f32_dpp v158, -v16, v102 row_newbcast:2 row_mask:0xf bank_mask:0xf
	v_fmac_f32_dpp v158, -v16, v103 row_newbcast:3 row_mask:0xf bank_mask:0xf
	v_fmac_f32_dpp v158, -v16, v104 row_newbcast:4 row_mask:0xf bank_mask:0xf
	v_fmac_f32_dpp v158, -v16, v105 row_newbcast:5 row_mask:0xf bank_mask:0xf
	v_fmac_f32_dpp v158, -v16, v106 row_newbcast:6 row_mask:0xf bank_mask:0xf
	v_fmac_f32_dpp v158, -v16, v107 row_newbcast:7 row_mask:0xf bank_mask:0xf
	v_fmac_f32_dpp v158, -v16, v108 row_newbcast:8 row_mask:0xf bank_mask:0xf
	v_fmac_f32_dpp v158, -v16, v109 row_newbcast:9 row_mask:0xf bank_mask:0xf
	v_fmac_f32_dpp v158, -v16, v110 row_newbcast:10 row_mask:0xf bank_mask:0xf
	v_fmac_f32_dpp v158, -v16, v111 row_newbcast:11 row_mask:0xf bank_mask:0xf
	v_fmac_f32_dpp v158, -v16, v112 row_newbcast:12 row_mask:0xf bank_mask:0xf
	v_fmac_f32_dpp v158, -v16, v113 row_newbcast:13 row_mask:0xf bank_mask:0xf
	v_fmac_f32_dpp v158, -v16, v114 row_newbcast:14 row_mask:0xf bank_mask:0xf
	v_fmac_f32_dpp v158, -v16, v115 row_newbcast:15 row_mask:0xf bank_mask:0xf
	ds_read_b32 v16, v0 offset:16320
	s_waitcnt lgkmcnt(9)
	v_fmac_f32_dpp v158, -v17, v116 row_newbcast:0 row_mask:0xf bank_mask:0xf
	v_fmac_f32_dpp v158, -v17, v117 row_newbcast:1 row_mask:0xf bank_mask:0xf
	v_fmac_f32_dpp v158, -v17, v118 row_newbcast:2 row_mask:0xf bank_mask:0xf
	v_fmac_f32_dpp v158, -v17, v119 row_newbcast:3 row_mask:0xf bank_mask:0xf
	v_fmac_f32_dpp v158, -v17, v120 row_newbcast:4 row_mask:0xf bank_mask:0xf
	v_fmac_f32_dpp v158, -v17, v121 row_newbcast:5 row_mask:0xf bank_mask:0xf
	v_fmac_f32_dpp v158, -v17, v122 row_newbcast:6 row_mask:0xf bank_mask:0xf
	v_fmac_f32_dpp v158, -v17, v123 row_newbcast:7 row_mask:0xf bank_mask:0xf
	v_fmac_f32_dpp v158, -v17, v124 row_newbcast:8 row_mask:0xf bank_mask:0xf
	v_fmac_f32_dpp v158, -v17, v125 row_newbcast:9 row_mask:0xf bank_mask:0xf
	v_fmac_f32_dpp v158, -v17, v126 row_newbcast:10 row_mask:0xf bank_mask:0xf
	v_fmac_f32_dpp v158, -v17, v127 row_newbcast:11 row_mask:0xf bank_mask:0xf
	v_fmac_f32_dpp v158, -v17, v128 row_newbcast:12 row_mask:0xf bank_mask:0xf
	v_fmac_f32_dpp v158, -v17, v129 row_newbcast:13 row_mask:0xf bank_mask:0xf
	v_fmac_f32_dpp v158, -v17, v130 row_newbcast:14 row_mask:0xf bank_mask:0xf
	v_fmac_f32_dpp v158, -v17, v131 row_newbcast:15 row_mask:0xf bank_mask:0xf
	ds_read_b32 v17, v0 offset:16384
	s_waitcnt lgkmcnt(9)
	v_fmac_f32_dpp v158, -v18, v132 row_newbcast:0 row_mask:0xf bank_mask:0xf
	v_fmac_f32_dpp v158, -v18, v133 row_newbcast:1 row_mask:0xf bank_mask:0xf
	v_fmac_f32_dpp v158, -v18, v134 row_newbcast:2 row_mask:0xf bank_mask:0xf
	v_fmac_f32_dpp v158, -v18, v135 row_newbcast:3 row_mask:0xf bank_mask:0xf
	v_fmac_f32_dpp v158, -v18, v136 row_newbcast:4 row_mask:0xf bank_mask:0xf
	v_fmac_f32_dpp v158, -v18, v137 row_newbcast:5 row_mask:0xf bank_mask:0xf
	v_fmac_f32_dpp v158, -v18, v138 row_newbcast:6 row_mask:0xf bank_mask:0xf
	v_fmac_f32_dpp v158, -v18, v139 row_newbcast:7 row_mask:0xf bank_mask:0xf
	v_fmac_f32_dpp v158, -v18, v140 row_newbcast:8 row_mask:0xf bank_mask:0xf
	v_fmac_f32_dpp v158, -v18, v141 row_newbcast:9 row_mask:0xf bank_mask:0xf
	v_fmac_f32_dpp v158, -v18, v142 row_newbcast:10 row_mask:0xf bank_mask:0xf
	v_fmac_f32_dpp v158, -v18, v143 row_newbcast:11 row_mask:0xf bank_mask:0xf
	v_fmac_f32_dpp v158, -v18, v144 row_newbcast:12 row_mask:0xf bank_mask:0xf
	v_fmac_f32_dpp v158, -v18, v145 row_newbcast:13 row_mask:0xf bank_mask:0xf
	v_fmac_f32_dpp v158, -v18, v146 row_newbcast:14 row_mask:0xf bank_mask:0xf
	v_fmac_f32_dpp v158, -v18, v147 row_newbcast:15 row_mask:0xf bank_mask:0xf
	ds_read_b32 v18, v0 offset:16448
	s_waitcnt lgkmcnt(8)
	v_fmac_f32_dpp v158, -v19, v148 row_newbcast:0 row_mask:0xf bank_mask:0xf
	v_fmac_f32_dpp v158, -v19, v149 row_newbcast:1 row_mask:0xf bank_mask:0xf
	v_fmac_f32_dpp v158, -v19, v150 row_newbcast:2 row_mask:0xf bank_mask:0xf
	v_fmac_f32_dpp v158, -v19, v151 row_newbcast:3 row_mask:0xf bank_mask:0xf
	v_fmac_f32_dpp v158, -v19, v152 row_newbcast:4 row_mask:0xf bank_mask:0xf
	v_fmac_f32_dpp v158, -v19, v153 row_newbcast:5 row_mask:0xf bank_mask:0xf
	v_fmac_f32_dpp v158, -v19, v154 row_newbcast:6 row_mask:0xf bank_mask:0xf
	v_fmac_f32_dpp v158, -v19, v155 row_newbcast:7 row_mask:0xf bank_mask:0xf
	v_fmac_f32_dpp v158, -v19, v156 row_newbcast:8 row_mask:0xf bank_mask:0xf
	v_fmac_f32_dpp v158, -v19, v157 row_newbcast:9 row_mask:0xf bank_mask:0xf
	ds_write_b32 v169, v158 offset:15776
	v_cmp_eq_u32_e32 vcc, 59, v166
	s_nop 1
	v_cndmask_b32_e64 v159, 0, 1.0, vcc
	ds_read_b32 v19, v0 offset:16512
	s_waitcnt lgkmcnt(9)
	v_fmac_f32_dpp v159, -v12, v100 row_newbcast:0 row_mask:0xf bank_mask:0xf
	v_fmac_f32_dpp v159, -v12, v101 row_newbcast:1 row_mask:0xf bank_mask:0xf
	v_fmac_f32_dpp v159, -v12, v102 row_newbcast:2 row_mask:0xf bank_mask:0xf
	v_fmac_f32_dpp v159, -v12, v103 row_newbcast:3 row_mask:0xf bank_mask:0xf
	v_fmac_f32_dpp v159, -v12, v104 row_newbcast:4 row_mask:0xf bank_mask:0xf
	v_fmac_f32_dpp v159, -v12, v105 row_newbcast:5 row_mask:0xf bank_mask:0xf
	v_fmac_f32_dpp v159, -v12, v106 row_newbcast:6 row_mask:0xf bank_mask:0xf
	v_fmac_f32_dpp v159, -v12, v107 row_newbcast:7 row_mask:0xf bank_mask:0xf
	v_fmac_f32_dpp v159, -v12, v108 row_newbcast:8 row_mask:0xf bank_mask:0xf
	v_fmac_f32_dpp v159, -v12, v109 row_newbcast:9 row_mask:0xf bank_mask:0xf
	v_fmac_f32_dpp v159, -v12, v110 row_newbcast:10 row_mask:0xf bank_mask:0xf
	v_fmac_f32_dpp v159, -v12, v111 row_newbcast:11 row_mask:0xf bank_mask:0xf
	v_fmac_f32_dpp v159, -v12, v112 row_newbcast:12 row_mask:0xf bank_mask:0xf
	v_fmac_f32_dpp v159, -v12, v113 row_newbcast:13 row_mask:0xf bank_mask:0xf
	v_fmac_f32_dpp v159, -v12, v114 row_newbcast:14 row_mask:0xf bank_mask:0xf
	v_fmac_f32_dpp v159, -v12, v115 row_newbcast:15 row_mask:0xf bank_mask:0xf
	ds_read_b32 v12, v0 offset:16592
	s_waitcnt lgkmcnt(9)
; DI void d2_chunk(const Params& P, int l, int chunk, LAS float* Nm, LAS float* gs, int lane_in) {
;     ...
;         D2_TBLOCK(0); D2_TBLOCK(1); D2_TBLOCK(2); D2_TBLOCK(3);
	v_fmac_f32_dpp v159, -v13, v116 row_newbcast:0 row_mask:0xf bank_mask:0xf
	v_fmac_f32_dpp v159, -v13, v117 row_newbcast:1 row_mask:0xf bank_mask:0xf
	v_fmac_f32_dpp v159, -v13, v118 row_newbcast:2 row_mask:0xf bank_mask:0xf
	v_fmac_f32_dpp v159, -v13, v119 row_newbcast:3 row_mask:0xf bank_mask:0xf
	v_fmac_f32_dpp v159, -v13, v120 row_newbcast:4 row_mask:0xf bank_mask:0xf
	v_fmac_f32_dpp v159, -v13, v121 row_newbcast:5 row_mask:0xf bank_mask:0xf
	v_fmac_f32_dpp v159, -v13, v122 row_newbcast:6 row_mask:0xf bank_mask:0xf
	v_fmac_f32_dpp v159, -v13, v123 row_newbcast:7 row_mask:0xf bank_mask:0xf
	v_fmac_f32_dpp v159, -v13, v124 row_newbcast:8 row_mask:0xf bank_mask:0xf
	v_fmac_f32_dpp v159, -v13, v125 row_newbcast:9 row_mask:0xf bank_mask:0xf
	v_fmac_f32_dpp v159, -v13, v126 row_newbcast:10 row_mask:0xf bank_mask:0xf
	v_fmac_f32_dpp v159, -v13, v127 row_newbcast:11 row_mask:0xf bank_mask:0xf
	v_fmac_f32_dpp v159, -v13, v128 row_newbcast:12 row_mask:0xf bank_mask:0xf
	v_fmac_f32_dpp v159, -v13, v129 row_newbcast:13 row_mask:0xf bank_mask:0xf
	v_fmac_f32_dpp v159, -v13, v130 row_newbcast:14 row_mask:0xf bank_mask:0xf
	v_fmac_f32_dpp v159, -v13, v131 row_newbcast:15 row_mask:0xf bank_mask:0xf
	ds_read_b32 v13, v0 offset:16656
	s_waitcnt lgkmcnt(9)
	v_fmac_f32_dpp v159, -v14, v132 row_newbcast:0 row_mask:0xf bank_mask:0xf
	v_fmac_f32_dpp v159, -v14, v133 row_newbcast:1 row_mask:0xf bank_mask:0xf
	v_fmac_f32_dpp v159, -v14, v134 row_newbcast:2 row_mask:0xf bank_mask:0xf
	v_fmac_f32_dpp v159, -v14, v135 row_newbcast:3 row_mask:0xf bank_mask:0xf
	v_fmac_f32_dpp v159, -v14, v136 row_newbcast:4 row_mask:0xf bank_mask:0xf
	v_fmac_f32_dpp v159, -v14, v137 row_newbcast:5 row_mask:0xf bank_mask:0xf
	v_fmac_f32_dpp v159, -v14, v138 row_newbcast:6 row_mask:0xf bank_mask:0xf
	v_fmac_f32_dpp v159, -v14, v139 row_newbcast:7 row_mask:0xf bank_mask:0xf
	v_fmac_f32_dpp v159, -v14, v140 row_newbcast:8 row_mask:0xf bank_mask:0xf
	v_fmac_f32_dpp v159, -v14, v141 row_newbcast:9 row_mask:0xf bank_mask:0xf
	v_fmac_f32_dpp v159, -v14, v142 row_newbcast:10 row_mask:0xf bank_mask:0xf
	v_fmac_f32_dpp v159, -v14, v143 row_newbcast:11 row_mask:0xf bank_mask:0xf
	v_fmac_f32_dpp v159, -v14, v144 row_newbcast:12 row_mask:0xf bank_mask:0xf
	v_fmac_f32_dpp v159, -v14, v145 row_newbcast:13 row_mask:0xf bank_mask:0xf
	v_fmac_f32_dpp v159, -v14, v146 row_newbcast:14 row_mask:0xf bank_mask:0xf
	v_fmac_f32_dpp v159, -v14, v147 row_newbcast:15 row_mask:0xf bank_mask:0xf
	ds_read_b32 v14, v0 offset:16720
	s_waitcnt lgkmcnt(8)
	v_fmac_f32_dpp v159, -v15, v148 row_newbcast:0 row_mask:0xf bank_mask:0xf
	v_fmac_f32_dpp v159, -v15, v149 row_newbcast:1 row_mask:0xf bank_mask:0xf
	v_fmac_f32_dpp v159, -v15, v150 row_newbcast:2 row_mask:0xf bank_mask:0xf
	v_fmac_f32_dpp v159, -v15, v151 row_newbcast:3 row_mask:0xf bank_mask:0xf
	v_fmac_f32_dpp v159, -v15, v152 row_newbcast:4 row_mask:0xf bank_mask:0xf
	v_fmac_f32_dpp v159, -v15, v153 row_newbcast:5 row_mask:0xf bank_mask:0xf
	v_fmac_f32_dpp v159, -v15, v154 row_newbcast:6 row_mask:0xf bank_mask:0xf
	v_fmac_f32_dpp v159, -v15, v155 row_newbcast:7 row_mask:0xf bank_mask:0xf
	v_fmac_f32_dpp v159, -v15, v156 row_newbcast:8 row_mask:0xf bank_mask:0xf
	v_fmac_f32_dpp v159, -v15, v157 row_newbcast:9 row_mask:0xf bank_mask:0xf
	v_fmac_f32_dpp v159, -v15, v158 row_newbcast:10 row_mask:0xf bank_mask:0xf
	ds_write_b32 v169, v159 offset:16048
	v_cmp_eq_u32_e32 vcc, 60, v166
	s_nop 1
	v_cndmask_b32_e64 v160, 0, 1.0, vcc
	ds_read_b32 v15, v0 offset:16784
	s_waitcnt lgkmcnt(9)
	v_fmac_f32_dpp v160, -v16, v100 row_newbcast:0 row_mask:0xf bank_mask:0xf
	v_fmac_f32_dpp v160, -v16, v101 row_newbcast:1 row_mask:0xf bank_mask:0xf
	v_fmac_f32_dpp v160, -v16, v102 row_newbcast:2 row_mask:0xf bank_mask:0xf
	v_fmac_f32_dpp v160, -v16, v103 row_newbcast:3 row_mask:0xf bank_mask:0xf
	v_fmac_f32_dpp v160, -v16, v104 row_newbcast:4 row_mask:0xf bank_mask:0xf
	v_fmac_f32_dpp v160, -v16, v105 row_newbcast:5 row_mask:0xf bank_mask:0xf
	v_fmac_f32_dpp v160, -v16, v106 row_newbcast:6 row_mask:0xf bank_mask:0xf
	v_fmac_f32_dpp v160, -v16, v107 row_newbcast:7 row_mask:0xf bank_mask:0xf
	v_fmac_f32_dpp v160, -v16, v108 row_newbcast:8 row_mask:0xf bank_mask:0xf
	v_fmac_f32_dpp v160, -v16, v109 row_newbcast:9 row_mask:0xf bank_mask:0xf
	v_fmac_f32_dpp v160, -v16, v110 row_newbcast:10 row_mask:0xf bank_mask:0xf
	v_fmac_f32_dpp v160, -v16, v111 row_newbcast:11 row_mask:0xf bank_mask:0xf
	v_fmac_f32_dpp v160, -v16, v112 row_newbcast:12 row_mask:0xf bank_mask:0xf
	v_fmac_f32_dpp v160, -v16, v113 row_newbcast:13 row_mask:0xf bank_mask:0xf
	v_fmac_f32_dpp v160, -v16, v114 row_newbcast:14 row_mask:0xf bank_mask:0xf
	v_fmac_f32_dpp v160, -v16, v115 row_newbcast:15 row_mask:0xf bank_mask:0xf
	ds_read_b32 v16, v0 offset:16864
	s_waitcnt lgkmcnt(9)
	v_fmac_f32_dpp v160, -v17, v116 row_newbcast:0 row_mask:0xf bank_mask:0xf
	v_fmac_f32_dpp v160, -v17, v117 row_newbcast:1 row_mask:0xf bank_mask:0xf
	v_fmac_f32_dpp v160, -v17, v118 row_newbcast:2 row_mask:0xf bank_mask:0xf
	v_fmac_f32_dpp v160, -v17, v119 row_newbcast:3 row_mask:0xf bank_mask:0xf
	v_fmac_f32_dpp v160, -v17, v120 row_newbcast:4 row_mask:0xf bank_mask:0xf
	v_fmac_f32_dpp v160, -v17, v121 row_newbcast:5 row_mask:0xf bank_mask:0xf
	v_fmac_f32_dpp v160, -v17, v122 row_newbcast:6 row_mask:0xf bank_mask:0xf
	v_fmac_f32_dpp v160, -v17, v123 row_newbcast:7 row_mask:0xf bank_mask:0xf
	v_fmac_f32_dpp v160, -v17, v124 row_newbcast:8 row_mask:0xf bank_mask:0xf
	v_fmac_f32_dpp v160, -v17, v125 row_newbcast:9 row_mask:0xf bank_mask:0xf
	v_fmac_f32_dpp v160, -v17, v126 row_newbcast:10 row_mask:0xf bank_mask:0xf
	v_fmac_f32_dpp v160, -v17, v127 row_newbcast:11 row_mask:0xf bank_mask:0xf
	v_fmac_f32_dpp v160, -v17, v128 row_newbcast:12 row_mask:0xf bank_mask:0xf
	v_fmac_f32_dpp v160, -v17, v129 row_newbcast:13 row_mask:0xf bank_mask:0xf
	v_fmac_f32_dpp v160, -v17, v130 row_newbcast:14 row_mask:0xf bank_mask:0xf
	v_fmac_f32_dpp v160, -v17, v131 row_newbcast:15 row_mask:0xf bank_mask:0xf
	ds_read_b32 v17, v0 offset:16928
	s_waitcnt lgkmcnt(9)
; DI void d2_chunk(const Params& P, int l, int chunk, LAS float* Nm, LAS float* gs, int lane_in) {
;     ...
;         D2_TBLOCK(0); D2_TBLOCK(1); D2_TBLOCK(2); D2_TBLOCK(3);
	v_fmac_f32_dpp v160, -v18, v132 row_newbcast:0 row_mask:0xf bank_mask:0xf
	v_fmac_f32_dpp v160, -v18, v133 row_newbcast:1 row_mask:0xf bank_mask:0xf
	v_fmac_f32_dpp v160, -v18, v134 row_newbcast:2 row_mask:0xf bank_mask:0xf
	v_fmac_f32_dpp v160, -v18, v135 row_newbcast:3 row_mask:0xf bank_mask:0xf
	v_fmac_f32_dpp v160, -v18, v136 row_newbcast:4 row_mask:0xf bank_mask:0xf
	v_fmac_f32_dpp v160, -v18, v137 row_newbcast:5 row_mask:0xf bank_mask:0xf
	v_fmac_f32_dpp v160, -v18, v138 row_newbcast:6 row_mask:0xf bank_mask:0xf
	v_fmac_f32_dpp v160, -v18, v139 row_newbcast:7 row_mask:0xf bank_mask:0xf
	v_fmac_f32_dpp v160, -v18, v140 row_newbcast:8 row_mask:0xf bank_mask:0xf
	v_fmac_f32_dpp v160, -v18, v141 row_newbcast:9 row_mask:0xf bank_mask:0xf
	v_fmac_f32_dpp v160, -v18, v142 row_newbcast:10 row_mask:0xf bank_mask:0xf
	v_fmac_f32_dpp v160, -v18, v143 row_newbcast:11 row_mask:0xf bank_mask:0xf
	v_fmac_f32_dpp v160, -v18, v144 row_newbcast:12 row_mask:0xf bank_mask:0xf
	v_fmac_f32_dpp v160, -v18, v145 row_newbcast:13 row_mask:0xf bank_mask:0xf
	v_fmac_f32_dpp v160, -v18, v146 row_newbcast:14 row_mask:0xf bank_mask:0xf
	v_fmac_f32_dpp v160, -v18, v147 row_newbcast:15 row_mask:0xf bank_mask:0xf
	ds_read_b32 v18, v0 offset:16992
	s_waitcnt lgkmcnt(8)
	v_fmac_f32_dpp v160, -v19, v148 row_newbcast:0 row_mask:0xf bank_mask:0xf
	v_fmac_f32_dpp v160, -v19, v149 row_newbcast:1 row_mask:0xf bank_mask:0xf
	v_fmac_f32_dpp v160, -v19, v150 row_newbcast:2 row_mask:0xf bank_mask:0xf
	v_fmac_f32_dpp v160, -v19, v151 row_newbcast:3 row_mask:0xf bank_mask:0xf
	v_fmac_f32_dpp v160, -v19, v152 row_newbcast:4 row_mask:0xf bank_mask:0xf
	v_fmac_f32_dpp v160, -v19, v153 row_newbcast:5 row_mask:0xf bank_mask:0xf
	v_fmac_f32_dpp v160, -v19, v154 row_newbcast:6 row_mask:0xf bank_mask:0xf
	v_fmac_f32_dpp v160, -v19, v155 row_newbcast:7 row_mask:0xf bank_mask:0xf
	v_fmac_f32_dpp v160, -v19, v156 row_newbcast:8 row_mask:0xf bank_mask:0xf
	v_fmac_f32_dpp v160, -v19, v157 row_newbcast:9 row_mask:0xf bank_mask:0xf
	v_fmac_f32_dpp v160, -v19, v158 row_newbcast:10 row_mask:0xf bank_mask:0xf
	v_fmac_f32_dpp v160, -v19, v159 row_newbcast:11 row_mask:0xf bank_mask:0xf
	ds_write_b32 v169, v160 offset:16320
	v_cmp_eq_u32_e32 vcc, 61, v166
	s_nop 1
	v_cndmask_b32_e64 v161, 0, 1.0, vcc
	ds_read_b32 v19, v0 offset:17056
	s_waitcnt lgkmcnt(9)
	v_fmac_f32_dpp v161, -v12, v100 row_newbcast:0 row_mask:0xf bank_mask:0xf
	v_fmac_f32_dpp v161, -v12, v101 row_newbcast:1 row_mask:0xf bank_mask:0xf
	v_fmac_f32_dpp v161, -v12, v102 row_newbcast:2 row_mask:0xf bank_mask:0xf
	v_fmac_f32_dpp v161, -v12, v103 row_newbcast:3 row_mask:0xf bank_mask:0xf
	v_fmac_f32_dpp v161, -v12, v104 row_newbcast:4 row_mask:0xf bank_mask:0xf
	v_fmac_f32_dpp v161, -v12, v105 row_newbcast:5 row_mask:0xf bank_mask:0xf
	v_fmac_f32_dpp v161, -v12, v106 row_newbcast:6 row_mask:0xf bank_mask:0xf
	v_fmac_f32_dpp v161, -v12, v107 row_newbcast:7 row_mask:0xf bank_mask:0xf
	v_fmac_f32_dpp v161, -v12, v108 row_newbcast:8 row_mask:0xf bank_mask:0xf
	v_fmac_f32_dpp v161, -v12, v109 row_newbcast:9 row_mask:0xf bank_mask:0xf
	v_fmac_f32_dpp v161, -v12, v110 row_newbcast:10 row_mask:0xf bank_mask:0xf
	v_fmac_f32_dpp v161, -v12, v111 row_newbcast:11 row_mask:0xf bank_mask:0xf
	v_fmac_f32_dpp v161, -v12, v112 row_newbcast:12 row_mask:0xf bank_mask:0xf
	v_fmac_f32_dpp v161, -v12, v113 row_newbcast:13 row_mask:0xf bank_mask:0xf
	v_fmac_f32_dpp v161, -v12, v114 row_newbcast:14 row_mask:0xf bank_mask:0xf
	v_fmac_f32_dpp v161, -v12, v115 row_newbcast:15 row_mask:0xf bank_mask:0xf
	ds_read_b32 v12, v0 offset:17136
	s_waitcnt lgkmcnt(9)
	v_fmac_f32_dpp v161, -v13, v116 row_newbcast:0 row_mask:0xf bank_mask:0xf
	v_fmac_f32_dpp v161, -v13, v117 row_newbcast:1 row_mask:0xf bank_mask:0xf
	v_fmac_f32_dpp v161, -v13, v118 row_newbcast:2 row_mask:0xf bank_mask:0xf
	v_fmac_f32_dpp v161, -v13, v119 row_newbcast:3 row_mask:0xf bank_mask:0xf
	v_fmac_f32_dpp v161, -v13, v120 row_newbcast:4 row_mask:0xf bank_mask:0xf
	v_fmac_f32_dpp v161, -v13, v121 row_newbcast:5 row_mask:0xf bank_mask:0xf
	v_fmac_f32_dpp v161, -v13, v122 row_newbcast:6 row_mask:0xf bank_mask:0xf
	v_fmac_f32_dpp v161, -v13, v123 row_newbcast:7 row_mask:0xf bank_mask:0xf
	v_fmac_f32_dpp v161, -v13, v124 row_newbcast:8 row_mask:0xf bank_mask:0xf
	v_fmac_f32_dpp v161, -v13, v125 row_newbcast:9 row_mask:0xf bank_mask:0xf
	v_fmac_f32_dpp v161, -v13, v126 row_newbcast:10 row_mask:0xf bank_mask:0xf
	v_fmac_f32_dpp v161, -v13, v127 row_newbcast:11 row_mask:0xf bank_mask:0xf
	v_fmac_f32_dpp v161, -v13, v128 row_newbcast:12 row_mask:0xf bank_mask:0xf
	v_fmac_f32_dpp v161, -v13, v129 row_newbcast:13 row_mask:0xf bank_mask:0xf
	v_fmac_f32_dpp v161, -v13, v130 row_newbcast:14 row_mask:0xf bank_mask:0xf
	v_fmac_f32_dpp v161, -v13, v131 row_newbcast:15 row_mask:0xf bank_mask:0xf
	ds_read_b32 v13, v0 offset:17200
	s_waitcnt lgkmcnt(9)
	v_fmac_f32_dpp v161, -v14, v132 row_newbcast:0 row_mask:0xf bank_mask:0xf
	v_fmac_f32_dpp v161, -v14, v133 row_newbcast:1 row_mask:0xf bank_mask:0xf
	v_fmac_f32_dpp v161, -v14, v134 row_newbcast:2 row_mask:0xf bank_mask:0xf
	v_fmac_f32_dpp v161, -v14, v135 row_newbcast:3 row_mask:0xf bank_mask:0xf
	v_fmac_f32_dpp v161, -v14, v136 row_newbcast:4 row_mask:0xf bank_mask:0xf
	v_fmac_f32_dpp v161, -v14, v137 row_newbcast:5 row_mask:0xf bank_mask:0xf
	v_fmac_f32_dpp v161, -v14, v138 row_newbcast:6 row_mask:0xf bank_mask:0xf
	v_fmac_f32_dpp v161, -v14, v139 row_newbcast:7 row_mask:0xf bank_mask:0xf
	v_fmac_f32_dpp v161, -v14, v140 row_newbcast:8 row_mask:0xf bank_mask:0xf
	v_fmac_f32_dpp v161, -v14, v141 row_newbcast:9 row_mask:0xf bank_mask:0xf
	v_fmac_f32_dpp v161, -v14, v142 row_newbcast:10 row_mask:0xf bank_mask:0xf
	v_fmac_f32_dpp v161, -v14, v143 row_newbcast:11 row_mask:0xf bank_mask:0xf
	v_fmac_f32_dpp v161, -v14, v144 row_newbcast:12 row_mask:0xf bank_mask:0xf
	v_fmac_f32_dpp v161, -v14, v145 row_newbcast:13 row_mask:0xf bank_mask:0xf
	v_fmac_f32_dpp v161, -v14, v146 row_newbcast:14 row_mask:0xf bank_mask:0xf
	v_fmac_f32_dpp v161, -v14, v147 row_newbcast:15 row_mask:0xf bank_mask:0xf
	ds_read_b32 v14, v0 offset:17264
	s_waitcnt lgkmcnt(8)
; DI void d2_chunk(const Params& P, int l, int chunk, LAS float* Nm, LAS float* gs, int lane_in) {
;     ...
;         D2_TBLOCK(0); D2_TBLOCK(1); D2_TBLOCK(2); D2_TBLOCK(3);
	v_fmac_f32_dpp v161, -v15, v148 row_newbcast:0 row_mask:0xf bank_mask:0xf
	v_fmac_f32_dpp v161, -v15, v149 row_newbcast:1 row_mask:0xf bank_mask:0xf
	v_fmac_f32_dpp v161, -v15, v150 row_newbcast:2 row_mask:0xf bank_mask:0xf
	v_fmac_f32_dpp v161, -v15, v151 row_newbcast:3 row_mask:0xf bank_mask:0xf
	v_fmac_f32_dpp v161, -v15, v152 row_newbcast:4 row_mask:0xf bank_mask:0xf
	v_fmac_f32_dpp v161, -v15, v153 row_newbcast:5 row_mask:0xf bank_mask:0xf
	v_fmac_f32_dpp v161, -v15, v154 row_newbcast:6 row_mask:0xf bank_mask:0xf
	v_fmac_f32_dpp v161, -v15, v155 row_newbcast:7 row_mask:0xf bank_mask:0xf
	v_fmac_f32_dpp v161, -v15, v156 row_newbcast:8 row_mask:0xf bank_mask:0xf
	v_fmac_f32_dpp v161, -v15, v157 row_newbcast:9 row_mask:0xf bank_mask:0xf
	v_fmac_f32_dpp v161, -v15, v158 row_newbcast:10 row_mask:0xf bank_mask:0xf
	v_fmac_f32_dpp v161, -v15, v159 row_newbcast:11 row_mask:0xf bank_mask:0xf
	v_fmac_f32_dpp v161, -v15, v160 row_newbcast:12 row_mask:0xf bank_mask:0xf
	ds_write_b32 v169, v161 offset:16592
	v_cmp_eq_u32_e32 vcc, 62, v166
	s_nop 1
	v_cndmask_b32_e64 v162, 0, 1.0, vcc
	ds_read_b32 v15, v0 offset:17328
	s_waitcnt lgkmcnt(9)
	v_fmac_f32_dpp v162, -v16, v100 row_newbcast:0 row_mask:0xf bank_mask:0xf
	v_fmac_f32_dpp v162, -v16, v101 row_newbcast:1 row_mask:0xf bank_mask:0xf
	v_fmac_f32_dpp v162, -v16, v102 row_newbcast:2 row_mask:0xf bank_mask:0xf
	v_fmac_f32_dpp v162, -v16, v103 row_newbcast:3 row_mask:0xf bank_mask:0xf
	v_fmac_f32_dpp v162, -v16, v104 row_newbcast:4 row_mask:0xf bank_mask:0xf
	v_fmac_f32_dpp v162, -v16, v105 row_newbcast:5 row_mask:0xf bank_mask:0xf
	v_fmac_f32_dpp v162, -v16, v106 row_newbcast:6 row_mask:0xf bank_mask:0xf
	v_fmac_f32_dpp v162, -v16, v107 row_newbcast:7 row_mask:0xf bank_mask:0xf
	v_fmac_f32_dpp v162, -v16, v108 row_newbcast:8 row_mask:0xf bank_mask:0xf
	v_fmac_f32_dpp v162, -v16, v109 row_newbcast:9 row_mask:0xf bank_mask:0xf
	v_fmac_f32_dpp v162, -v16, v110 row_newbcast:10 row_mask:0xf bank_mask:0xf
	v_fmac_f32_dpp v162, -v16, v111 row_newbcast:11 row_mask:0xf bank_mask:0xf
	v_fmac_f32_dpp v162, -v16, v112 row_newbcast:12 row_mask:0xf bank_mask:0xf
	v_fmac_f32_dpp v162, -v16, v113 row_newbcast:13 row_mask:0xf bank_mask:0xf
	v_fmac_f32_dpp v162, -v16, v114 row_newbcast:14 row_mask:0xf bank_mask:0xf
	v_fmac_f32_dpp v162, -v16, v115 row_newbcast:15 row_mask:0xf bank_mask:0xf
	s_waitcnt lgkmcnt(8)
	v_fmac_f32_dpp v162, -v17, v116 row_newbcast:0 row_mask:0xf bank_mask:0xf
	v_fmac_f32_dpp v162, -v17, v117 row_newbcast:1 row_mask:0xf bank_mask:0xf
	v_fmac_f32_dpp v162, -v17, v118 row_newbcast:2 row_mask:0xf bank_mask:0xf
	v_fmac_f32_dpp v162, -v17, v119 row_newbcast:3 row_mask:0xf bank_mask:0xf
	v_fmac_f32_dpp v162, -v17, v120 row_newbcast:4 row_mask:0xf bank_mask:0xf
	v_fmac_f32_dpp v162, -v17, v121 row_newbcast:5 row_mask:0xf bank_mask:0xf
	v_fmac_f32_dpp v162, -v17, v122 row_newbcast:6 row_mask:0xf bank_mask:0xf
	v_fmac_f32_dpp v162, -v17, v123 row_newbcast:7 row_mask:0xf bank_mask:0xf
	v_fmac_f32_dpp v162, -v17, v124 row_newbcast:8 row_mask:0xf bank_mask:0xf
	v_fmac_f32_dpp v162, -v17, v125 row_newbcast:9 row_mask:0xf bank_mask:0xf
	v_fmac_f32_dpp v162, -v17, v126 row_newbcast:10 row_mask:0xf bank_mask:0xf
	v_fmac_f32_dpp v162, -v17, v127 row_newbcast:11 row_mask:0xf bank_mask:0xf
	v_fmac_f32_dpp v162, -v17, v128 row_newbcast:12 row_mask:0xf bank_mask:0xf
	v_fmac_f32_dpp v162, -v17, v129 row_newbcast:13 row_mask:0xf bank_mask:0xf
	v_fmac_f32_dpp v162, -v17, v130 row_newbcast:14 row_mask:0xf bank_mask:0xf
	v_fmac_f32_dpp v162, -v17, v131 row_newbcast:15 row_mask:0xf bank_mask:0xf
	s_waitcnt lgkmcnt(7)
	v_fmac_f32_dpp v162, -v18, v132 row_newbcast:0 row_mask:0xf bank_mask:0xf
	v_fmac_f32_dpp v162, -v18, v133 row_newbcast:1 row_mask:0xf bank_mask:0xf
	v_fmac_f32_dpp v162, -v18, v134 row_newbcast:2 row_mask:0xf bank_mask:0xf
	v_fmac_f32_dpp v162, -v18, v135 row_newbcast:3 row_mask:0xf bank_mask:0xf
	v_fmac_f32_dpp v162, -v18, v136 row_newbcast:4 row_mask:0xf bank_mask:0xf
	v_fmac_f32_dpp v162, -v18, v137 row_newbcast:5 row_mask:0xf bank_mask:0xf
	v_fmac_f32_dpp v162, -v18, v138 row_newbcast:6 row_mask:0xf bank_mask:0xf
	v_fmac_f32_dpp v162, -v18, v139 row_newbcast:7 row_mask:0xf bank_mask:0xf
	v_fmac_f32_dpp v162, -v18, v140 row_newbcast:8 row_mask:0xf bank_mask:0xf
	v_fmac_f32_dpp v162, -v18, v141 row_newbcast:9 row_mask:0xf bank_mask:0xf
	v_fmac_f32_dpp v162, -v18, v142 row_newbcast:10 row_mask:0xf bank_mask:0xf
	v_fmac_f32_dpp v162, -v18, v143 row_newbcast:11 row_mask:0xf bank_mask:0xf
	v_fmac_f32_dpp v162, -v18, v144 row_newbcast:12 row_mask:0xf bank_mask:0xf
	v_fmac_f32_dpp v162, -v18, v145 row_newbcast:13 row_mask:0xf bank_mask:0xf
	v_fmac_f32_dpp v162, -v18, v146 row_newbcast:14 row_mask:0xf bank_mask:0xf
	v_fmac_f32_dpp v162, -v18, v147 row_newbcast:15 row_mask:0xf bank_mask:0xf
	s_waitcnt lgkmcnt(5)
	v_fmac_f32_dpp v162, -v19, v148 row_newbcast:0 row_mask:0xf bank_mask:0xf
	v_fmac_f32_dpp v162, -v19, v149 row_newbcast:1 row_mask:0xf bank_mask:0xf
	v_fmac_f32_dpp v162, -v19, v150 row_newbcast:2 row_mask:0xf bank_mask:0xf
	v_fmac_f32_dpp v162, -v19, v151 row_newbcast:3 row_mask:0xf bank_mask:0xf
	v_fmac_f32_dpp v162, -v19, v152 row_newbcast:4 row_mask:0xf bank_mask:0xf
	v_fmac_f32_dpp v162, -v19, v153 row_newbcast:5 row_mask:0xf bank_mask:0xf
	v_fmac_f32_dpp v162, -v19, v154 row_newbcast:6 row_mask:0xf bank_mask:0xf
	v_fmac_f32_dpp v162, -v19, v155 row_newbcast:7 row_mask:0xf bank_mask:0xf
	v_fmac_f32_dpp v162, -v19, v156 row_newbcast:8 row_mask:0xf bank_mask:0xf
	v_fmac_f32_dpp v162, -v19, v157 row_newbcast:9 row_mask:0xf bank_mask:0xf
	v_fmac_f32_dpp v162, -v19, v158 row_newbcast:10 row_mask:0xf bank_mask:0xf
	v_fmac_f32_dpp v162, -v19, v159 row_newbcast:11 row_mask:0xf bank_mask:0xf
	v_fmac_f32_dpp v162, -v19, v160 row_newbcast:12 row_mask:0xf bank_mask:0xf
	v_fmac_f32_dpp v162, -v19, v161 row_newbcast:13 row_mask:0xf bank_mask:0xf
	ds_write_b32 v169, v162 offset:16864
	v_cmp_eq_u32_e32 vcc, 63, v166
	s_nop 1
	v_cndmask_b32_e64 v163, 0, 1.0, vcc
	s_waitcnt lgkmcnt(5)
; #define LAS __attribute__((address_space(3)))
; DI unsigned cvtpk(float lo, float hi) { f32x2 v = {lo, hi}; bf16x2_t b = __builtin_convertvector(v, bf16x2_t); return __builtin_bit_cast(unsigned, b); }
; DI void d2_chunk(const Params& P, int l, int chunk, LAS float* Nm, LAS float* gs, int lane_in) {
;     ...
;         D2_TBLOCK(0); D2_TBLOCK(1); D2_TBLOCK(2); D2_TBLOCK(3);
;     ...
;         bf16x8 Tfw[2][4], Tfu[2][4];
; #pragma unroll
;         for (int ct = 0; ct < 2; ++ct)
; #pragma unroll
;             for (int ks = 0; ks < 4; ++ks) { const LAS f32x4* tp = (const LAS f32x4*)(Nm + (32 * ct + r) * NMS + 16 * ks + 8 * hi); const f32x4 a = tp[0], c2 = tp[1];
;                 const LAS f32x4* fw = (const LAS f32x4*)(gs + 128 + 16 * ks + 8 * hi); const LAS f32x4* fb = (const LAS f32x4*)(gs + 64 + 16 * ks + 8 * hi);
;                 const f32x4 w0 = fw[0], w1 = fw[1], b0 = fb[0], b1 = fb[1];
;                 u32x4 p; p.x = cvtpk(a.x * w0.x, a.y * w0.y); p.y = cvtpk(a.z * w0.z, a.w * w0.w); p.z = cvtpk(c2.x * w1.x, c2.y * w1.y); p.w = cvtpk(c2.z * w1.z, c2.w * w1.w); Tfw[ct][ks] = __builtin_bit_cast(bf16x8, p);
;                 u32x4 q; q.x = cvtpk(a.x * b0.x, a.y * b0.y); q.y = cvtpk(a.z * b0.z, a.w * b0.w); q.z = cvtpk(c2.x * b1.x, c2.y * b1.y); q.w = cvtpk(c2.z * b1.z, c2.w * b1.w); Tfu[ct][ks] = __builtin_bit_cast(bf16x8, q); }
	v_fmac_f32_dpp v163, -v12, v100 row_newbcast:0 row_mask:0xf bank_mask:0xf
	v_fmac_f32_dpp v163, -v12, v101 row_newbcast:1 row_mask:0xf bank_mask:0xf
	v_fmac_f32_dpp v163, -v12, v102 row_newbcast:2 row_mask:0xf bank_mask:0xf
	v_fmac_f32_dpp v163, -v12, v103 row_newbcast:3 row_mask:0xf bank_mask:0xf
	v_fmac_f32_dpp v163, -v12, v104 row_newbcast:4 row_mask:0xf bank_mask:0xf
	v_fmac_f32_dpp v163, -v12, v105 row_newbcast:5 row_mask:0xf bank_mask:0xf
	v_fmac_f32_dpp v163, -v12, v106 row_newbcast:6 row_mask:0xf bank_mask:0xf
	v_fmac_f32_dpp v163, -v12, v107 row_newbcast:7 row_mask:0xf bank_mask:0xf
	v_fmac_f32_dpp v163, -v12, v108 row_newbcast:8 row_mask:0xf bank_mask:0xf
	v_fmac_f32_dpp v163, -v12, v109 row_newbcast:9 row_mask:0xf bank_mask:0xf
	v_fmac_f32_dpp v163, -v12, v110 row_newbcast:10 row_mask:0xf bank_mask:0xf
	v_fmac_f32_dpp v163, -v12, v111 row_newbcast:11 row_mask:0xf bank_mask:0xf
	v_fmac_f32_dpp v163, -v12, v112 row_newbcast:12 row_mask:0xf bank_mask:0xf
	v_fmac_f32_dpp v163, -v12, v113 row_newbcast:13 row_mask:0xf bank_mask:0xf
	v_fmac_f32_dpp v163, -v12, v114 row_newbcast:14 row_mask:0xf bank_mask:0xf
	v_fmac_f32_dpp v163, -v12, v115 row_newbcast:15 row_mask:0xf bank_mask:0xf
	s_waitcnt lgkmcnt(4)
	v_fmac_f32_dpp v163, -v13, v116 row_newbcast:0 row_mask:0xf bank_mask:0xf
	v_fmac_f32_dpp v163, -v13, v117 row_newbcast:1 row_mask:0xf bank_mask:0xf
	v_fmac_f32_dpp v163, -v13, v118 row_newbcast:2 row_mask:0xf bank_mask:0xf
	v_fmac_f32_dpp v163, -v13, v119 row_newbcast:3 row_mask:0xf bank_mask:0xf
	v_fmac_f32_dpp v163, -v13, v120 row_newbcast:4 row_mask:0xf bank_mask:0xf
	v_fmac_f32_dpp v163, -v13, v121 row_newbcast:5 row_mask:0xf bank_mask:0xf
	v_fmac_f32_dpp v163, -v13, v122 row_newbcast:6 row_mask:0xf bank_mask:0xf
	v_fmac_f32_dpp v163, -v13, v123 row_newbcast:7 row_mask:0xf bank_mask:0xf
	v_fmac_f32_dpp v163, -v13, v124 row_newbcast:8 row_mask:0xf bank_mask:0xf
	v_fmac_f32_dpp v163, -v13, v125 row_newbcast:9 row_mask:0xf bank_mask:0xf
	v_fmac_f32_dpp v163, -v13, v126 row_newbcast:10 row_mask:0xf bank_mask:0xf
	v_fmac_f32_dpp v163, -v13, v127 row_newbcast:11 row_mask:0xf bank_mask:0xf
	v_fmac_f32_dpp v163, -v13, v128 row_newbcast:12 row_mask:0xf bank_mask:0xf
	v_fmac_f32_dpp v163, -v13, v129 row_newbcast:13 row_mask:0xf bank_mask:0xf
	v_fmac_f32_dpp v163, -v13, v130 row_newbcast:14 row_mask:0xf bank_mask:0xf
	v_fmac_f32_dpp v163, -v13, v131 row_newbcast:15 row_mask:0xf bank_mask:0xf
	s_waitcnt lgkmcnt(3)
	v_fmac_f32_dpp v163, -v14, v132 row_newbcast:0 row_mask:0xf bank_mask:0xf
	v_fmac_f32_dpp v163, -v14, v133 row_newbcast:1 row_mask:0xf bank_mask:0xf
	v_fmac_f32_dpp v163, -v14, v134 row_newbcast:2 row_mask:0xf bank_mask:0xf
	v_fmac_f32_dpp v163, -v14, v135 row_newbcast:3 row_mask:0xf bank_mask:0xf
	v_fmac_f32_dpp v163, -v14, v136 row_newbcast:4 row_mask:0xf bank_mask:0xf
	v_fmac_f32_dpp v163, -v14, v137 row_newbcast:5 row_mask:0xf bank_mask:0xf
	v_fmac_f32_dpp v163, -v14, v138 row_newbcast:6 row_mask:0xf bank_mask:0xf
	v_fmac_f32_dpp v163, -v14, v139 row_newbcast:7 row_mask:0xf bank_mask:0xf
	v_fmac_f32_dpp v163, -v14, v140 row_newbcast:8 row_mask:0xf bank_mask:0xf
	v_fmac_f32_dpp v163, -v14, v141 row_newbcast:9 row_mask:0xf bank_mask:0xf
	v_fmac_f32_dpp v163, -v14, v142 row_newbcast:10 row_mask:0xf bank_mask:0xf
	v_fmac_f32_dpp v163, -v14, v143 row_newbcast:11 row_mask:0xf bank_mask:0xf
	v_fmac_f32_dpp v163, -v14, v144 row_newbcast:12 row_mask:0xf bank_mask:0xf
	v_fmac_f32_dpp v163, -v14, v145 row_newbcast:13 row_mask:0xf bank_mask:0xf
	v_fmac_f32_dpp v163, -v14, v146 row_newbcast:14 row_mask:0xf bank_mask:0xf
	v_fmac_f32_dpp v163, -v14, v147 row_newbcast:15 row_mask:0xf bank_mask:0xf
	s_waitcnt lgkmcnt(1)
	v_fmac_f32_dpp v163, -v15, v148 row_newbcast:0 row_mask:0xf bank_mask:0xf
	v_fmac_f32_dpp v163, -v15, v149 row_newbcast:1 row_mask:0xf bank_mask:0xf
	v_fmac_f32_dpp v163, -v15, v150 row_newbcast:2 row_mask:0xf bank_mask:0xf
	v_fmac_f32_dpp v163, -v15, v151 row_newbcast:3 row_mask:0xf bank_mask:0xf
	v_fmac_f32_dpp v163, -v15, v152 row_newbcast:4 row_mask:0xf bank_mask:0xf
	v_fmac_f32_dpp v163, -v15, v153 row_newbcast:5 row_mask:0xf bank_mask:0xf
	v_fmac_f32_dpp v163, -v15, v154 row_newbcast:6 row_mask:0xf bank_mask:0xf
	v_fmac_f32_dpp v163, -v15, v155 row_newbcast:7 row_mask:0xf bank_mask:0xf
	v_fmac_f32_dpp v163, -v15, v156 row_newbcast:8 row_mask:0xf bank_mask:0xf
	v_fmac_f32_dpp v163, -v15, v157 row_newbcast:9 row_mask:0xf bank_mask:0xf
	v_fmac_f32_dpp v163, -v15, v158 row_newbcast:10 row_mask:0xf bank_mask:0xf
	v_fmac_f32_dpp v163, -v15, v159 row_newbcast:11 row_mask:0xf bank_mask:0xf
	v_fmac_f32_dpp v163, -v15, v160 row_newbcast:12 row_mask:0xf bank_mask:0xf
	v_fmac_f32_dpp v163, -v15, v161 row_newbcast:13 row_mask:0xf bank_mask:0xf
	v_fmac_f32_dpp v163, -v15, v162 row_newbcast:14 row_mask:0xf bank_mask:0xf
	ds_write_b32 v169, v163 offset:17136
	v_lshlrev_b32_e32 v0, 2, v98
	v_add_u32_e32 v11, s12, v0
	v_add_u32_e32 v30, v11, v99
	v_add_u32_e32 v32, s13, v0
	ds_read_b128 v[38:41], v30
	ds_read_b128 v[34:37], v30 offset:16
	ds_read_b128 v[4:7], v32 offset:512
	ds_read_b128 v[0:3], v32 offset:528
	ds_read_b128 v[54:57], v32 offset:256
	ds_read_b128 v[50:53], v32 offset:272
	v_add_u32_e32 v9, v11, v9
	s_waitcnt lgkmcnt(3)
	v_pk_mul_f32 v[12:13], v[38:39], v[4:5]
	v_ashrrev_i32_e32 v167, 31, v166
	v_cvt_pk_bf16_f32 v42, v12, v13
	v_pk_mul_f32 v[12:13], v[40:41], v[6:7]
	v_lshlrev_b64 v[180:181], 4, v[166:167]
	v_cvt_pk_bf16_f32 v43, v12, v13
	s_waitcnt lgkmcnt(2)
; #define LAS __attribute__((address_space(3)))
; DI unsigned cvtpk(float lo, float hi) { f32x2 v = {lo, hi}; bf16x2_t b = __builtin_convertvector(v, bf16x2_t); return __builtin_bit_cast(unsigned, b); }
; DI void d2_chunk(const Params& P, int l, int chunk, LAS float* Nm, LAS float* gs, int lane_in) {
;     ...
;         bf16x8 Tfw[2][4], Tfu[2][4];
; #pragma unroll
;         for (int ct = 0; ct < 2; ++ct)
; #pragma unroll
;             for (int ks = 0; ks < 4; ++ks) { const LAS f32x4* tp = (const LAS f32x4*)(Nm + (32 * ct + r) * NMS + 16 * ks + 8 * hi); const f32x4 a = tp[0], c2 = tp[1];
;                 const LAS f32x4* fw = (const LAS f32x4*)(gs + 128 + 16 * ks + 8 * hi); const LAS f32x4* fb = (const LAS f32x4*)(gs + 64 + 16 * ks + 8 * hi);
;                 const f32x4 w0 = fw[0], w1 = fw[1], b0 = fb[0], b1 = fb[1];
;                 u32x4 p; p.x = cvtpk(a.x * w0.x, a.y * w0.y); p.y = cvtpk(a.z * w0.z, a.w * w0.w); p.z = cvtpk(c2.x * w1.x, c2.y * w1.y); p.w = cvtpk(c2.z * w1.z, c2.w * w1.w); Tfw[ct][ks] = __builtin_bit_cast(bf16x8, p);
;                 u32x4 q; q.x = cvtpk(a.x * b0.x, a.y * b0.y); q.y = cvtpk(a.z * b0.z, a.w * b0.w); q.z = cvtpk(c2.x * b1.x, c2.y * b1.y); q.w = cvtpk(c2.z * b1.z, c2.w * b1.w); Tfu[ct][ks] = __builtin_bit_cast(bf16x8, q); }
	v_pk_mul_f32 v[12:13], v[34:35], v[0:1]
	v_ashrrev_i32_e32 v11, 31, v10
	v_cvt_pk_bf16_f32 v44, v12, v13
	v_pk_mul_f32 v[12:13], v[36:37], v[2:3]
	v_lshlrev_b32_e32 v178, 4, v166
	v_cvt_pk_bf16_f32 v45, v12, v13
	ds_read_b128 v[66:69], v30 offset:64
	ds_read_b128 v[46:49], v30 offset:80
	ds_read_b128 v[12:15], v32 offset:576
	ds_read_b128 v[16:19], v32 offset:592
	ds_read_b128 v[62:65], v32 offset:320
	ds_read_b128 v[58:61], v32 offset:336
	v_add_u32_e32 v244, s12, v178
	s_waitcnt lgkmcnt(3)
	v_pk_mul_f32 v[20:21], v[66:67], v[12:13]
	s_nop 0
	v_cvt_pk_bf16_f32 v78, v20, v21
	v_pk_mul_f32 v[20:21], v[68:69], v[14:15]
	s_nop 0
	v_cvt_pk_bf16_f32 v79, v20, v21
	s_waitcnt lgkmcnt(2)
	v_pk_mul_f32 v[20:21], v[46:47], v[16:17]
	s_nop 0
	v_cvt_pk_bf16_f32 v80, v20, v21
	v_pk_mul_f32 v[20:21], v[48:49], v[18:19]
	s_nop 0
	v_cvt_pk_bf16_f32 v81, v20, v21
	ds_read_b128 v[86:89], v30 offset:128
	ds_read_b128 v[82:85], v30 offset:144
	ds_read_b128 v[20:23], v32 offset:640
	ds_read_b128 v[24:27], v32 offset:656
	ds_read_b128 v[74:77], v32 offset:384
	ds_read_b128 v[70:73], v32 offset:400
	s_waitcnt lgkmcnt(3)
	v_pk_mul_f32 v[28:29], v[86:87], v[20:21]
	s_nop 0
	v_cvt_pk_bf16_f32 v102, v28, v29
	v_pk_mul_f32 v[28:29], v[88:89], v[22:23]
	s_nop 0
	v_cvt_pk_bf16_f32 v103, v28, v29
	s_waitcnt lgkmcnt(2)
	v_pk_mul_f32 v[28:29], v[82:83], v[24:25]
	s_nop 0
	v_cvt_pk_bf16_f32 v104, v28, v29
	v_pk_mul_f32 v[28:29], v[84:85], v[26:27]
	s_nop 0
	v_cvt_pk_bf16_f32 v105, v28, v29
	ds_read_b128 v[110:113], v30 offset:192
	ds_read_b128 v[106:109], v30 offset:208
	ds_read_b128 v[28:31], v32 offset:704
	ds_read_b128 v[196:199], v32 offset:720
	ds_read_b128 v[98:101], v32 offset:448
	ds_read_b128 v[90:93], v32 offset:464
	ds_read_b128 v[122:125], v9
	ds_read_b128 v[118:121], v9 offset:16
	ds_read_b128 v[130:133], v9 offset:64
	ds_read_b128 v[126:129], v9 offset:80
	ds_read_b128 v[142:145], v9 offset:128
	ds_read_b128 v[138:141], v9 offset:144
	ds_read_b128 v[154:157], v9 offset:192
	ds_read_b128 v[150:153], v9 offset:208
	s_waitcnt lgkmcnt(11)
	v_pk_mul_f32 v[32:33], v[110:111], v[28:29]
	s_waitcnt lgkmcnt(6)
	v_pk_mul_f32 v[0:1], v[0:1], v[118:119]
	v_cvt_pk_bf16_f32 v114, v32, v33
	v_cvt_pk_bf16_f32 v136, v0, v1
	v_pk_mul_f32 v[0:1], v[2:3], v[120:121]
	v_pk_mul_f32 v[32:33], v[112:113], v[30:31]
	v_cvt_pk_bf16_f32 v137, v0, v1
	s_waitcnt lgkmcnt(5)
	v_pk_mul_f32 v[0:1], v[12:13], v[130:131]
	v_pk_mul_f32 v[4:5], v[4:5], v[122:123]
	v_cvt_pk_bf16_f32 v146, v0, v1
	v_pk_mul_f32 v[0:1], v[14:15], v[132:133]
	v_ashrrev_i32_e32 v9, 31, v8
	v_cvt_pk_bf16_f32 v147, v0, v1
	s_waitcnt lgkmcnt(4)
	v_pk_mul_f32 v[0:1], v[16:17], v[126:127]
	v_cvt_pk_bf16_f32 v115, v32, v33
	v_cvt_pk_bf16_f32 v148, v0, v1
	v_pk_mul_f32 v[0:1], v[18:19], v[128:129]
	v_pk_mul_f32 v[32:33], v[106:107], v[196:197]
	v_cvt_pk_bf16_f32 v149, v0, v1
	s_waitcnt lgkmcnt(3)
	v_pk_mul_f32 v[0:1], v[20:21], v[142:143]
	v_cvt_pk_bf16_f32 v134, v4, v5
	v_cvt_pk_bf16_f32 v158, v0, v1
	v_pk_mul_f32 v[0:1], v[22:23], v[144:145]
	v_pk_mul_f32 v[4:5], v[6:7], v[124:125]
	v_cvt_pk_bf16_f32 v159, v0, v1
	s_waitcnt lgkmcnt(2)
	v_pk_mul_f32 v[0:1], v[24:25], v[138:139]
	v_add_u32_e32 v12, 0xc0, v166
	v_cvt_pk_bf16_f32 v160, v0, v1
	v_pk_mul_f32 v[0:1], v[26:27], v[140:141]
	v_cvt_pk_bf16_f32 v116, v32, v33
	v_cvt_pk_bf16_f32 v161, v0, v1
	s_waitcnt lgkmcnt(1)
	v_pk_mul_f32 v[0:1], v[28:29], v[154:155]
	v_pk_mul_f32 v[32:33], v[108:109], v[198:199]
	v_cvt_pk_bf16_f32 v162, v0, v1
	v_pk_mul_f32 v[0:1], v[30:31], v[156:157]
	v_cvt_pk_bf16_f32 v135, v4, v5
	v_cvt_pk_bf16_f32 v163, v0, v1
	s_waitcnt lgkmcnt(0)
; #define LAS __attribute__((address_space(3)))
; DI unsigned cvtpk(float lo, float hi) { f32x2 v = {lo, hi}; bf16x2_t b = __builtin_convertvector(v, bf16x2_t); return __builtin_bit_cast(unsigned, b); }
; DI void wave_lds_fence() { __builtin_amdgcn_fence(__ATOMIC_RELEASE, "wavefront"); __builtin_amdgcn_wave_barrier(); __builtin_amdgcn_fence(__ATOMIC_ACQUIRE, "wavefront"); }
; DI void d2_chunk(const Params& P, int l, int chunk, LAS float* Nm, LAS float* gs, int lane_in) {
;     ...
;                 u32x4 p; p.x = cvtpk(a.x * w0.x, a.y * w0.y); p.y = cvtpk(a.z * w0.z, a.w * w0.w); p.z = cvtpk(c2.x * w1.x, c2.y * w1.y); p.w = cvtpk(c2.z * w1.z, c2.w * w1.w); Tfw[ct][ks] = __builtin_bit_cast(bf16x8, p);
;                 u32x4 q; q.x = cvtpk(a.x * b0.x, a.y * b0.y); q.y = cvtpk(a.z * b0.z, a.w * b0.w); q.z = cvtpk(c2.x * b1.x, c2.y * b1.y); q.w = cvtpk(c2.z * b1.z, c2.w * b1.w); Tfu[ct][ks] = __builtin_bit_cast(bf16x8, q); }
;         wave_lds_fence();
;         LAS bf16_t* Xs = (LAS bf16_t*)Nm;
;     ...
;         D2_STAGE(Kc);
	v_pk_mul_f32 v[0:1], v[196:197], v[150:151]
	v_lshlrev_b64 v[196:197], 4, v[8:9]
	v_cvt_pk_bf16_f32 v164, v0, v1
	v_pk_mul_f32 v[0:1], v[198:199], v[152:153]
	s_nop 0
	v_cvt_pk_bf16_f32 v165, v0, v1
	v_lshl_add_u64 v[0:1], s[48:49], 0, v[180:181]
	global_load_dwordx4 v[0:3], v[0:1], off
	v_lshl_add_u64 v[4:5], s[48:49], 0, v[196:197]
	v_lshlrev_b64 v[198:199], 4, v[10:11]
	v_ashrrev_i32_e32 v13, 31, v12
	v_add_u32_e32 v16, 0x100, v166
	global_load_dwordx4 v[4:7], v[4:5], off
	v_lshl_add_u64 v[8:9], s[48:49], 0, v[198:199]
	v_lshlrev_b64 v[200:201], 4, v[12:13]
	v_ashrrev_i32_e32 v17, 31, v16
	v_add_u32_e32 v20, 0x140, v166
	global_load_dwordx4 v[8:11], v[8:9], off
	v_lshl_add_u64 v[12:13], s[48:49], 0, v[200:201]
	v_lshlrev_b64 v[202:203], 4, v[16:17]
	v_ashrrev_i32_e32 v21, 31, v20
	v_add_u32_e32 v24, 0x180, v166
	global_load_dwordx4 v[12:15], v[12:13], off
	v_lshl_add_u64 v[16:17], s[48:49], 0, v[202:203]
	v_lshlrev_b64 v[204:205], 4, v[20:21]
	v_ashrrev_i32_e32 v25, 31, v24
	v_add_u32_e32 v28, 0x1c0, v166
	global_load_dwordx4 v[16:19], v[16:17], off
	v_lshl_add_u64 v[20:21], s[48:49], 0, v[204:205]
	v_lshlrev_b64 v[206:207], 4, v[24:25]
	v_ashrrev_i32_e32 v29, 31, v28
	global_load_dwordx4 v[20:23], v[20:21], off
	v_lshl_add_u64 v[24:25], s[48:49], 0, v[206:207]
	v_lshlrev_b64 v[208:209], 4, v[28:29]
	global_load_dwordx4 v[24:27], v[24:25], off
	v_lshl_add_u64 v[28:29], s[48:49], 0, v[208:209]
	global_load_dwordx4 v[28:31], v[28:29], off
	v_cvt_pk_bf16_f32 v117, v32, v33
	s_waitcnt vmcnt(7)
	ds_write_b128 v244, v[0:3]
	s_waitcnt vmcnt(6)
	ds_write_b128 v244, v[4:7] offset:1024
	s_waitcnt vmcnt(5)
	ds_write_b128 v244, v[8:11] offset:2048
	s_waitcnt vmcnt(4)
	ds_write_b128 v244, v[12:15] offset:3072
	s_waitcnt vmcnt(3)
	ds_write_b128 v244, v[16:19] offset:4096
	s_waitcnt vmcnt(2)
	ds_write_b128 v244, v[20:23] offset:5120
	s_waitcnt vmcnt(1)
	ds_write_b128 v244, v[24:27] offset:6144
	s_waitcnt vmcnt(0)
	ds_write_b128 v244, v[28:31] offset:7168
	v_add_u32_e32 v0, 0x200, v166
	v_add_u32_e32 v2, 0x240, v166
	v_add_u32_e32 v8, 0x280, v166
	v_add_u32_e32 v10, 0x2c0, v166
	v_add_u32_e32 v16, 0x300, v166
	v_add_u32_e32 v18, 0x340, v166
	v_add_u32_e32 v24, 0x380, v166
	v_add_u32_e32 v26, 0x3c0, v166
	v_ashrrev_i32_e32 v1, 31, v0
	v_ashrrev_i32_e32 v3, 31, v2
	v_ashrrev_i32_e32 v9, 31, v8
	v_ashrrev_i32_e32 v11, 31, v10
	v_ashrrev_i32_e32 v17, 31, v16
	v_ashrrev_i32_e32 v19, 31, v18
	v_ashrrev_i32_e32 v25, 31, v24
	v_ashrrev_i32_e32 v27, 31, v26
	v_lshlrev_b64 v[210:211], 4, v[0:1]
	v_lshlrev_b64 v[212:213], 4, v[2:3]
	v_lshlrev_b64 v[214:215], 4, v[8:9]
	v_lshlrev_b64 v[216:217], 4, v[10:11]
	v_lshlrev_b64 v[218:219], 4, v[16:17]
	v_lshlrev_b64 v[220:221], 4, v[18:19]
	v_lshlrev_b64 v[222:223], 4, v[24:25]
	v_lshlrev_b64 v[224:225], 4, v[26:27]
	v_lshl_add_u64 v[0:1], s[48:49], 0, v[210:211]
	v_lshl_add_u64 v[4:5], s[48:49], 0, v[212:213]
	v_lshl_add_u64 v[8:9], s[48:49], 0, v[214:215]
	v_lshl_add_u64 v[12:13], s[48:49], 0, v[216:217]
	v_lshl_add_u64 v[16:17], s[48:49], 0, v[218:219]
	v_lshl_add_u64 v[20:21], s[48:49], 0, v[220:221]
	v_lshl_add_u64 v[24:25], s[48:49], 0, v[222:223]
	v_lshl_add_u64 v[28:29], s[48:49], 0, v[224:225]
	global_load_dwordx4 v[0:3], v[0:1], off
	s_nop 0
	global_load_dwordx4 v[4:7], v[4:5], off
	s_nop 0
	global_load_dwordx4 v[8:11], v[8:9], off
	s_nop 0
	global_load_dwordx4 v[12:15], v[12:13], off
	s_nop 0
	global_load_dwordx4 v[16:19], v[16:17], off
	s_nop 0
	global_load_dwordx4 v[20:23], v[20:21], off
	s_nop 0
	global_load_dwordx4 v[24:27], v[24:25], off
	s_nop 0
	global_load_dwordx4 v[28:31], v[28:29], off
	s_waitcnt vmcnt(7)
	ds_write_b128 v244, v[0:3] offset:8192
	s_waitcnt vmcnt(6)
	ds_write_b128 v244, v[4:7] offset:9216
	s_waitcnt vmcnt(5)
	ds_write_b128 v244, v[8:11] offset:10240
	s_waitcnt vmcnt(4)
	ds_write_b128 v244, v[12:15] offset:11264
	s_waitcnt vmcnt(3)
	ds_write_b128 v244, v[16:19] offset:12288
	s_waitcnt vmcnt(2)
	ds_write_b128 v244, v[20:23] offset:13312
	s_waitcnt vmcnt(1)
	ds_write_b128 v244, v[24:27] offset:14336
	s_waitcnt vmcnt(0)
	ds_write_b128 v244, v[28:31] offset:15360
	v_lshlrev_b32_e32 v0, 11, v179
	v_lshlrev_b32_e32 v1, 1, v96
	v_add3_u32 v167, s12, v0, v1
	v_mov_b32_e32 v32, v94
